# GEMM MFMA order: accumulator pairs back to back, pairs grouped by first operand with a snake turn
# speedup vs baseline: 1.0155x; 1.0028x over previous
.LBB0_236:
	ds_read_b128 v[146:149], v162
	ds_read_b128 v[150:153], v162 offset:1024
	ds_read_b128 v[166:169], v162 offset:2048
	ds_read_b128 v[170:173], v162 offset:3072
	ds_read_b128 v[174:177], v163
	ds_read_b128 v[182:185], v163 offset:1024
	ds_read_b128 v[186:189], v163 offset:2048
	ds_read_b128 v[190:193], v163 offset:3072
	s_add_u32 s26, s4, 0xfff80080
	s_addc_u32 s27, s5, -1
	s_cmp_eq_u32 s63, 28
	s_cselect_b32 s29, s17, s27
	s_cselect_b32 s28, s58, s26
	s_cselect_b32 s27, s15, s62
	s_cselect_b32 s26, s59, s60
	v_lshl_add_u64 v[226:227], s[4:5], 0, v[138:139]
	s_add_i32 m0, s23, 0xc000
	ds_read_b128 v[194:197], v164
	ds_read_b128 v[198:201], v164 offset:1024
	ds_read_b128 v[202:205], v164 offset:2048
	ds_read_b128 v[206:209], v164 offset:3072
	ds_read_b128 v[210:213], v164 offset:4096
	ds_read_b128 v[214:217], v164 offset:5120
	ds_read_b128 v[218:221], v164 offset:6144
	ds_read_b128 v[222:225], v164 offset:7168
	global_load_lds_dwordx4 v[226:227], off
	v_lshl_add_u64 v[226:227], s[4:5], 0, v[140:141]
	s_add_i32 m0, s23, 0xe000
	s_nop 0
	global_load_lds_dwordx4 v[226:227], off
	s_waitcnt vmcnt(8)
	s_waitcnt lgkmcnt(0)
	s_setprio 1
	s_barrier
	v_mfma_f32_16x16x32_bf16 v[126:129], v[146:149], v[194:197], v[126:129]
	v_mfma_f32_16x16x32_bf16 v[126:129], v[150:153], v[198:201], v[126:129]
	v_mfma_f32_16x16x32_bf16 v[110:113], v[146:149], v[202:205], v[110:113]
	v_mfma_f32_16x16x32_bf16 v[110:113], v[150:153], v[206:209], v[110:113]
	v_mfma_f32_16x16x32_bf16 v[94:97], v[146:149], v[210:213], v[94:97]
	v_mfma_f32_16x16x32_bf16 v[94:97], v[150:153], v[214:217], v[94:97]
	v_mfma_f32_16x16x32_bf16 v[78:81], v[146:149], v[218:221], v[78:81]
	v_mfma_f32_16x16x32_bf16 v[78:81], v[150:153], v[222:225], v[78:81]
	v_mfma_f32_16x16x32_bf16 v[74:77], v[166:169], v[218:221], v[74:77]
	v_mfma_f32_16x16x32_bf16 v[74:77], v[170:173], v[222:225], v[74:77]
	v_mfma_f32_16x16x32_bf16 v[90:93], v[166:169], v[210:213], v[90:93]
	v_mfma_f32_16x16x32_bf16 v[90:93], v[170:173], v[214:217], v[90:93]
	v_mfma_f32_16x16x32_bf16 v[106:109], v[166:169], v[202:205], v[106:109]
	v_mfma_f32_16x16x32_bf16 v[106:109], v[170:173], v[206:209], v[106:109]
	v_mfma_f32_16x16x32_bf16 v[122:125], v[166:169], v[194:197], v[122:125]
	v_mfma_f32_16x16x32_bf16 v[122:125], v[170:173], v[198:201], v[122:125]
	v_mfma_f32_16x16x32_bf16 v[118:121], v[174:177], v[194:197], v[118:121]
	v_mfma_f32_16x16x32_bf16 v[118:121], v[182:185], v[198:201], v[118:121]
	v_mfma_f32_16x16x32_bf16 v[102:105], v[174:177], v[202:205], v[102:105]
	v_mfma_f32_16x16x32_bf16 v[102:105], v[182:185], v[206:209], v[102:105]
	v_mfma_f32_16x16x32_bf16 v[86:89], v[174:177], v[210:213], v[86:89]
	v_mfma_f32_16x16x32_bf16 v[86:89], v[182:185], v[214:217], v[86:89]
	v_mfma_f32_16x16x32_bf16 v[70:73], v[174:177], v[218:221], v[70:73]
	v_mfma_f32_16x16x32_bf16 v[70:73], v[182:185], v[222:225], v[70:73]
	v_mfma_f32_16x16x32_bf16 v[66:69], v[186:189], v[218:221], v[66:69]
	v_mfma_f32_16x16x32_bf16 v[66:69], v[190:193], v[222:225], v[66:69]
	v_mfma_f32_16x16x32_bf16 v[82:85], v[186:189], v[210:213], v[82:85]
	v_mfma_f32_16x16x32_bf16 v[82:85], v[190:193], v[214:217], v[82:85]
	v_mfma_f32_16x16x32_bf16 v[98:101], v[186:189], v[202:205], v[98:101]
	v_mfma_f32_16x16x32_bf16 v[98:101], v[190:193], v[206:209], v[98:101]
	v_mfma_f32_16x16x32_bf16 v[114:117], v[186:189], v[194:197], v[114:117]
	v_mfma_f32_16x16x32_bf16 v[114:117], v[190:193], v[198:201], v[114:117]
	s_barrier
	s_setprio 0
	s_add_i32 s64, s55, s30
	v_lshl_add_u64 v[226:227], s[26:27], 0, v[132:133]
	s_mov_b32 m0, s64
	ds_read_b128 v[194:197], v164 offset:16384
	ds_read_b128 v[198:201], v164 offset:17408
	ds_read_b128 v[202:205], v164 offset:18432
	ds_read_b128 v[206:209], v164 offset:19456
	ds_read_b128 v[210:213], v164 offset:20480
	ds_read_b128 v[214:217], v164 offset:21504
	ds_read_b128 v[218:221], v164 offset:22528
	ds_read_b128 v[222:225], v164 offset:23552
	global_load_lds_dwordx4 v[226:227], off
	s_add_i32 m0, s64, 0x2000
	s_add_u32 s64, s26, 0x80000
	v_lshl_add_u64 v[228:229], s[26:27], 0, v[136:137]
	s_addc_u32 s65, s27, 0
	s_add_i32 s66, s56, s30
	global_load_lds_dwordx4 v[228:229], off
	v_lshl_add_u64 v[230:231], s[64:65], 0, v[132:133]
	s_mov_b32 m0, s66
	v_lshl_add_u64 v[232:233], s[28:29], 0, v[134:135]
	global_load_lds_dwordx4 v[230:231], off
	v_lshl_add_u64 v[230:231], s[64:65], 0, v[136:137]
	s_add_i32 m0, s66, 0x2000
	s_nop 0
	global_load_lds_dwordx4 v[230:231], off
	v_lshl_add_u64 v[230:231], s[28:29], 0, v[130:131]
	s_mov_b32 m0, s23
	s_nop 0
	global_load_lds_dwordx4 v[230:231], off
	s_mov_b32 m0, s25
	s_nop 0
	global_load_lds_dwordx4 v[232:233], off
	s_waitcnt vmcnt(8)
	s_waitcnt lgkmcnt(0)
	s_setprio 1
	s_barrier
	v_mfma_f32_16x16x32_bf16 v[62:65], v[146:149], v[194:197], v[62:65]
	v_mfma_f32_16x16x32_bf16 v[62:65], v[150:153], v[198:201], v[62:65]
	v_mfma_f32_16x16x32_bf16 v[46:49], v[146:149], v[202:205], v[46:49]
	v_mfma_f32_16x16x32_bf16 v[46:49], v[150:153], v[206:209], v[46:49]
	v_mfma_f32_16x16x32_bf16 v[30:33], v[146:149], v[210:213], v[30:33]
	v_mfma_f32_16x16x32_bf16 v[30:33], v[150:153], v[214:217], v[30:33]
	v_mfma_f32_16x16x32_bf16 v[14:17], v[146:149], v[218:221], v[14:17]
	v_mfma_f32_16x16x32_bf16 v[14:17], v[150:153], v[222:225], v[14:17]
	v_mfma_f32_16x16x32_bf16 v[10:13], v[166:169], v[218:221], v[10:13]
	v_mfma_f32_16x16x32_bf16 v[10:13], v[170:173], v[222:225], v[10:13]
	v_mfma_f32_16x16x32_bf16 v[26:29], v[166:169], v[210:213], v[26:29]
	v_mfma_f32_16x16x32_bf16 v[26:29], v[170:173], v[214:217], v[26:29]
	v_mfma_f32_16x16x32_bf16 v[42:45], v[166:169], v[202:205], v[42:45]
	v_mfma_f32_16x16x32_bf16 v[42:45], v[170:173], v[206:209], v[42:45]
	v_mfma_f32_16x16x32_bf16 v[58:61], v[166:169], v[194:197], v[58:61]
	v_mfma_f32_16x16x32_bf16 v[58:61], v[170:173], v[198:201], v[58:61]
	v_mfma_f32_16x16x32_bf16 v[54:57], v[174:177], v[194:197], v[54:57]
	v_mfma_f32_16x16x32_bf16 v[54:57], v[182:185], v[198:201], v[54:57]
	v_mfma_f32_16x16x32_bf16 v[38:41], v[174:177], v[202:205], v[38:41]
	v_mfma_f32_16x16x32_bf16 v[38:41], v[182:185], v[206:209], v[38:41]
	v_mfma_f32_16x16x32_bf16 v[22:25], v[174:177], v[210:213], v[22:25]
	v_mfma_f32_16x16x32_bf16 v[22:25], v[182:185], v[214:217], v[22:25]
	v_mfma_f32_16x16x32_bf16 v[6:9], v[174:177], v[218:221], v[6:9]
	v_mfma_f32_16x16x32_bf16 v[6:9], v[182:185], v[222:225], v[6:9]
	v_mfma_f32_16x16x32_bf16 v[2:5], v[186:189], v[218:221], v[2:5]
	v_mfma_f32_16x16x32_bf16 v[2:5], v[190:193], v[222:225], v[2:5]
	v_mfma_f32_16x16x32_bf16 v[18:21], v[186:189], v[210:213], v[18:21]
	v_mfma_f32_16x16x32_bf16 v[18:21], v[190:193], v[214:217], v[18:21]
	v_mfma_f32_16x16x32_bf16 v[34:37], v[186:189], v[202:205], v[34:37]
	v_mfma_f32_16x16x32_bf16 v[34:37], v[190:193], v[206:209], v[34:37]
	v_mfma_f32_16x16x32_bf16 v[50:53], v[186:189], v[194:197], v[50:53]
	v_mfma_f32_16x16x32_bf16 v[50:53], v[190:193], v[198:201], v[50:53]
	s_barrier
	s_setprio 0
	s_add_i32 s64, 0, 0x18000
	s_add_i32 s65, 0, 0x1c000
	v_add_u32_e32 v170, s64, v156
	v_add_u32_e32 v179, s65, v156
	ds_read_b128 v[146:149], v170
	ds_read_b128 v[150:153], v170 offset:1024
	ds_read_b128 v[166:169], v170 offset:2048
	ds_read_b128 v[170:173], v170 offset:3072
	ds_read_b128 v[174:177], v179
	ds_read_b128 v[182:185], v179 offset:1024
	ds_read_b128 v[186:189], v179 offset:2048
	ds_read_b128 v[190:193], v179 offset:3072
	s_add_u32 s28, s28, 0x80000
	s_addc_u32 s29, s29, 0
	s_mov_b32 m0, s31
	v_lshl_add_u64 v[234:235], s[28:29], 0, v[130:131]
	ds_read_b128 v[194:197], v164 offset:32768
	ds_read_b128 v[198:201], v164 offset:33792
	ds_read_b128 v[202:205], v164 offset:34816
	ds_read_b128 v[206:209], v164 offset:35840
	ds_read_b128 v[210:213], v164 offset:36864
	ds_read_b128 v[214:217], v164 offset:37888
	ds_read_b128 v[218:221], v164 offset:38912
	ds_read_b128 v[222:225], v164 offset:39936
	global_load_lds_dwordx4 v[234:235], off
	v_lshl_add_u64 v[234:235], s[28:29], 0, v[134:135]
	s_mov_b32 m0, s34
	s_nop 0
	global_load_lds_dwordx4 v[234:235], off
	s_waitcnt vmcnt(8)
	s_waitcnt lgkmcnt(0)
	s_setprio 1
	s_barrier
	v_mfma_f32_16x16x32_bf16 v[126:129], v[146:149], v[194:197], v[126:129]
	v_mfma_f32_16x16x32_bf16 v[126:129], v[150:153], v[198:201], v[126:129]
	v_mfma_f32_16x16x32_bf16 v[110:113], v[146:149], v[202:205], v[110:113]
	v_mfma_f32_16x16x32_bf16 v[110:113], v[150:153], v[206:209], v[110:113]
	v_mfma_f32_16x16x32_bf16 v[94:97], v[146:149], v[210:213], v[94:97]
	v_mfma_f32_16x16x32_bf16 v[94:97], v[150:153], v[214:217], v[94:97]
	v_mfma_f32_16x16x32_bf16 v[78:81], v[146:149], v[218:221], v[78:81]
	v_mfma_f32_16x16x32_bf16 v[78:81], v[150:153], v[222:225], v[78:81]
	v_mfma_f32_16x16x32_bf16 v[74:77], v[166:169], v[218:221], v[74:77]
	v_mfma_f32_16x16x32_bf16 v[74:77], v[170:173], v[222:225], v[74:77]
	v_mfma_f32_16x16x32_bf16 v[90:93], v[166:169], v[210:213], v[90:93]
	v_mfma_f32_16x16x32_bf16 v[90:93], v[170:173], v[214:217], v[90:93]
	v_mfma_f32_16x16x32_bf16 v[106:109], v[166:169], v[202:205], v[106:109]
	v_mfma_f32_16x16x32_bf16 v[106:109], v[170:173], v[206:209], v[106:109]
	v_mfma_f32_16x16x32_bf16 v[122:125], v[166:169], v[194:197], v[122:125]
	v_mfma_f32_16x16x32_bf16 v[122:125], v[170:173], v[198:201], v[122:125]
	v_mfma_f32_16x16x32_bf16 v[118:121], v[174:177], v[194:197], v[118:121]
	v_mfma_f32_16x16x32_bf16 v[118:121], v[182:185], v[198:201], v[118:121]
	v_mfma_f32_16x16x32_bf16 v[102:105], v[174:177], v[202:205], v[102:105]
	v_mfma_f32_16x16x32_bf16 v[102:105], v[182:185], v[206:209], v[102:105]
	v_mfma_f32_16x16x32_bf16 v[86:89], v[174:177], v[210:213], v[86:89]
	v_mfma_f32_16x16x32_bf16 v[86:89], v[182:185], v[214:217], v[86:89]
	v_mfma_f32_16x16x32_bf16 v[70:73], v[174:177], v[218:221], v[70:73]
	v_mfma_f32_16x16x32_bf16 v[70:73], v[182:185], v[222:225], v[70:73]
	v_mfma_f32_16x16x32_bf16 v[66:69], v[186:189], v[218:221], v[66:69]
	v_mfma_f32_16x16x32_bf16 v[66:69], v[190:193], v[222:225], v[66:69]
	v_mfma_f32_16x16x32_bf16 v[82:85], v[186:189], v[210:213], v[82:85]
	v_mfma_f32_16x16x32_bf16 v[82:85], v[190:193], v[214:217], v[82:85]
	v_mfma_f32_16x16x32_bf16 v[98:101], v[186:189], v[202:205], v[98:101]
	v_mfma_f32_16x16x32_bf16 v[98:101], v[190:193], v[206:209], v[98:101]
	v_mfma_f32_16x16x32_bf16 v[114:117], v[186:189], v[194:197], v[114:117]
	v_mfma_f32_16x16x32_bf16 v[114:117], v[190:193], v[198:201], v[114:117]
	s_barrier
	s_setprio 0
	s_add_i32 s28, s64, s30
	v_lshl_add_u64 v[226:227], v[226:227], 0, s[10:11]
	s_mov_b32 m0, s28
	ds_read_b128 v[194:197], v164 offset:49152
	ds_read_b128 v[198:201], v164 offset:50176
	ds_read_b128 v[202:205], v164 offset:51200
	ds_read_b128 v[206:209], v164 offset:52224
	ds_read_b128 v[210:213], v164 offset:53248
	ds_read_b128 v[214:217], v164 offset:54272
	ds_read_b128 v[218:221], v164 offset:55296
	ds_read_b128 v[222:225], v164 offset:56320
	global_load_lds_dwordx4 v[226:227], off
	s_add_i32 m0, s28, 0x2000
	s_add_u32 s26, s26, 0x80080
	v_lshl_add_u64 v[226:227], v[228:229], 0, s[10:11]
	s_addc_u32 s27, s27, 0
	s_add_i32 s28, s65, s30
	global_load_lds_dwordx4 v[226:227], off
	v_lshl_add_u64 v[226:227], s[26:27], 0, v[132:133]
	s_mov_b32 m0, s28
	s_nop 0
	global_load_lds_dwordx4 v[226:227], off
	v_lshl_add_u64 v[226:227], s[26:27], 0, v[136:137]
	s_add_i32 m0, s28, 0x2000
	s_nop 0
	global_load_lds_dwordx4 v[226:227], off
	v_lshl_add_u64 v[226:227], v[230:231], 0, s[10:11]
	s_mov_b32 m0, s36
	s_nop 0
	global_load_lds_dwordx4 v[226:227], off
	v_lshl_add_u64 v[226:227], v[232:233], 0, s[10:11]
	s_mov_b32 m0, s37
	s_nop 0
	global_load_lds_dwordx4 v[226:227], off
	s_waitcnt vmcnt(8)
	s_waitcnt lgkmcnt(0)
	s_setprio 1
	s_barrier
	v_mfma_f32_16x16x32_bf16 v[62:65], v[146:149], v[194:197], v[62:65]
	v_mfma_f32_16x16x32_bf16 v[62:65], v[150:153], v[198:201], v[62:65]
	v_mfma_f32_16x16x32_bf16 v[46:49], v[146:149], v[202:205], v[46:49]
	v_mfma_f32_16x16x32_bf16 v[46:49], v[150:153], v[206:209], v[46:49]
	v_mfma_f32_16x16x32_bf16 v[30:33], v[146:149], v[210:213], v[30:33]
	v_mfma_f32_16x16x32_bf16 v[30:33], v[150:153], v[214:217], v[30:33]
	v_mfma_f32_16x16x32_bf16 v[14:17], v[146:149], v[218:221], v[14:17]
	v_mfma_f32_16x16x32_bf16 v[14:17], v[150:153], v[222:225], v[14:17]
	v_mfma_f32_16x16x32_bf16 v[10:13], v[166:169], v[218:221], v[10:13]
	v_mfma_f32_16x16x32_bf16 v[10:13], v[170:173], v[222:225], v[10:13]
	v_mfma_f32_16x16x32_bf16 v[26:29], v[166:169], v[210:213], v[26:29]
	v_mfma_f32_16x16x32_bf16 v[26:29], v[170:173], v[214:217], v[26:29]
	v_mfma_f32_16x16x32_bf16 v[42:45], v[166:169], v[202:205], v[42:45]
	v_mfma_f32_16x16x32_bf16 v[42:45], v[170:173], v[206:209], v[42:45]
	v_mfma_f32_16x16x32_bf16 v[58:61], v[166:169], v[194:197], v[58:61]
	v_mfma_f32_16x16x32_bf16 v[58:61], v[170:173], v[198:201], v[58:61]
	v_mfma_f32_16x16x32_bf16 v[54:57], v[174:177], v[194:197], v[54:57]
	v_mfma_f32_16x16x32_bf16 v[54:57], v[182:185], v[198:201], v[54:57]
	v_mfma_f32_16x16x32_bf16 v[38:41], v[174:177], v[202:205], v[38:41]
	v_mfma_f32_16x16x32_bf16 v[38:41], v[182:185], v[206:209], v[38:41]
	v_mfma_f32_16x16x32_bf16 v[22:25], v[174:177], v[210:213], v[22:25]
	v_mfma_f32_16x16x32_bf16 v[22:25], v[182:185], v[214:217], v[22:25]
	v_mfma_f32_16x16x32_bf16 v[6:9], v[174:177], v[218:221], v[6:9]
	v_mfma_f32_16x16x32_bf16 v[6:9], v[182:185], v[222:225], v[6:9]
	v_mfma_f32_16x16x32_bf16 v[2:5], v[186:189], v[218:221], v[2:5]
	v_mfma_f32_16x16x32_bf16 v[2:5], v[190:193], v[222:225], v[2:5]
	v_mfma_f32_16x16x32_bf16 v[18:21], v[186:189], v[210:213], v[18:21]
	v_mfma_f32_16x16x32_bf16 v[18:21], v[190:193], v[214:217], v[18:21]
	v_mfma_f32_16x16x32_bf16 v[34:37], v[186:189], v[202:205], v[34:37]
	v_mfma_f32_16x16x32_bf16 v[34:37], v[190:193], v[206:209], v[34:37]
	v_mfma_f32_16x16x32_bf16 v[50:53], v[186:189], v[194:197], v[50:53]
	v_mfma_f32_16x16x32_bf16 v[50:53], v[190:193], v[198:201], v[50:53]
	s_barrier
	s_setprio 0
	s_add_i32 s63, s63, 2
	s_add_u32 s4, s4, 0x100
	s_addc_u32 s5, s5, 0
	s_add_u32 s60, s60, 0x100
	s_addc_u32 s62, s62, 0
	s_cmp_gt_u32 s63, 29
	s_cbranch_scc0 .LBB0_236
	s_and_b64 vcc, exec, s[12:13]
	s_cbranch_vccz .LBB0_239
	s_barrier

.LBB0_591:
	ds_read_b128 v[144:147], v150
	ds_read_b128 v[154:157], v150 offset:1024
	ds_read_b128 v[158:161], v150 offset:2048
	ds_read_b128 v[162:165], v150 offset:3072
	ds_read_b128 v[166:169], v151
	ds_read_b128 v[170:173], v151 offset:1024
	ds_read_b128 v[174:177], v151 offset:2048
	ds_read_b128 v[182:185], v151 offset:3072
	s_add_i32 s63, s22, 2
	s_add_u32 s23, s20, 0xfff80080
	s_addc_u32 s26, s21, -1
	s_cmp_eq_u32 s11, s22
	s_cselect_b32 s22, s18, s13
	s_cselect_b32 s27, s17, s26
	s_cselect_b32 s26, s16, s23
	s_cselect_b32 s23, s19, s15
	v_lshl_add_u64 v[218:219], s[20:21], 0, v[138:139]
	s_add_i32 m0, s3, 0xc000
	ds_read_b128 v[186:189], v152
	ds_read_b128 v[190:193], v152 offset:1024
	ds_read_b128 v[194:197], v152 offset:2048
	ds_read_b128 v[198:201], v152 offset:3072
	ds_read_b128 v[202:205], v152 offset:4096
	ds_read_b128 v[206:209], v152 offset:5120
	ds_read_b128 v[210:213], v152 offset:6144
	ds_read_b128 v[214:217], v152 offset:7168
	global_load_lds_dwordx4 v[218:219], off
	v_lshl_add_u64 v[218:219], s[20:21], 0, v[140:141]
	s_add_i32 m0, s3, 0xe000
	s_nop 0
	global_load_lds_dwordx4 v[218:219], off
	s_waitcnt vmcnt(8)
	s_waitcnt lgkmcnt(0)
	s_setprio 1
	s_barrier
	v_mfma_f32_16x16x32_bf16 v[126:129], v[144:147], v[186:189], v[126:129]
	v_mfma_f32_16x16x32_bf16 v[126:129], v[154:157], v[190:193], v[126:129]
	v_mfma_f32_16x16x32_bf16 v[118:121], v[144:147], v[194:197], v[118:121]
	v_mfma_f32_16x16x32_bf16 v[118:121], v[154:157], v[198:201], v[118:121]
	v_mfma_f32_16x16x32_bf16 v[106:109], v[144:147], v[202:205], v[106:109]
	v_mfma_f32_16x16x32_bf16 v[106:109], v[154:157], v[206:209], v[106:109]
	v_mfma_f32_16x16x32_bf16 v[90:93], v[144:147], v[210:213], v[90:93]
	v_mfma_f32_16x16x32_bf16 v[90:93], v[154:157], v[214:217], v[90:93]
	v_mfma_f32_16x16x32_bf16 v[82:85], v[158:161], v[210:213], v[82:85]
	v_mfma_f32_16x16x32_bf16 v[82:85], v[162:165], v[214:217], v[82:85]
	v_mfma_f32_16x16x32_bf16 v[98:101], v[158:161], v[202:205], v[98:101]
	v_mfma_f32_16x16x32_bf16 v[98:101], v[162:165], v[206:209], v[98:101]
	v_mfma_f32_16x16x32_bf16 v[114:117], v[158:161], v[194:197], v[114:117]
	v_mfma_f32_16x16x32_bf16 v[114:117], v[162:165], v[198:201], v[114:117]
	v_mfma_f32_16x16x32_bf16 v[122:125], v[158:161], v[186:189], v[122:125]
	v_mfma_f32_16x16x32_bf16 v[122:125], v[162:165], v[190:193], v[122:125]
	v_mfma_f32_16x16x32_bf16 v[110:113], v[166:169], v[186:189], v[110:113]
	v_mfma_f32_16x16x32_bf16 v[110:113], v[170:173], v[190:193], v[110:113]
	v_mfma_f32_16x16x32_bf16 v[94:97], v[166:169], v[194:197], v[94:97]
	v_mfma_f32_16x16x32_bf16 v[94:97], v[170:173], v[198:201], v[94:97]
	v_mfma_f32_16x16x32_bf16 v[78:81], v[166:169], v[202:205], v[78:81]
	v_mfma_f32_16x16x32_bf16 v[78:81], v[170:173], v[206:209], v[78:81]
	v_mfma_f32_16x16x32_bf16 v[70:73], v[166:169], v[210:213], v[70:73]
	v_mfma_f32_16x16x32_bf16 v[70:73], v[170:173], v[214:217], v[70:73]
	v_mfma_f32_16x16x32_bf16 v[66:69], v[174:177], v[210:213], v[66:69]
	v_mfma_f32_16x16x32_bf16 v[66:69], v[182:185], v[214:217], v[66:69]
	v_mfma_f32_16x16x32_bf16 v[74:77], v[174:177], v[202:205], v[74:77]
	v_mfma_f32_16x16x32_bf16 v[74:77], v[182:185], v[206:209], v[74:77]
	v_mfma_f32_16x16x32_bf16 v[86:89], v[174:177], v[194:197], v[86:89]
	v_mfma_f32_16x16x32_bf16 v[86:89], v[182:185], v[198:201], v[86:89]
	v_mfma_f32_16x16x32_bf16 v[102:105], v[174:177], v[186:189], v[102:105]
	v_mfma_f32_16x16x32_bf16 v[102:105], v[182:185], v[190:193], v[102:105]
	s_barrier
	s_setprio 0
	s_add_i32 s66, s56, s30
	v_lshl_add_u64 v[218:219], s[22:23], 0, v[132:133]
	s_mov_b32 m0, s66
	ds_read_b128 v[186:189], v152 offset:16384
	ds_read_b128 v[190:193], v152 offset:17408
	ds_read_b128 v[194:197], v152 offset:18432
	ds_read_b128 v[198:201], v152 offset:19456
	ds_read_b128 v[202:205], v152 offset:20480
	ds_read_b128 v[206:209], v152 offset:21504
	ds_read_b128 v[210:213], v152 offset:22528
	ds_read_b128 v[214:217], v152 offset:23552
	global_load_lds_dwordx4 v[218:219], off
	s_add_i32 m0, s66, 0x2000
	s_add_u32 s66, s22, 0x80000
	v_lshl_add_u64 v[220:221], s[22:23], 0, v[136:137]
	s_addc_u32 s67, s23, 0
	s_add_i32 s68, s57, s30
	global_load_lds_dwordx4 v[220:221], off
	v_lshl_add_u64 v[222:223], s[66:67], 0, v[132:133]
	s_mov_b32 m0, s68
	v_lshl_add_u64 v[224:225], s[26:27], 0, v[134:135]
	global_load_lds_dwordx4 v[222:223], off
	v_lshl_add_u64 v[222:223], s[66:67], 0, v[136:137]
	s_add_i32 m0, s68, 0x2000
	s_nop 0
	global_load_lds_dwordx4 v[222:223], off
	v_lshl_add_u64 v[222:223], s[26:27], 0, v[130:131]
	s_mov_b32 m0, s3
	s_nop 0
	global_load_lds_dwordx4 v[222:223], off
	s_mov_b32 m0, s34
	s_nop 0
	global_load_lds_dwordx4 v[224:225], off
	s_waitcnt vmcnt(8)
	s_waitcnt lgkmcnt(0)
	s_setprio 1
	s_barrier
	v_mfma_f32_16x16x32_bf16 v[62:65], v[144:147], v[186:189], v[62:65]
	v_mfma_f32_16x16x32_bf16 v[62:65], v[154:157], v[190:193], v[62:65]
	v_mfma_f32_16x16x32_bf16 v[54:57], v[144:147], v[194:197], v[54:57]
	v_mfma_f32_16x16x32_bf16 v[54:57], v[154:157], v[198:201], v[54:57]
	v_mfma_f32_16x16x32_bf16 v[38:41], v[144:147], v[202:205], v[38:41]
	v_mfma_f32_16x16x32_bf16 v[38:41], v[154:157], v[206:209], v[38:41]
	v_mfma_f32_16x16x32_bf16 v[22:25], v[144:147], v[210:213], v[22:25]
	v_mfma_f32_16x16x32_bf16 v[22:25], v[154:157], v[214:217], v[22:25]
	v_mfma_f32_16x16x32_bf16 v[18:21], v[158:161], v[210:213], v[18:21]
	v_mfma_f32_16x16x32_bf16 v[18:21], v[162:165], v[214:217], v[18:21]
	v_mfma_f32_16x16x32_bf16 v[34:37], v[158:161], v[202:205], v[34:37]
	v_mfma_f32_16x16x32_bf16 v[34:37], v[162:165], v[206:209], v[34:37]
	v_mfma_f32_16x16x32_bf16 v[50:53], v[158:161], v[194:197], v[50:53]
	v_mfma_f32_16x16x32_bf16 v[50:53], v[162:165], v[198:201], v[50:53]
	v_mfma_f32_16x16x32_bf16 v[58:61], v[158:161], v[186:189], v[58:61]
	v_mfma_f32_16x16x32_bf16 v[58:61], v[162:165], v[190:193], v[58:61]
	v_mfma_f32_16x16x32_bf16 v[46:49], v[166:169], v[186:189], v[46:49]
	v_mfma_f32_16x16x32_bf16 v[46:49], v[170:173], v[190:193], v[46:49]
	v_mfma_f32_16x16x32_bf16 v[30:33], v[166:169], v[194:197], v[30:33]
	v_mfma_f32_16x16x32_bf16 v[30:33], v[170:173], v[198:201], v[30:33]
	v_mfma_f32_16x16x32_bf16 v[14:17], v[166:169], v[202:205], v[14:17]
	v_mfma_f32_16x16x32_bf16 v[14:17], v[170:173], v[206:209], v[14:17]
	v_mfma_f32_16x16x32_bf16 v[6:9], v[166:169], v[210:213], v[6:9]
	v_mfma_f32_16x16x32_bf16 v[6:9], v[170:173], v[214:217], v[6:9]
	v_mfma_f32_16x16x32_bf16 v[2:5], v[174:177], v[210:213], v[2:5]
	v_mfma_f32_16x16x32_bf16 v[2:5], v[182:185], v[214:217], v[2:5]
	v_mfma_f32_16x16x32_bf16 v[10:13], v[174:177], v[202:205], v[10:13]
	v_mfma_f32_16x16x32_bf16 v[10:13], v[182:185], v[206:209], v[10:13]
	v_mfma_f32_16x16x32_bf16 v[26:29], v[174:177], v[194:197], v[26:29]
	v_mfma_f32_16x16x32_bf16 v[26:29], v[182:185], v[198:201], v[26:29]
	v_mfma_f32_16x16x32_bf16 v[42:45], v[174:177], v[186:189], v[42:45]
	v_mfma_f32_16x16x32_bf16 v[42:45], v[182:185], v[190:193], v[42:45]
	s_barrier
	s_setprio 0
	s_add_i32 s66, 0, 0x18000
	v_add_u32_e32 v153, s66, v148
	s_add_i32 s67, 0, 0x1c000
	ds_read_b128 v[144:147], v153
	ds_read_b128 v[154:157], v153 offset:1024
	ds_read_b128 v[158:161], v153 offset:2048
	ds_read_b128 v[162:165], v153 offset:3072
	v_add_u32_e32 v153, s67, v148
	ds_read_b128 v[166:169], v153
	ds_read_b128 v[170:173], v153 offset:1024
	ds_read_b128 v[174:177], v153 offset:2048
	ds_read_b128 v[182:185], v153 offset:3072
	s_add_u32 s26, s26, 0x80000
	s_addc_u32 s27, s27, 0
	s_mov_b32 m0, s35
	v_lshl_add_u64 v[226:227], s[26:27], 0, v[130:131]
	ds_read_b128 v[186:189], v152 offset:32768
	ds_read_b128 v[190:193], v152 offset:33792
	ds_read_b128 v[194:197], v152 offset:34816
	ds_read_b128 v[198:201], v152 offset:35840
	ds_read_b128 v[202:205], v152 offset:36864
	ds_read_b128 v[206:209], v152 offset:37888
	ds_read_b128 v[210:213], v152 offset:38912
	ds_read_b128 v[214:217], v152 offset:39936
	global_load_lds_dwordx4 v[226:227], off
	v_lshl_add_u64 v[226:227], s[26:27], 0, v[134:135]
	s_mov_b32 m0, s36
	s_nop 0
	global_load_lds_dwordx4 v[226:227], off
	s_waitcnt vmcnt(8)
	s_waitcnt lgkmcnt(0)
	s_setprio 1
	s_barrier
	v_mfma_f32_16x16x32_bf16 v[126:129], v[144:147], v[186:189], v[126:129]
	v_mfma_f32_16x16x32_bf16 v[126:129], v[154:157], v[190:193], v[126:129]
	v_mfma_f32_16x16x32_bf16 v[118:121], v[144:147], v[194:197], v[118:121]
	v_mfma_f32_16x16x32_bf16 v[118:121], v[154:157], v[198:201], v[118:121]
	v_mfma_f32_16x16x32_bf16 v[106:109], v[144:147], v[202:205], v[106:109]
	v_mfma_f32_16x16x32_bf16 v[106:109], v[154:157], v[206:209], v[106:109]
	v_mfma_f32_16x16x32_bf16 v[90:93], v[144:147], v[210:213], v[90:93]
	v_mfma_f32_16x16x32_bf16 v[90:93], v[154:157], v[214:217], v[90:93]
	v_mfma_f32_16x16x32_bf16 v[82:85], v[158:161], v[210:213], v[82:85]
	v_mfma_f32_16x16x32_bf16 v[82:85], v[162:165], v[214:217], v[82:85]
	v_mfma_f32_16x16x32_bf16 v[98:101], v[158:161], v[202:205], v[98:101]
	v_mfma_f32_16x16x32_bf16 v[98:101], v[162:165], v[206:209], v[98:101]
	v_mfma_f32_16x16x32_bf16 v[114:117], v[158:161], v[194:197], v[114:117]
	v_mfma_f32_16x16x32_bf16 v[114:117], v[162:165], v[198:201], v[114:117]
	v_mfma_f32_16x16x32_bf16 v[122:125], v[158:161], v[186:189], v[122:125]
	v_mfma_f32_16x16x32_bf16 v[122:125], v[162:165], v[190:193], v[122:125]
	v_mfma_f32_16x16x32_bf16 v[110:113], v[166:169], v[186:189], v[110:113]
	v_mfma_f32_16x16x32_bf16 v[110:113], v[170:173], v[190:193], v[110:113]
	v_mfma_f32_16x16x32_bf16 v[94:97], v[166:169], v[194:197], v[94:97]
	v_mfma_f32_16x16x32_bf16 v[94:97], v[170:173], v[198:201], v[94:97]
	v_mfma_f32_16x16x32_bf16 v[78:81], v[166:169], v[202:205], v[78:81]
	v_mfma_f32_16x16x32_bf16 v[78:81], v[170:173], v[206:209], v[78:81]
	v_mfma_f32_16x16x32_bf16 v[70:73], v[166:169], v[210:213], v[70:73]
	v_mfma_f32_16x16x32_bf16 v[70:73], v[170:173], v[214:217], v[70:73]
	v_mfma_f32_16x16x32_bf16 v[66:69], v[174:177], v[210:213], v[66:69]
	v_mfma_f32_16x16x32_bf16 v[66:69], v[182:185], v[214:217], v[66:69]
	v_mfma_f32_16x16x32_bf16 v[74:77], v[174:177], v[202:205], v[74:77]
	v_mfma_f32_16x16x32_bf16 v[74:77], v[182:185], v[206:209], v[74:77]
	v_mfma_f32_16x16x32_bf16 v[86:89], v[174:177], v[194:197], v[86:89]
	v_mfma_f32_16x16x32_bf16 v[86:89], v[182:185], v[198:201], v[86:89]
	v_mfma_f32_16x16x32_bf16 v[102:105], v[174:177], v[186:189], v[102:105]
	v_mfma_f32_16x16x32_bf16 v[102:105], v[182:185], v[190:193], v[102:105]
	s_barrier
	s_setprio 0
	s_add_i32 s26, s66, s30
	v_lshl_add_u64 v[218:219], v[218:219], 0, s[6:7]
	s_mov_b32 m0, s26
	ds_read_b128 v[186:189], v152 offset:49152
	ds_read_b128 v[190:193], v152 offset:50176
	ds_read_b128 v[194:197], v152 offset:51200
	ds_read_b128 v[198:201], v152 offset:52224
	ds_read_b128 v[202:205], v152 offset:53248
	ds_read_b128 v[206:209], v152 offset:54272
	ds_read_b128 v[210:213], v152 offset:55296
	ds_read_b128 v[214:217], v152 offset:56320
	global_load_lds_dwordx4 v[218:219], off
	s_add_i32 m0, s26, 0x2000
	s_add_u32 s22, s22, 0x80080
	v_lshl_add_u64 v[218:219], v[220:221], 0, s[6:7]
	s_addc_u32 s23, s23, 0
	s_add_i32 s26, s67, s30
	global_load_lds_dwordx4 v[218:219], off
	v_lshl_add_u64 v[218:219], s[22:23], 0, v[132:133]
	s_mov_b32 m0, s26
	s_nop 0
	global_load_lds_dwordx4 v[218:219], off
	v_lshl_add_u64 v[218:219], s[22:23], 0, v[136:137]
	s_add_i32 m0, s26, 0x2000
	s_nop 0
	global_load_lds_dwordx4 v[218:219], off
	v_lshl_add_u64 v[218:219], v[222:223], 0, s[6:7]
	s_mov_b32 m0, s52
	s_nop 0
	global_load_lds_dwordx4 v[218:219], off
	v_lshl_add_u64 v[218:219], v[224:225], 0, s[6:7]
	s_mov_b32 m0, s53
	s_nop 0
	global_load_lds_dwordx4 v[218:219], off
	s_waitcnt vmcnt(8)
	s_waitcnt lgkmcnt(0)
	s_setprio 1
	s_barrier
	v_mfma_f32_16x16x32_bf16 v[62:65], v[144:147], v[186:189], v[62:65]
	v_mfma_f32_16x16x32_bf16 v[62:65], v[154:157], v[190:193], v[62:65]
	v_mfma_f32_16x16x32_bf16 v[54:57], v[144:147], v[194:197], v[54:57]
	v_mfma_f32_16x16x32_bf16 v[54:57], v[154:157], v[198:201], v[54:57]
	v_mfma_f32_16x16x32_bf16 v[38:41], v[144:147], v[202:205], v[38:41]
	v_mfma_f32_16x16x32_bf16 v[38:41], v[154:157], v[206:209], v[38:41]
	v_mfma_f32_16x16x32_bf16 v[22:25], v[144:147], v[210:213], v[22:25]
	v_mfma_f32_16x16x32_bf16 v[22:25], v[154:157], v[214:217], v[22:25]
	v_mfma_f32_16x16x32_bf16 v[18:21], v[158:161], v[210:213], v[18:21]
	v_mfma_f32_16x16x32_bf16 v[18:21], v[162:165], v[214:217], v[18:21]
	v_mfma_f32_16x16x32_bf16 v[34:37], v[158:161], v[202:205], v[34:37]
	v_mfma_f32_16x16x32_bf16 v[34:37], v[162:165], v[206:209], v[34:37]
	v_mfma_f32_16x16x32_bf16 v[50:53], v[158:161], v[194:197], v[50:53]
	v_mfma_f32_16x16x32_bf16 v[50:53], v[162:165], v[198:201], v[50:53]
	v_mfma_f32_16x16x32_bf16 v[58:61], v[158:161], v[186:189], v[58:61]
	v_mfma_f32_16x16x32_bf16 v[58:61], v[162:165], v[190:193], v[58:61]
	v_mfma_f32_16x16x32_bf16 v[46:49], v[166:169], v[186:189], v[46:49]
	v_mfma_f32_16x16x32_bf16 v[46:49], v[170:173], v[190:193], v[46:49]
	v_mfma_f32_16x16x32_bf16 v[30:33], v[166:169], v[194:197], v[30:33]
	v_mfma_f32_16x16x32_bf16 v[30:33], v[170:173], v[198:201], v[30:33]
	v_mfma_f32_16x16x32_bf16 v[14:17], v[166:169], v[202:205], v[14:17]
	v_mfma_f32_16x16x32_bf16 v[14:17], v[170:173], v[206:209], v[14:17]
	v_mfma_f32_16x16x32_bf16 v[6:9], v[166:169], v[210:213], v[6:9]
	v_mfma_f32_16x16x32_bf16 v[6:9], v[170:173], v[214:217], v[6:9]
	v_mfma_f32_16x16x32_bf16 v[2:5], v[174:177], v[210:213], v[2:5]
	v_mfma_f32_16x16x32_bf16 v[2:5], v[182:185], v[214:217], v[2:5]
	v_mfma_f32_16x16x32_bf16 v[10:13], v[174:177], v[202:205], v[10:13]
	v_mfma_f32_16x16x32_bf16 v[10:13], v[182:185], v[206:209], v[10:13]
	v_mfma_f32_16x16x32_bf16 v[26:29], v[174:177], v[194:197], v[26:29]
	v_mfma_f32_16x16x32_bf16 v[26:29], v[182:185], v[198:201], v[26:29]
	v_mfma_f32_16x16x32_bf16 v[42:45], v[174:177], v[186:189], v[42:45]
	v_mfma_f32_16x16x32_bf16 v[42:45], v[182:185], v[190:193], v[42:45]
	s_barrier
	s_setprio 0
	s_add_u32 s20, s20, 0x100
	s_addc_u32 s21, s21, 0
	s_add_u32 s13, s13, 0x100
	s_addc_u32 s15, s15, 0
	s_cmp_ge_i32 s63, s62
	s_mov_b32 s22, s63
	s_cbranch_scc0 .LBB0_591
	s_and_b64 vcc, exec, s[8:9]
	s_cbranch_vccz .LBB0_594
	s_barrier

.LBB0_736:
	ds_read_b128 v[154:157], v151
	ds_read_b128 v[158:161], v151 offset:1024
	ds_read_b128 v[162:165], v151 offset:2048
	ds_read_b128 v[166:169], v151 offset:3072
	ds_read_b128 v[170:173], v152
	ds_read_b128 v[174:177], v152 offset:1024
	ds_read_b128 v[182:185], v152 offset:2048
	ds_read_b128 v[186:189], v152 offset:3072
	s_add_u32 s20, s18, 0xfff80080
	s_addc_u32 s21, s19, -1
	s_cmp_eq_u32 s63, 28
	s_cselect_b32 s23, s11, s21
	s_cselect_b32 s22, s58, s20
	s_cselect_b32 s21, s9, s62
	s_cselect_b32 s20, s59, s60
	v_lshl_add_u64 v[146:147], s[18:19], 0, v[138:139]
	s_add_i32 m0, s31, 0xc000
	ds_read_b128 v[190:193], v153
	ds_read_b128 v[194:197], v153 offset:1024
	ds_read_b128 v[198:201], v153 offset:2048
	ds_read_b128 v[202:205], v153 offset:3072
	ds_read_b128 v[206:209], v153 offset:4096
	ds_read_b128 v[210:213], v153 offset:5120
	ds_read_b128 v[214:217], v153 offset:6144
	ds_read_b128 v[218:221], v153 offset:7168
	global_load_lds_dwordx4 v[146:147], off
	v_lshl_add_u64 v[146:147], s[18:19], 0, v[140:141]
	s_add_i32 m0, s31, 0xe000
	s_nop 0
	global_load_lds_dwordx4 v[146:147], off
	s_waitcnt vmcnt(8)
	s_waitcnt lgkmcnt(0)
	s_setprio 1
	s_barrier
	v_mfma_f32_16x16x32_bf16 v[126:129], v[154:157], v[190:193], v[126:129]
	v_mfma_f32_16x16x32_bf16 v[126:129], v[158:161], v[194:197], v[126:129]
	v_mfma_f32_16x16x32_bf16 v[110:113], v[154:157], v[198:201], v[110:113]
	v_mfma_f32_16x16x32_bf16 v[110:113], v[158:161], v[202:205], v[110:113]
	v_mfma_f32_16x16x32_bf16 v[94:97], v[154:157], v[206:209], v[94:97]
	v_mfma_f32_16x16x32_bf16 v[94:97], v[158:161], v[210:213], v[94:97]
	v_mfma_f32_16x16x32_bf16 v[78:81], v[154:157], v[214:217], v[78:81]
	v_mfma_f32_16x16x32_bf16 v[78:81], v[158:161], v[218:221], v[78:81]
	v_mfma_f32_16x16x32_bf16 v[70:73], v[162:165], v[214:217], v[70:73]
	v_mfma_f32_16x16x32_bf16 v[70:73], v[166:169], v[218:221], v[70:73]
	v_mfma_f32_16x16x32_bf16 v[86:89], v[162:165], v[206:209], v[86:89]
	v_mfma_f32_16x16x32_bf16 v[86:89], v[166:169], v[210:213], v[86:89]
	v_mfma_f32_16x16x32_bf16 v[102:105], v[162:165], v[198:201], v[102:105]
	v_mfma_f32_16x16x32_bf16 v[102:105], v[166:169], v[202:205], v[102:105]
	v_mfma_f32_16x16x32_bf16 v[118:121], v[162:165], v[190:193], v[118:121]
	v_mfma_f32_16x16x32_bf16 v[118:121], v[166:169], v[194:197], v[118:121]
	v_mfma_f32_16x16x32_bf16 v[122:125], v[170:173], v[190:193], v[122:125]
	v_mfma_f32_16x16x32_bf16 v[122:125], v[174:177], v[194:197], v[122:125]
	v_mfma_f32_16x16x32_bf16 v[106:109], v[170:173], v[198:201], v[106:109]
	v_mfma_f32_16x16x32_bf16 v[106:109], v[174:177], v[202:205], v[106:109]
	v_mfma_f32_16x16x32_bf16 v[90:93], v[170:173], v[206:209], v[90:93]
	v_mfma_f32_16x16x32_bf16 v[90:93], v[174:177], v[210:213], v[90:93]
	v_mfma_f32_16x16x32_bf16 v[74:77], v[170:173], v[214:217], v[74:77]
	v_mfma_f32_16x16x32_bf16 v[74:77], v[174:177], v[218:221], v[74:77]
	v_mfma_f32_16x16x32_bf16 v[66:69], v[182:185], v[214:217], v[66:69]
	v_mfma_f32_16x16x32_bf16 v[66:69], v[186:189], v[218:221], v[66:69]
	v_mfma_f32_16x16x32_bf16 v[82:85], v[182:185], v[206:209], v[82:85]
	v_mfma_f32_16x16x32_bf16 v[82:85], v[186:189], v[210:213], v[82:85]
	v_mfma_f32_16x16x32_bf16 v[98:101], v[182:185], v[198:201], v[98:101]
	v_mfma_f32_16x16x32_bf16 v[98:101], v[186:189], v[202:205], v[98:101]
	v_mfma_f32_16x16x32_bf16 v[114:117], v[182:185], v[190:193], v[114:117]
	v_mfma_f32_16x16x32_bf16 v[114:117], v[186:189], v[194:197], v[114:117]
	s_barrier
	s_setprio 0
	s_add_i32 s66, s55, s28
	v_lshl_add_u64 v[146:147], s[20:21], 0, v[134:135]
	s_mov_b32 m0, s66
	ds_read_b128 v[190:193], v153 offset:16384
	ds_read_b128 v[194:197], v153 offset:17408
	ds_read_b128 v[198:201], v153 offset:18432
	ds_read_b128 v[202:205], v153 offset:19456
	ds_read_b128 v[206:209], v153 offset:20480
	ds_read_b128 v[210:213], v153 offset:21504
	ds_read_b128 v[214:217], v153 offset:22528
	ds_read_b128 v[218:221], v153 offset:23552
	global_load_lds_dwordx4 v[146:147], off
	s_add_i32 m0, s66, 0x2000
	s_add_u32 s66, s20, 0x80000
	v_lshl_add_u64 v[222:223], s[20:21], 0, v[130:131]
	s_addc_u32 s67, s21, 0
	s_add_i32 s68, s56, s28
	global_load_lds_dwordx4 v[222:223], off
	v_lshl_add_u64 v[224:225], s[66:67], 0, v[134:135]
	s_mov_b32 m0, s68
	v_lshl_add_u64 v[226:227], s[22:23], 0, v[132:133]
	global_load_lds_dwordx4 v[224:225], off
	v_lshl_add_u64 v[224:225], s[66:67], 0, v[130:131]
	s_add_i32 m0, s68, 0x2000
	s_nop 0
	global_load_lds_dwordx4 v[224:225], off
	v_lshl_add_u64 v[224:225], s[22:23], 0, v[136:137]
	s_mov_b32 m0, s31
	s_nop 0
	global_load_lds_dwordx4 v[224:225], off
	s_mov_b32 m0, s34
	s_nop 0
	global_load_lds_dwordx4 v[226:227], off
	s_waitcnt vmcnt(8)
	s_waitcnt lgkmcnt(0)
	s_setprio 1
	s_barrier
	v_mfma_f32_16x16x32_bf16 v[62:65], v[154:157], v[190:193], v[62:65]
	v_mfma_f32_16x16x32_bf16 v[62:65], v[158:161], v[194:197], v[62:65]
	v_mfma_f32_16x16x32_bf16 v[46:49], v[154:157], v[198:201], v[46:49]
	v_mfma_f32_16x16x32_bf16 v[46:49], v[158:161], v[202:205], v[46:49]
	v_mfma_f32_16x16x32_bf16 v[30:33], v[154:157], v[206:209], v[30:33]
	v_mfma_f32_16x16x32_bf16 v[30:33], v[158:161], v[210:213], v[30:33]
	v_mfma_f32_16x16x32_bf16 v[14:17], v[154:157], v[214:217], v[14:17]
	v_mfma_f32_16x16x32_bf16 v[14:17], v[158:161], v[218:221], v[14:17]
	v_mfma_f32_16x16x32_bf16 v[6:9], v[162:165], v[214:217], v[6:9]
	v_mfma_f32_16x16x32_bf16 v[6:9], v[166:169], v[218:221], v[6:9]
	v_mfma_f32_16x16x32_bf16 v[22:25], v[162:165], v[206:209], v[22:25]
	v_mfma_f32_16x16x32_bf16 v[22:25], v[166:169], v[210:213], v[22:25]
	v_mfma_f32_16x16x32_bf16 v[38:41], v[162:165], v[198:201], v[38:41]
	v_mfma_f32_16x16x32_bf16 v[38:41], v[166:169], v[202:205], v[38:41]
	v_mfma_f32_16x16x32_bf16 v[54:57], v[162:165], v[190:193], v[54:57]
	v_mfma_f32_16x16x32_bf16 v[54:57], v[166:169], v[194:197], v[54:57]
	v_mfma_f32_16x16x32_bf16 v[58:61], v[170:173], v[190:193], v[58:61]
	v_mfma_f32_16x16x32_bf16 v[58:61], v[174:177], v[194:197], v[58:61]
	v_mfma_f32_16x16x32_bf16 v[42:45], v[170:173], v[198:201], v[42:45]
	v_mfma_f32_16x16x32_bf16 v[42:45], v[174:177], v[202:205], v[42:45]
	v_mfma_f32_16x16x32_bf16 v[26:29], v[170:173], v[206:209], v[26:29]
	v_mfma_f32_16x16x32_bf16 v[26:29], v[174:177], v[210:213], v[26:29]
	v_mfma_f32_16x16x32_bf16 v[10:13], v[170:173], v[214:217], v[10:13]
	v_mfma_f32_16x16x32_bf16 v[10:13], v[174:177], v[218:221], v[10:13]
	v_mfma_f32_16x16x32_bf16 v[2:5], v[182:185], v[214:217], v[2:5]
	v_mfma_f32_16x16x32_bf16 v[2:5], v[186:189], v[218:221], v[2:5]
	v_mfma_f32_16x16x32_bf16 v[18:21], v[182:185], v[206:209], v[18:21]
	v_mfma_f32_16x16x32_bf16 v[18:21], v[186:189], v[210:213], v[18:21]
	v_mfma_f32_16x16x32_bf16 v[34:37], v[182:185], v[198:201], v[34:37]
	v_mfma_f32_16x16x32_bf16 v[34:37], v[186:189], v[202:205], v[34:37]
	v_mfma_f32_16x16x32_bf16 v[50:53], v[182:185], v[190:193], v[50:53]
	v_mfma_f32_16x16x32_bf16 v[50:53], v[186:189], v[194:197], v[50:53]
	s_barrier
	s_setprio 0
	s_add_i32 s66, 0, 0x18000
	s_add_i32 s67, 0, 0x1c000
	v_add_u32_e32 v166, s66, v149
	v_add_u32_e32 v179, s67, v149
	ds_read_b128 v[154:157], v166
	ds_read_b128 v[158:161], v166 offset:1024
	ds_read_b128 v[162:165], v166 offset:2048
	ds_read_b128 v[166:169], v166 offset:3072
	ds_read_b128 v[170:173], v179
	ds_read_b128 v[174:177], v179 offset:1024
	ds_read_b128 v[182:185], v179 offset:2048
	ds_read_b128 v[186:189], v179 offset:3072
	s_add_u32 s22, s22, 0x80000
	s_addc_u32 s23, s23, 0
	s_mov_b32 m0, s35
	v_lshl_add_u64 v[228:229], s[22:23], 0, v[136:137]
	ds_read_b128 v[190:193], v153 offset:32768
	ds_read_b128 v[194:197], v153 offset:33792
	ds_read_b128 v[198:201], v153 offset:34816
	ds_read_b128 v[202:205], v153 offset:35840
	ds_read_b128 v[206:209], v153 offset:36864
	ds_read_b128 v[210:213], v153 offset:37888
	ds_read_b128 v[214:217], v153 offset:38912
	ds_read_b128 v[218:221], v153 offset:39936
	global_load_lds_dwordx4 v[228:229], off
	v_lshl_add_u64 v[228:229], s[22:23], 0, v[132:133]
	s_mov_b32 m0, s36
	s_nop 0
	global_load_lds_dwordx4 v[228:229], off
	s_waitcnt vmcnt(8)
	s_waitcnt lgkmcnt(0)
	s_setprio 1
	s_barrier
	v_mfma_f32_16x16x32_bf16 v[126:129], v[154:157], v[190:193], v[126:129]
	v_mfma_f32_16x16x32_bf16 v[126:129], v[158:161], v[194:197], v[126:129]
	v_mfma_f32_16x16x32_bf16 v[110:113], v[154:157], v[198:201], v[110:113]
	v_mfma_f32_16x16x32_bf16 v[110:113], v[158:161], v[202:205], v[110:113]
	v_mfma_f32_16x16x32_bf16 v[94:97], v[154:157], v[206:209], v[94:97]
	v_mfma_f32_16x16x32_bf16 v[94:97], v[158:161], v[210:213], v[94:97]
	v_mfma_f32_16x16x32_bf16 v[78:81], v[154:157], v[214:217], v[78:81]
	v_mfma_f32_16x16x32_bf16 v[78:81], v[158:161], v[218:221], v[78:81]
	v_mfma_f32_16x16x32_bf16 v[70:73], v[162:165], v[214:217], v[70:73]
	v_mfma_f32_16x16x32_bf16 v[70:73], v[166:169], v[218:221], v[70:73]
	v_mfma_f32_16x16x32_bf16 v[86:89], v[162:165], v[206:209], v[86:89]
	v_mfma_f32_16x16x32_bf16 v[86:89], v[166:169], v[210:213], v[86:89]
	v_mfma_f32_16x16x32_bf16 v[102:105], v[162:165], v[198:201], v[102:105]
	v_mfma_f32_16x16x32_bf16 v[102:105], v[166:169], v[202:205], v[102:105]
	v_mfma_f32_16x16x32_bf16 v[118:121], v[162:165], v[190:193], v[118:121]
	v_mfma_f32_16x16x32_bf16 v[118:121], v[166:169], v[194:197], v[118:121]
	v_mfma_f32_16x16x32_bf16 v[122:125], v[170:173], v[190:193], v[122:125]
	v_mfma_f32_16x16x32_bf16 v[122:125], v[174:177], v[194:197], v[122:125]
	v_mfma_f32_16x16x32_bf16 v[106:109], v[170:173], v[198:201], v[106:109]
	v_mfma_f32_16x16x32_bf16 v[106:109], v[174:177], v[202:205], v[106:109]
	v_mfma_f32_16x16x32_bf16 v[90:93], v[170:173], v[206:209], v[90:93]
	v_mfma_f32_16x16x32_bf16 v[90:93], v[174:177], v[210:213], v[90:93]
	v_mfma_f32_16x16x32_bf16 v[74:77], v[170:173], v[214:217], v[74:77]
	v_mfma_f32_16x16x32_bf16 v[74:77], v[174:177], v[218:221], v[74:77]
	v_mfma_f32_16x16x32_bf16 v[66:69], v[182:185], v[214:217], v[66:69]
	v_mfma_f32_16x16x32_bf16 v[66:69], v[186:189], v[218:221], v[66:69]
	v_mfma_f32_16x16x32_bf16 v[82:85], v[182:185], v[206:209], v[82:85]
	v_mfma_f32_16x16x32_bf16 v[82:85], v[186:189], v[210:213], v[82:85]
	v_mfma_f32_16x16x32_bf16 v[98:101], v[182:185], v[198:201], v[98:101]
	v_mfma_f32_16x16x32_bf16 v[98:101], v[186:189], v[202:205], v[98:101]
	v_mfma_f32_16x16x32_bf16 v[114:117], v[182:185], v[190:193], v[114:117]
	v_mfma_f32_16x16x32_bf16 v[114:117], v[186:189], v[194:197], v[114:117]
	s_barrier
	s_setprio 0
	s_add_i32 s22, s66, s28
	v_lshl_add_u64 v[146:147], v[146:147], 0, s[4:5]
	s_mov_b32 m0, s22
	ds_read_b128 v[190:193], v153 offset:49152
	ds_read_b128 v[194:197], v153 offset:50176
	ds_read_b128 v[198:201], v153 offset:51200
	ds_read_b128 v[202:205], v153 offset:52224
	ds_read_b128 v[206:209], v153 offset:53248
	ds_read_b128 v[210:213], v153 offset:54272
	ds_read_b128 v[214:217], v153 offset:55296
	ds_read_b128 v[218:221], v153 offset:56320
	global_load_lds_dwordx4 v[146:147], off
	s_add_i32 m0, s22, 0x2000
	s_add_u32 s20, s20, 0x80080
	v_lshl_add_u64 v[146:147], v[222:223], 0, s[4:5]
	s_addc_u32 s21, s21, 0
	s_add_i32 s22, s67, s28
	global_load_lds_dwordx4 v[146:147], off
	v_lshl_add_u64 v[146:147], s[20:21], 0, v[134:135]
	s_mov_b32 m0, s22
	s_nop 0
	global_load_lds_dwordx4 v[146:147], off
	v_lshl_add_u64 v[146:147], s[20:21], 0, v[130:131]
	s_add_i32 m0, s22, 0x2000
	s_nop 0
	global_load_lds_dwordx4 v[146:147], off
	v_lshl_add_u64 v[146:147], v[224:225], 0, s[4:5]
	s_mov_b32 m0, s52
	s_nop 0
	global_load_lds_dwordx4 v[146:147], off
	v_lshl_add_u64 v[146:147], v[226:227], 0, s[4:5]
	s_mov_b32 m0, s53
	s_nop 0
	global_load_lds_dwordx4 v[146:147], off
	s_waitcnt vmcnt(8)
	s_waitcnt lgkmcnt(0)
	s_setprio 1
	s_barrier
	v_mfma_f32_16x16x32_bf16 v[62:65], v[154:157], v[190:193], v[62:65]
	v_mfma_f32_16x16x32_bf16 v[62:65], v[158:161], v[194:197], v[62:65]
	v_mfma_f32_16x16x32_bf16 v[46:49], v[154:157], v[198:201], v[46:49]
	v_mfma_f32_16x16x32_bf16 v[46:49], v[158:161], v[202:205], v[46:49]
	v_mfma_f32_16x16x32_bf16 v[30:33], v[154:157], v[206:209], v[30:33]
	v_mfma_f32_16x16x32_bf16 v[30:33], v[158:161], v[210:213], v[30:33]
	v_mfma_f32_16x16x32_bf16 v[14:17], v[154:157], v[214:217], v[14:17]
	v_mfma_f32_16x16x32_bf16 v[14:17], v[158:161], v[218:221], v[14:17]
	v_mfma_f32_16x16x32_bf16 v[6:9], v[162:165], v[214:217], v[6:9]
	v_mfma_f32_16x16x32_bf16 v[6:9], v[166:169], v[218:221], v[6:9]
	v_mfma_f32_16x16x32_bf16 v[22:25], v[162:165], v[206:209], v[22:25]
	v_mfma_f32_16x16x32_bf16 v[22:25], v[166:169], v[210:213], v[22:25]
	v_mfma_f32_16x16x32_bf16 v[38:41], v[162:165], v[198:201], v[38:41]
	v_mfma_f32_16x16x32_bf16 v[38:41], v[166:169], v[202:205], v[38:41]
	v_mfma_f32_16x16x32_bf16 v[54:57], v[162:165], v[190:193], v[54:57]
	v_mfma_f32_16x16x32_bf16 v[54:57], v[166:169], v[194:197], v[54:57]
	v_mfma_f32_16x16x32_bf16 v[58:61], v[170:173], v[190:193], v[58:61]
	v_mfma_f32_16x16x32_bf16 v[58:61], v[174:177], v[194:197], v[58:61]
	v_mfma_f32_16x16x32_bf16 v[42:45], v[170:173], v[198:201], v[42:45]
	v_mfma_f32_16x16x32_bf16 v[42:45], v[174:177], v[202:205], v[42:45]
	v_mfma_f32_16x16x32_bf16 v[26:29], v[170:173], v[206:209], v[26:29]
	v_mfma_f32_16x16x32_bf16 v[26:29], v[174:177], v[210:213], v[26:29]
	v_mfma_f32_16x16x32_bf16 v[10:13], v[170:173], v[214:217], v[10:13]
	v_mfma_f32_16x16x32_bf16 v[10:13], v[174:177], v[218:221], v[10:13]
	v_mfma_f32_16x16x32_bf16 v[2:5], v[182:185], v[214:217], v[2:5]
	v_mfma_f32_16x16x32_bf16 v[2:5], v[186:189], v[218:221], v[2:5]
	v_mfma_f32_16x16x32_bf16 v[18:21], v[182:185], v[206:209], v[18:21]
	v_mfma_f32_16x16x32_bf16 v[18:21], v[186:189], v[210:213], v[18:21]
	v_mfma_f32_16x16x32_bf16 v[34:37], v[182:185], v[198:201], v[34:37]
	v_mfma_f32_16x16x32_bf16 v[34:37], v[186:189], v[202:205], v[34:37]
	v_mfma_f32_16x16x32_bf16 v[50:53], v[182:185], v[190:193], v[50:53]
	v_mfma_f32_16x16x32_bf16 v[50:53], v[186:189], v[194:197], v[50:53]
	s_barrier
	s_setprio 0
	s_add_i32 s63, s63, 2
	s_add_u32 s18, s18, 0x100
	s_addc_u32 s19, s19, 0
	s_add_u32 s60, s60, 0x100
	s_addc_u32 s62, s62, 0
	s_cmp_gt_u32 s63, 29
	s_cbranch_scc0 .LBB0_736
	s_and_b64 vcc, exec, s[6:7]
	s_cbranch_vccz .LBB0_739
	s_barrier

.LBB0_854:
	ds_read_b128 v[144:147], v151
	ds_read_b128 v[154:157], v151 offset:1024
	ds_read_b128 v[158:161], v151 offset:2048
	ds_read_b128 v[162:165], v151 offset:3072
	ds_read_b128 v[166:169], v152
	ds_read_b128 v[170:173], v152 offset:1024
	ds_read_b128 v[174:177], v152 offset:2048
	ds_read_b128 v[182:185], v152 offset:3072
	s_add_i32 s63, s14, 2
	s_add_u32 s15, s12, 0xffea0080
	s_addc_u32 s16, s13, -1
	s_cmp_eq_u32 s59, s14
	s_cselect_b32 s14, s10, s60
	s_cselect_b32 s17, s9, s16
	s_cselect_b32 s16, s8, s15
	s_cselect_b32 s15, s11, s62
	v_lshl_add_u64 v[218:219], s[12:13], 0, v[138:139]
	s_add_i32 m0, s23, 0xc000
	ds_read_b128 v[186:189], v153
	ds_read_b128 v[190:193], v153 offset:1024
	ds_read_b128 v[194:197], v153 offset:2048
	ds_read_b128 v[198:201], v153 offset:3072
	ds_read_b128 v[202:205], v153 offset:4096
	ds_read_b128 v[206:209], v153 offset:5120
	ds_read_b128 v[210:213], v153 offset:6144
	ds_read_b128 v[214:217], v153 offset:7168
	global_load_lds_dwordx4 v[218:219], off
	v_lshl_add_u64 v[218:219], s[12:13], 0, v[140:141]
	s_add_i32 m0, s23, 0xe000
	s_nop 0
	global_load_lds_dwordx4 v[218:219], off
	s_waitcnt vmcnt(8)
	s_waitcnt lgkmcnt(0)
	s_setprio 1
	s_barrier
	v_mfma_f32_16x16x32_bf16 v[126:129], v[144:147], v[186:189], v[126:129]
	v_mfma_f32_16x16x32_bf16 v[126:129], v[154:157], v[190:193], v[126:129]
	v_mfma_f32_16x16x32_bf16 v[118:121], v[144:147], v[194:197], v[118:121]
	v_mfma_f32_16x16x32_bf16 v[118:121], v[154:157], v[198:201], v[118:121]
	v_mfma_f32_16x16x32_bf16 v[106:109], v[144:147], v[202:205], v[106:109]
	v_mfma_f32_16x16x32_bf16 v[106:109], v[154:157], v[206:209], v[106:109]
	v_mfma_f32_16x16x32_bf16 v[90:93], v[144:147], v[210:213], v[90:93]
	v_mfma_f32_16x16x32_bf16 v[90:93], v[154:157], v[214:217], v[90:93]
	v_mfma_f32_16x16x32_bf16 v[82:85], v[158:161], v[210:213], v[82:85]
	v_mfma_f32_16x16x32_bf16 v[82:85], v[162:165], v[214:217], v[82:85]
	v_mfma_f32_16x16x32_bf16 v[98:101], v[158:161], v[202:205], v[98:101]
	v_mfma_f32_16x16x32_bf16 v[98:101], v[162:165], v[206:209], v[98:101]
	v_mfma_f32_16x16x32_bf16 v[114:117], v[158:161], v[194:197], v[114:117]
	v_mfma_f32_16x16x32_bf16 v[114:117], v[162:165], v[198:201], v[114:117]
	v_mfma_f32_16x16x32_bf16 v[122:125], v[158:161], v[186:189], v[122:125]
	v_mfma_f32_16x16x32_bf16 v[122:125], v[162:165], v[190:193], v[122:125]
	v_mfma_f32_16x16x32_bf16 v[110:113], v[166:169], v[186:189], v[110:113]
	v_mfma_f32_16x16x32_bf16 v[110:113], v[170:173], v[190:193], v[110:113]
	v_mfma_f32_16x16x32_bf16 v[94:97], v[166:169], v[194:197], v[94:97]
	v_mfma_f32_16x16x32_bf16 v[94:97], v[170:173], v[198:201], v[94:97]
	v_mfma_f32_16x16x32_bf16 v[78:81], v[166:169], v[202:205], v[78:81]
	v_mfma_f32_16x16x32_bf16 v[78:81], v[170:173], v[206:209], v[78:81]
	v_mfma_f32_16x16x32_bf16 v[70:73], v[166:169], v[210:213], v[70:73]
	v_mfma_f32_16x16x32_bf16 v[70:73], v[170:173], v[214:217], v[70:73]
	v_mfma_f32_16x16x32_bf16 v[66:69], v[174:177], v[210:213], v[66:69]
	v_mfma_f32_16x16x32_bf16 v[66:69], v[182:185], v[214:217], v[66:69]
	v_mfma_f32_16x16x32_bf16 v[74:77], v[174:177], v[202:205], v[74:77]
	v_mfma_f32_16x16x32_bf16 v[74:77], v[182:185], v[206:209], v[74:77]
	v_mfma_f32_16x16x32_bf16 v[86:89], v[174:177], v[194:197], v[86:89]
	v_mfma_f32_16x16x32_bf16 v[86:89], v[182:185], v[198:201], v[86:89]
	v_mfma_f32_16x16x32_bf16 v[102:105], v[174:177], v[186:189], v[102:105]
	v_mfma_f32_16x16x32_bf16 v[102:105], v[182:185], v[190:193], v[102:105]
	s_barrier
	s_setprio 0
	s_add_i32 s66, s36, s20
	v_lshl_add_u64 v[218:219], s[14:15], 0, v[132:133]
	s_mov_b32 m0, s66
	ds_read_b128 v[186:189], v153 offset:16384
	ds_read_b128 v[190:193], v153 offset:17408
	ds_read_b128 v[194:197], v153 offset:18432
	ds_read_b128 v[198:201], v153 offset:19456
	ds_read_b128 v[202:205], v153 offset:20480
	ds_read_b128 v[206:209], v153 offset:21504
	ds_read_b128 v[210:213], v153 offset:22528
	ds_read_b128 v[214:217], v153 offset:23552
	global_load_lds_dwordx4 v[218:219], off
	s_add_i32 m0, s66, 0x2000
	s_add_u32 s66, s14, 0x160000
	v_lshl_add_u64 v[220:221], s[14:15], 0, v[136:137]
	s_addc_u32 s67, s15, 0
	s_add_i32 s68, s37, s20
	global_load_lds_dwordx4 v[220:221], off
	v_lshl_add_u64 v[222:223], s[66:67], 0, v[132:133]
	s_mov_b32 m0, s68
	v_lshl_add_u64 v[224:225], s[16:17], 0, v[134:135]
	global_load_lds_dwordx4 v[222:223], off
	v_lshl_add_u64 v[222:223], s[66:67], 0, v[136:137]
	s_add_i32 m0, s68, 0x2000
	s_nop 0
	global_load_lds_dwordx4 v[222:223], off
	v_lshl_add_u64 v[222:223], s[16:17], 0, v[130:131]
	s_mov_b32 m0, s23
	s_nop 0
	global_load_lds_dwordx4 v[222:223], off
	s_mov_b32 m0, s26
	s_nop 0
	global_load_lds_dwordx4 v[224:225], off
	s_waitcnt vmcnt(8)
	s_waitcnt lgkmcnt(0)
	s_setprio 1
	s_barrier
	v_mfma_f32_16x16x32_bf16 v[62:65], v[144:147], v[186:189], v[62:65]
	v_mfma_f32_16x16x32_bf16 v[62:65], v[154:157], v[190:193], v[62:65]
	v_mfma_f32_16x16x32_bf16 v[54:57], v[144:147], v[194:197], v[54:57]
	v_mfma_f32_16x16x32_bf16 v[54:57], v[154:157], v[198:201], v[54:57]
	v_mfma_f32_16x16x32_bf16 v[38:41], v[144:147], v[202:205], v[38:41]
	v_mfma_f32_16x16x32_bf16 v[38:41], v[154:157], v[206:209], v[38:41]
	v_mfma_f32_16x16x32_bf16 v[22:25], v[144:147], v[210:213], v[22:25]
	v_mfma_f32_16x16x32_bf16 v[22:25], v[154:157], v[214:217], v[22:25]
	v_mfma_f32_16x16x32_bf16 v[18:21], v[158:161], v[210:213], v[18:21]
	v_mfma_f32_16x16x32_bf16 v[18:21], v[162:165], v[214:217], v[18:21]
	v_mfma_f32_16x16x32_bf16 v[34:37], v[158:161], v[202:205], v[34:37]
	v_mfma_f32_16x16x32_bf16 v[34:37], v[162:165], v[206:209], v[34:37]
	v_mfma_f32_16x16x32_bf16 v[50:53], v[158:161], v[194:197], v[50:53]
	v_mfma_f32_16x16x32_bf16 v[50:53], v[162:165], v[198:201], v[50:53]
	v_mfma_f32_16x16x32_bf16 v[58:61], v[158:161], v[186:189], v[58:61]
	v_mfma_f32_16x16x32_bf16 v[58:61], v[162:165], v[190:193], v[58:61]
	v_mfma_f32_16x16x32_bf16 v[46:49], v[166:169], v[186:189], v[46:49]
	v_mfma_f32_16x16x32_bf16 v[46:49], v[170:173], v[190:193], v[46:49]
	v_mfma_f32_16x16x32_bf16 v[30:33], v[166:169], v[194:197], v[30:33]
	v_mfma_f32_16x16x32_bf16 v[30:33], v[170:173], v[198:201], v[30:33]
	v_mfma_f32_16x16x32_bf16 v[14:17], v[166:169], v[202:205], v[14:17]
	v_mfma_f32_16x16x32_bf16 v[14:17], v[170:173], v[206:209], v[14:17]
	v_mfma_f32_16x16x32_bf16 v[6:9], v[166:169], v[210:213], v[6:9]
	v_mfma_f32_16x16x32_bf16 v[6:9], v[170:173], v[214:217], v[6:9]
	v_mfma_f32_16x16x32_bf16 v[2:5], v[174:177], v[210:213], v[2:5]
	v_mfma_f32_16x16x32_bf16 v[2:5], v[182:185], v[214:217], v[2:5]
	v_mfma_f32_16x16x32_bf16 v[10:13], v[174:177], v[202:205], v[10:13]
	v_mfma_f32_16x16x32_bf16 v[10:13], v[182:185], v[206:209], v[10:13]
	v_mfma_f32_16x16x32_bf16 v[26:29], v[174:177], v[194:197], v[26:29]
	v_mfma_f32_16x16x32_bf16 v[26:29], v[182:185], v[198:201], v[26:29]
	v_mfma_f32_16x16x32_bf16 v[42:45], v[174:177], v[186:189], v[42:45]
	v_mfma_f32_16x16x32_bf16 v[42:45], v[182:185], v[190:193], v[42:45]
	s_barrier
	s_setprio 0
	s_add_i32 s66, 0, 0x18000
	s_add_i32 s67, 0, 0x1c000
	v_add_u32_e32 v162, s66, v149
	v_add_u32_e32 v179, s67, v149
	ds_read_b128 v[144:147], v162
	ds_read_b128 v[154:157], v162 offset:1024
	ds_read_b128 v[158:161], v162 offset:2048
	ds_read_b128 v[162:165], v162 offset:3072
	ds_read_b128 v[166:169], v179
	ds_read_b128 v[170:173], v179 offset:1024
	ds_read_b128 v[174:177], v179 offset:2048
	ds_read_b128 v[182:185], v179 offset:3072
	s_add_u32 s16, s16, 0x160000
	s_addc_u32 s17, s17, 0
	s_mov_b32 m0, s27
	v_lshl_add_u64 v[226:227], s[16:17], 0, v[130:131]
	ds_read_b128 v[186:189], v153 offset:32768
	ds_read_b128 v[190:193], v153 offset:33792
	ds_read_b128 v[194:197], v153 offset:34816
	ds_read_b128 v[198:201], v153 offset:35840
	ds_read_b128 v[202:205], v153 offset:36864
	ds_read_b128 v[206:209], v153 offset:37888
	ds_read_b128 v[210:213], v153 offset:38912
	ds_read_b128 v[214:217], v153 offset:39936
	global_load_lds_dwordx4 v[226:227], off
	v_lshl_add_u64 v[226:227], s[16:17], 0, v[134:135]
	s_mov_b32 m0, s28
	s_nop 0
	global_load_lds_dwordx4 v[226:227], off
	s_waitcnt vmcnt(8)
	s_waitcnt lgkmcnt(0)
	s_setprio 1
	s_barrier
	v_mfma_f32_16x16x32_bf16 v[126:129], v[144:147], v[186:189], v[126:129]
	v_mfma_f32_16x16x32_bf16 v[126:129], v[154:157], v[190:193], v[126:129]
	v_mfma_f32_16x16x32_bf16 v[118:121], v[144:147], v[194:197], v[118:121]
	v_mfma_f32_16x16x32_bf16 v[118:121], v[154:157], v[198:201], v[118:121]
	v_mfma_f32_16x16x32_bf16 v[106:109], v[144:147], v[202:205], v[106:109]
	v_mfma_f32_16x16x32_bf16 v[106:109], v[154:157], v[206:209], v[106:109]
	v_mfma_f32_16x16x32_bf16 v[90:93], v[144:147], v[210:213], v[90:93]
	v_mfma_f32_16x16x32_bf16 v[90:93], v[154:157], v[214:217], v[90:93]
	v_mfma_f32_16x16x32_bf16 v[82:85], v[158:161], v[210:213], v[82:85]
	v_mfma_f32_16x16x32_bf16 v[82:85], v[162:165], v[214:217], v[82:85]
	v_mfma_f32_16x16x32_bf16 v[98:101], v[158:161], v[202:205], v[98:101]
	v_mfma_f32_16x16x32_bf16 v[98:101], v[162:165], v[206:209], v[98:101]
	v_mfma_f32_16x16x32_bf16 v[114:117], v[158:161], v[194:197], v[114:117]
	v_mfma_f32_16x16x32_bf16 v[114:117], v[162:165], v[198:201], v[114:117]
	v_mfma_f32_16x16x32_bf16 v[122:125], v[158:161], v[186:189], v[122:125]
	v_mfma_f32_16x16x32_bf16 v[122:125], v[162:165], v[190:193], v[122:125]
	v_mfma_f32_16x16x32_bf16 v[110:113], v[166:169], v[186:189], v[110:113]
	v_mfma_f32_16x16x32_bf16 v[110:113], v[170:173], v[190:193], v[110:113]
	v_mfma_f32_16x16x32_bf16 v[94:97], v[166:169], v[194:197], v[94:97]
	v_mfma_f32_16x16x32_bf16 v[94:97], v[170:173], v[198:201], v[94:97]
	v_mfma_f32_16x16x32_bf16 v[78:81], v[166:169], v[202:205], v[78:81]
	v_mfma_f32_16x16x32_bf16 v[78:81], v[170:173], v[206:209], v[78:81]
	v_mfma_f32_16x16x32_bf16 v[70:73], v[166:169], v[210:213], v[70:73]
	v_mfma_f32_16x16x32_bf16 v[70:73], v[170:173], v[214:217], v[70:73]
	v_mfma_f32_16x16x32_bf16 v[66:69], v[174:177], v[210:213], v[66:69]
	v_mfma_f32_16x16x32_bf16 v[66:69], v[182:185], v[214:217], v[66:69]
	v_mfma_f32_16x16x32_bf16 v[74:77], v[174:177], v[202:205], v[74:77]
	v_mfma_f32_16x16x32_bf16 v[74:77], v[182:185], v[206:209], v[74:77]
	v_mfma_f32_16x16x32_bf16 v[86:89], v[174:177], v[194:197], v[86:89]
	v_mfma_f32_16x16x32_bf16 v[86:89], v[182:185], v[198:201], v[86:89]
	v_mfma_f32_16x16x32_bf16 v[102:105], v[174:177], v[186:189], v[102:105]
	v_mfma_f32_16x16x32_bf16 v[102:105], v[182:185], v[190:193], v[102:105]
	s_barrier
	s_setprio 0
	s_add_i32 s16, s66, s20
	v_lshl_add_u64 v[218:219], v[218:219], 0, s[4:5]
	s_mov_b32 m0, s16
	ds_read_b128 v[186:189], v153 offset:49152
	ds_read_b128 v[190:193], v153 offset:50176
	ds_read_b128 v[194:197], v153 offset:51200
	ds_read_b128 v[198:201], v153 offset:52224
	ds_read_b128 v[202:205], v153 offset:53248
	ds_read_b128 v[206:209], v153 offset:54272
	ds_read_b128 v[210:213], v153 offset:55296
	ds_read_b128 v[214:217], v153 offset:56320
	global_load_lds_dwordx4 v[218:219], off
	s_add_i32 m0, s16, 0x2000
	s_add_u32 s14, s14, 0x160080
	v_lshl_add_u64 v[218:219], v[220:221], 0, s[4:5]
	s_addc_u32 s15, s15, 0
	s_add_i32 s16, s67, s20
	global_load_lds_dwordx4 v[218:219], off
	v_lshl_add_u64 v[218:219], s[14:15], 0, v[132:133]
	s_mov_b32 m0, s16
	s_nop 0
	global_load_lds_dwordx4 v[218:219], off
	v_lshl_add_u64 v[218:219], s[14:15], 0, v[136:137]
	s_add_i32 m0, s16, 0x2000
	s_nop 0
	global_load_lds_dwordx4 v[218:219], off
	v_lshl_add_u64 v[218:219], v[222:223], 0, s[4:5]
	s_mov_b32 m0, s30
	s_nop 0
	global_load_lds_dwordx4 v[218:219], off
	v_lshl_add_u64 v[218:219], v[224:225], 0, s[4:5]
	s_mov_b32 m0, s31
	s_nop 0
	global_load_lds_dwordx4 v[218:219], off
	s_waitcnt vmcnt(8)
	s_waitcnt lgkmcnt(0)
	s_setprio 1
	s_barrier
	v_mfma_f32_16x16x32_bf16 v[62:65], v[144:147], v[186:189], v[62:65]
	v_mfma_f32_16x16x32_bf16 v[62:65], v[154:157], v[190:193], v[62:65]
	v_mfma_f32_16x16x32_bf16 v[54:57], v[144:147], v[194:197], v[54:57]
	v_mfma_f32_16x16x32_bf16 v[54:57], v[154:157], v[198:201], v[54:57]
	v_mfma_f32_16x16x32_bf16 v[38:41], v[144:147], v[202:205], v[38:41]
	v_mfma_f32_16x16x32_bf16 v[38:41], v[154:157], v[206:209], v[38:41]
	v_mfma_f32_16x16x32_bf16 v[22:25], v[144:147], v[210:213], v[22:25]
	v_mfma_f32_16x16x32_bf16 v[22:25], v[154:157], v[214:217], v[22:25]
	v_mfma_f32_16x16x32_bf16 v[18:21], v[158:161], v[210:213], v[18:21]
	v_mfma_f32_16x16x32_bf16 v[18:21], v[162:165], v[214:217], v[18:21]
	v_mfma_f32_16x16x32_bf16 v[34:37], v[158:161], v[202:205], v[34:37]
	v_mfma_f32_16x16x32_bf16 v[34:37], v[162:165], v[206:209], v[34:37]
	v_mfma_f32_16x16x32_bf16 v[50:53], v[158:161], v[194:197], v[50:53]
	v_mfma_f32_16x16x32_bf16 v[50:53], v[162:165], v[198:201], v[50:53]
	v_mfma_f32_16x16x32_bf16 v[58:61], v[158:161], v[186:189], v[58:61]
	v_mfma_f32_16x16x32_bf16 v[58:61], v[162:165], v[190:193], v[58:61]
	v_mfma_f32_16x16x32_bf16 v[46:49], v[166:169], v[186:189], v[46:49]
	v_mfma_f32_16x16x32_bf16 v[46:49], v[170:173], v[190:193], v[46:49]
	v_mfma_f32_16x16x32_bf16 v[30:33], v[166:169], v[194:197], v[30:33]
	v_mfma_f32_16x16x32_bf16 v[30:33], v[170:173], v[198:201], v[30:33]
	v_mfma_f32_16x16x32_bf16 v[14:17], v[166:169], v[202:205], v[14:17]
	v_mfma_f32_16x16x32_bf16 v[14:17], v[170:173], v[206:209], v[14:17]
	v_mfma_f32_16x16x32_bf16 v[6:9], v[166:169], v[210:213], v[6:9]
	v_mfma_f32_16x16x32_bf16 v[6:9], v[170:173], v[214:217], v[6:9]
	v_mfma_f32_16x16x32_bf16 v[2:5], v[174:177], v[210:213], v[2:5]
	v_mfma_f32_16x16x32_bf16 v[2:5], v[182:185], v[214:217], v[2:5]
	v_mfma_f32_16x16x32_bf16 v[10:13], v[174:177], v[202:205], v[10:13]
	v_mfma_f32_16x16x32_bf16 v[10:13], v[182:185], v[206:209], v[10:13]
	v_mfma_f32_16x16x32_bf16 v[26:29], v[174:177], v[194:197], v[26:29]
	v_mfma_f32_16x16x32_bf16 v[26:29], v[182:185], v[198:201], v[26:29]
	v_mfma_f32_16x16x32_bf16 v[42:45], v[174:177], v[186:189], v[42:45]
	v_mfma_f32_16x16x32_bf16 v[42:45], v[182:185], v[190:193], v[42:45]
	s_barrier
	s_setprio 0
	s_add_u32 s12, s12, 0x100
	s_addc_u32 s13, s13, 0
	s_add_u32 s60, s60, 0x100
	s_addc_u32 s62, s62, 0
	s_cmp_ge_i32 s63, s58
	s_mov_b32 s14, s63
	s_cbranch_scc0 .LBB0_854
	s_and_b64 vcc, exec, s[6:7]
	s_cbranch_vccz .LBB0_857
	s_barrier

.LBB0_1037:
	ds_read_b128 v[150:153], v170
	ds_read_b128 v[154:157], v170 offset:1024
	ds_read_b128 v[158:161], v170 offset:2048
	ds_read_b128 v[182:185], v170 offset:3072
	ds_read_b128 v[186:189], v171
	ds_read_b128 v[190:193], v171 offset:1024
	ds_read_b128 v[194:197], v171 offset:2048
	ds_read_b128 v[198:201], v171 offset:3072
	s_add_u32 s34, s4, 0xfff80080
	s_addc_u32 s35, s5, -1
	s_cmp_eq_u32 s69, 28
	s_cselect_b32 s37, s9, s35
	s_cselect_b32 s36, s14, s34
	s_cselect_b32 s35, s23, s68
	s_cselect_b32 s34, s27, s67
	v_lshl_add_u64 v[176:177], s[4:5], 0, v[142:143]
	s_add_i32 m0, s13, 0xc000
	ds_read_b128 v[202:205], v172
	ds_read_b128 v[206:209], v172 offset:1024
	ds_read_b128 v[210:213], v172 offset:2048
	ds_read_b128 v[214:217], v172 offset:3072
	ds_read_b128 v[218:221], v172 offset:4096
	ds_read_b128 v[222:225], v172 offset:5120
	ds_read_b128 v[226:229], v172 offset:6144
	ds_read_b128 v[230:233], v172 offset:7168
	global_load_lds_dwordx4 v[176:177], off
	v_lshl_add_u64 v[176:177], s[4:5], 0, v[144:145]
	s_add_i32 m0, s13, 0xe000
	s_nop 0
	global_load_lds_dwordx4 v[176:177], off
	s_waitcnt vmcnt(8)
	s_waitcnt lgkmcnt(0)
	s_setprio 1
	s_barrier
	v_mfma_f32_16x16x32_bf16 v[126:129], v[150:153], v[202:205], v[126:129]
	v_mfma_f32_16x16x32_bf16 v[126:129], v[154:157], v[206:209], v[126:129]
	v_mfma_f32_16x16x32_bf16 v[110:113], v[150:153], v[210:213], v[110:113]
	v_mfma_f32_16x16x32_bf16 v[110:113], v[154:157], v[214:217], v[110:113]
	v_mfma_f32_16x16x32_bf16 v[94:97], v[150:153], v[218:221], v[94:97]
	v_mfma_f32_16x16x32_bf16 v[94:97], v[154:157], v[222:225], v[94:97]
	v_mfma_f32_16x16x32_bf16 v[78:81], v[150:153], v[226:229], v[78:81]
	v_mfma_f32_16x16x32_bf16 v[78:81], v[154:157], v[230:233], v[78:81]
	v_mfma_f32_16x16x32_bf16 v[74:77], v[158:161], v[226:229], v[74:77]
	v_mfma_f32_16x16x32_bf16 v[74:77], v[182:185], v[230:233], v[74:77]
	v_mfma_f32_16x16x32_bf16 v[90:93], v[158:161], v[218:221], v[90:93]
	v_mfma_f32_16x16x32_bf16 v[90:93], v[182:185], v[222:225], v[90:93]
	v_mfma_f32_16x16x32_bf16 v[106:109], v[158:161], v[210:213], v[106:109]
	v_mfma_f32_16x16x32_bf16 v[106:109], v[182:185], v[214:217], v[106:109]
	v_mfma_f32_16x16x32_bf16 v[122:125], v[158:161], v[202:205], v[122:125]
	v_mfma_f32_16x16x32_bf16 v[122:125], v[182:185], v[206:209], v[122:125]
	v_mfma_f32_16x16x32_bf16 v[118:121], v[186:189], v[202:205], v[118:121]
	v_mfma_f32_16x16x32_bf16 v[118:121], v[190:193], v[206:209], v[118:121]
	v_mfma_f32_16x16x32_bf16 v[102:105], v[186:189], v[210:213], v[102:105]
	v_mfma_f32_16x16x32_bf16 v[102:105], v[190:193], v[214:217], v[102:105]
	v_mfma_f32_16x16x32_bf16 v[86:89], v[186:189], v[218:221], v[86:89]
	v_mfma_f32_16x16x32_bf16 v[86:89], v[190:193], v[222:225], v[86:89]
	v_mfma_f32_16x16x32_bf16 v[70:73], v[186:189], v[226:229], v[70:73]
	v_mfma_f32_16x16x32_bf16 v[70:73], v[190:193], v[230:233], v[70:73]
	v_mfma_f32_16x16x32_bf16 v[66:69], v[194:197], v[226:229], v[66:69]
	v_mfma_f32_16x16x32_bf16 v[66:69], v[198:201], v[230:233], v[66:69]
	v_mfma_f32_16x16x32_bf16 v[82:85], v[194:197], v[218:221], v[82:85]
	v_mfma_f32_16x16x32_bf16 v[82:85], v[198:201], v[222:225], v[82:85]
	v_mfma_f32_16x16x32_bf16 v[98:101], v[194:197], v[210:213], v[98:101]
	v_mfma_f32_16x16x32_bf16 v[98:101], v[198:201], v[214:217], v[98:101]
	v_mfma_f32_16x16x32_bf16 v[114:117], v[194:197], v[202:205], v[114:117]
	v_mfma_f32_16x16x32_bf16 v[114:117], v[198:201], v[206:209], v[114:117]
	s_barrier
	s_setprio 0
	s_add_i32 s70, s62, s52
	v_lshl_add_u64 v[176:177], s[34:35], 0, v[132:133]
	s_mov_b32 m0, s70
	ds_read_b128 v[202:205], v172 offset:16384
	ds_read_b128 v[206:209], v172 offset:17408
	ds_read_b128 v[210:213], v172 offset:18432
	ds_read_b128 v[214:217], v172 offset:19456
	ds_read_b128 v[218:221], v172 offset:20480
	ds_read_b128 v[222:225], v172 offset:21504
	ds_read_b128 v[226:229], v172 offset:22528
	ds_read_b128 v[230:233], v172 offset:23552
	global_load_lds_dwordx4 v[176:177], off
	s_add_i32 m0, s70, 0x2000
	s_add_u32 s70, s34, 0x80000
	v_lshl_add_u64 v[234:235], s[34:35], 0, v[136:137]
	s_addc_u32 s71, s35, 0
	s_add_i32 s72, s63, s52
	global_load_lds_dwordx4 v[234:235], off
	v_lshl_add_u64 v[236:237], s[70:71], 0, v[132:133]
	s_mov_b32 m0, s72
	v_lshl_add_u64 v[238:239], s[36:37], 0, v[134:135]
	global_load_lds_dwordx4 v[236:237], off
	v_lshl_add_u64 v[236:237], s[70:71], 0, v[136:137]
	s_add_i32 m0, s72, 0x2000
	s_nop 0
	global_load_lds_dwordx4 v[236:237], off
	v_lshl_add_u64 v[236:237], s[36:37], 0, v[130:131]
	s_mov_b32 m0, s13
	s_nop 0
	global_load_lds_dwordx4 v[236:237], off
	s_mov_b32 m0, s53
	s_nop 0
	global_load_lds_dwordx4 v[238:239], off
	s_waitcnt vmcnt(8)
	s_waitcnt lgkmcnt(0)
	s_setprio 1
	s_barrier
	v_mfma_f32_16x16x32_bf16 v[62:65], v[150:153], v[202:205], v[62:65]
	v_mfma_f32_16x16x32_bf16 v[62:65], v[154:157], v[206:209], v[62:65]
	v_mfma_f32_16x16x32_bf16 v[46:49], v[150:153], v[210:213], v[46:49]
	v_mfma_f32_16x16x32_bf16 v[46:49], v[154:157], v[214:217], v[46:49]
	v_mfma_f32_16x16x32_bf16 v[30:33], v[150:153], v[218:221], v[30:33]
	v_mfma_f32_16x16x32_bf16 v[30:33], v[154:157], v[222:225], v[30:33]
	v_mfma_f32_16x16x32_bf16 v[14:17], v[150:153], v[226:229], v[14:17]
	v_mfma_f32_16x16x32_bf16 v[14:17], v[154:157], v[230:233], v[14:17]
	v_mfma_f32_16x16x32_bf16 v[10:13], v[158:161], v[226:229], v[10:13]
	v_mfma_f32_16x16x32_bf16 v[10:13], v[182:185], v[230:233], v[10:13]
	v_mfma_f32_16x16x32_bf16 v[26:29], v[158:161], v[218:221], v[26:29]
	v_mfma_f32_16x16x32_bf16 v[26:29], v[182:185], v[222:225], v[26:29]
	v_mfma_f32_16x16x32_bf16 v[42:45], v[158:161], v[210:213], v[42:45]
	v_mfma_f32_16x16x32_bf16 v[42:45], v[182:185], v[214:217], v[42:45]
	v_mfma_f32_16x16x32_bf16 v[58:61], v[158:161], v[202:205], v[58:61]
	v_mfma_f32_16x16x32_bf16 v[58:61], v[182:185], v[206:209], v[58:61]
	v_mfma_f32_16x16x32_bf16 v[54:57], v[186:189], v[202:205], v[54:57]
	v_mfma_f32_16x16x32_bf16 v[54:57], v[190:193], v[206:209], v[54:57]
	v_mfma_f32_16x16x32_bf16 v[38:41], v[186:189], v[210:213], v[38:41]
	v_mfma_f32_16x16x32_bf16 v[38:41], v[190:193], v[214:217], v[38:41]
	v_mfma_f32_16x16x32_bf16 v[22:25], v[186:189], v[218:221], v[22:25]
	v_mfma_f32_16x16x32_bf16 v[22:25], v[190:193], v[222:225], v[22:25]
	v_mfma_f32_16x16x32_bf16 v[6:9], v[186:189], v[226:229], v[6:9]
	v_mfma_f32_16x16x32_bf16 v[6:9], v[190:193], v[230:233], v[6:9]
	v_mfma_f32_16x16x32_bf16 v[2:5], v[194:197], v[226:229], v[2:5]
	v_mfma_f32_16x16x32_bf16 v[2:5], v[198:201], v[230:233], v[2:5]
	v_mfma_f32_16x16x32_bf16 v[18:21], v[194:197], v[218:221], v[18:21]
	v_mfma_f32_16x16x32_bf16 v[18:21], v[198:201], v[222:225], v[18:21]
	v_mfma_f32_16x16x32_bf16 v[34:37], v[194:197], v[210:213], v[34:37]
	v_mfma_f32_16x16x32_bf16 v[34:37], v[198:201], v[214:217], v[34:37]
	v_mfma_f32_16x16x32_bf16 v[50:53], v[194:197], v[202:205], v[50:53]
	v_mfma_f32_16x16x32_bf16 v[50:53], v[198:201], v[206:209], v[50:53]
	s_barrier
	s_setprio 0
	s_add_i32 s70, 0, 0x18000
	v_add_u32_e32 v175, s70, v164
	s_add_i32 s71, 0, 0x1c000
	ds_read_b128 v[150:153], v175
	ds_read_b128 v[154:157], v175 offset:1024
	ds_read_b128 v[158:161], v175 offset:2048
	ds_read_b128 v[182:185], v175 offset:3072
	v_add_u32_e32 v175, s71, v164
	ds_read_b128 v[186:189], v175
	ds_read_b128 v[190:193], v175 offset:1024
	ds_read_b128 v[194:197], v175 offset:2048
	ds_read_b128 v[198:201], v175 offset:3072
	s_add_u32 s36, s36, 0x80000
	s_addc_u32 s37, s37, 0
	s_mov_b32 m0, s54
	v_lshl_add_u64 v[240:241], s[36:37], 0, v[130:131]
	ds_read_b128 v[202:205], v172 offset:32768
	ds_read_b128 v[206:209], v172 offset:33792
	ds_read_b128 v[210:213], v172 offset:34816
	ds_read_b128 v[214:217], v172 offset:35840
	ds_read_b128 v[218:221], v172 offset:36864
	ds_read_b128 v[222:225], v172 offset:37888
	ds_read_b128 v[226:229], v172 offset:38912
	ds_read_b128 v[230:233], v172 offset:39936
	global_load_lds_dwordx4 v[240:241], off
	v_lshl_add_u64 v[240:241], s[36:37], 0, v[134:135]
	s_mov_b32 m0, s55
	s_nop 0
	global_load_lds_dwordx4 v[240:241], off
	s_waitcnt vmcnt(8)
	s_waitcnt lgkmcnt(0)
	s_setprio 1
	s_barrier
	v_mfma_f32_16x16x32_bf16 v[126:129], v[150:153], v[202:205], v[126:129]
	v_mfma_f32_16x16x32_bf16 v[126:129], v[154:157], v[206:209], v[126:129]
	v_mfma_f32_16x16x32_bf16 v[110:113], v[150:153], v[210:213], v[110:113]
	v_mfma_f32_16x16x32_bf16 v[110:113], v[154:157], v[214:217], v[110:113]
	v_mfma_f32_16x16x32_bf16 v[94:97], v[150:153], v[218:221], v[94:97]
	v_mfma_f32_16x16x32_bf16 v[94:97], v[154:157], v[222:225], v[94:97]
	v_mfma_f32_16x16x32_bf16 v[78:81], v[150:153], v[226:229], v[78:81]
	v_mfma_f32_16x16x32_bf16 v[78:81], v[154:157], v[230:233], v[78:81]
	v_mfma_f32_16x16x32_bf16 v[74:77], v[158:161], v[226:229], v[74:77]
	v_mfma_f32_16x16x32_bf16 v[74:77], v[182:185], v[230:233], v[74:77]
	v_mfma_f32_16x16x32_bf16 v[90:93], v[158:161], v[218:221], v[90:93]
	v_mfma_f32_16x16x32_bf16 v[90:93], v[182:185], v[222:225], v[90:93]
	v_mfma_f32_16x16x32_bf16 v[106:109], v[158:161], v[210:213], v[106:109]
	v_mfma_f32_16x16x32_bf16 v[106:109], v[182:185], v[214:217], v[106:109]
	v_mfma_f32_16x16x32_bf16 v[122:125], v[158:161], v[202:205], v[122:125]
	v_mfma_f32_16x16x32_bf16 v[122:125], v[182:185], v[206:209], v[122:125]
	v_mfma_f32_16x16x32_bf16 v[118:121], v[186:189], v[202:205], v[118:121]
	v_mfma_f32_16x16x32_bf16 v[118:121], v[190:193], v[206:209], v[118:121]
	v_mfma_f32_16x16x32_bf16 v[102:105], v[186:189], v[210:213], v[102:105]
	v_mfma_f32_16x16x32_bf16 v[102:105], v[190:193], v[214:217], v[102:105]
	v_mfma_f32_16x16x32_bf16 v[86:89], v[186:189], v[218:221], v[86:89]
	v_mfma_f32_16x16x32_bf16 v[86:89], v[190:193], v[222:225], v[86:89]
	v_mfma_f32_16x16x32_bf16 v[70:73], v[186:189], v[226:229], v[70:73]
	v_mfma_f32_16x16x32_bf16 v[70:73], v[190:193], v[230:233], v[70:73]
	v_mfma_f32_16x16x32_bf16 v[66:69], v[194:197], v[226:229], v[66:69]
	v_mfma_f32_16x16x32_bf16 v[66:69], v[198:201], v[230:233], v[66:69]
	v_mfma_f32_16x16x32_bf16 v[82:85], v[194:197], v[218:221], v[82:85]
	v_mfma_f32_16x16x32_bf16 v[82:85], v[198:201], v[222:225], v[82:85]
	v_mfma_f32_16x16x32_bf16 v[98:101], v[194:197], v[210:213], v[98:101]
	v_mfma_f32_16x16x32_bf16 v[98:101], v[198:201], v[214:217], v[98:101]
	v_mfma_f32_16x16x32_bf16 v[114:117], v[194:197], v[202:205], v[114:117]
	v_mfma_f32_16x16x32_bf16 v[114:117], v[198:201], v[206:209], v[114:117]
	s_barrier
	s_setprio 0
	s_add_i32 s36, s70, s52
	v_lshl_add_u64 v[176:177], v[176:177], 0, s[16:17]
	s_mov_b32 m0, s36
	ds_read_b128 v[202:205], v172 offset:49152
	ds_read_b128 v[206:209], v172 offset:50176
	ds_read_b128 v[210:213], v172 offset:51200
	ds_read_b128 v[214:217], v172 offset:52224
	ds_read_b128 v[218:221], v172 offset:53248
	ds_read_b128 v[222:225], v172 offset:54272
	ds_read_b128 v[226:229], v172 offset:55296
	ds_read_b128 v[230:233], v172 offset:56320
	global_load_lds_dwordx4 v[176:177], off
	s_add_i32 m0, s36, 0x2000
	s_add_u32 s34, s34, 0x80080
	v_lshl_add_u64 v[176:177], v[234:235], 0, s[16:17]
	s_addc_u32 s35, s35, 0
	s_add_i32 s36, s71, s52
	global_load_lds_dwordx4 v[176:177], off
	v_lshl_add_u64 v[176:177], s[34:35], 0, v[132:133]
	s_mov_b32 m0, s36
	s_nop 0
	global_load_lds_dwordx4 v[176:177], off
	v_lshl_add_u64 v[176:177], s[34:35], 0, v[136:137]
	s_add_i32 m0, s36, 0x2000
	s_nop 0
	global_load_lds_dwordx4 v[176:177], off
	v_lshl_add_u64 v[176:177], v[236:237], 0, s[16:17]
	s_mov_b32 m0, s56
	s_nop 0
	global_load_lds_dwordx4 v[176:177], off
	v_lshl_add_u64 v[176:177], v[238:239], 0, s[16:17]
	s_mov_b32 m0, s57
	s_nop 0
	global_load_lds_dwordx4 v[176:177], off
	s_waitcnt vmcnt(8)
	s_waitcnt lgkmcnt(0)
	s_setprio 1
	s_barrier
	v_mfma_f32_16x16x32_bf16 v[62:65], v[150:153], v[202:205], v[62:65]
	v_mfma_f32_16x16x32_bf16 v[62:65], v[154:157], v[206:209], v[62:65]
	v_mfma_f32_16x16x32_bf16 v[46:49], v[150:153], v[210:213], v[46:49]
	v_mfma_f32_16x16x32_bf16 v[46:49], v[154:157], v[214:217], v[46:49]
	v_mfma_f32_16x16x32_bf16 v[30:33], v[150:153], v[218:221], v[30:33]
	v_mfma_f32_16x16x32_bf16 v[30:33], v[154:157], v[222:225], v[30:33]
	v_mfma_f32_16x16x32_bf16 v[14:17], v[150:153], v[226:229], v[14:17]
	v_mfma_f32_16x16x32_bf16 v[14:17], v[154:157], v[230:233], v[14:17]
	v_mfma_f32_16x16x32_bf16 v[10:13], v[158:161], v[226:229], v[10:13]
	v_mfma_f32_16x16x32_bf16 v[10:13], v[182:185], v[230:233], v[10:13]
	v_mfma_f32_16x16x32_bf16 v[26:29], v[158:161], v[218:221], v[26:29]
	v_mfma_f32_16x16x32_bf16 v[26:29], v[182:185], v[222:225], v[26:29]
	v_mfma_f32_16x16x32_bf16 v[42:45], v[158:161], v[210:213], v[42:45]
	v_mfma_f32_16x16x32_bf16 v[42:45], v[182:185], v[214:217], v[42:45]
	v_mfma_f32_16x16x32_bf16 v[58:61], v[158:161], v[202:205], v[58:61]
	v_mfma_f32_16x16x32_bf16 v[58:61], v[182:185], v[206:209], v[58:61]
	v_mfma_f32_16x16x32_bf16 v[54:57], v[186:189], v[202:205], v[54:57]
	v_mfma_f32_16x16x32_bf16 v[54:57], v[190:193], v[206:209], v[54:57]
	v_mfma_f32_16x16x32_bf16 v[38:41], v[186:189], v[210:213], v[38:41]
	v_mfma_f32_16x16x32_bf16 v[38:41], v[190:193], v[214:217], v[38:41]
	v_mfma_f32_16x16x32_bf16 v[22:25], v[186:189], v[218:221], v[22:25]
	v_mfma_f32_16x16x32_bf16 v[22:25], v[190:193], v[222:225], v[22:25]
	v_mfma_f32_16x16x32_bf16 v[6:9], v[186:189], v[226:229], v[6:9]
	v_mfma_f32_16x16x32_bf16 v[6:9], v[190:193], v[230:233], v[6:9]
	v_mfma_f32_16x16x32_bf16 v[2:5], v[194:197], v[226:229], v[2:5]
	v_mfma_f32_16x16x32_bf16 v[2:5], v[198:201], v[230:233], v[2:5]
	v_mfma_f32_16x16x32_bf16 v[18:21], v[194:197], v[218:221], v[18:21]
	v_mfma_f32_16x16x32_bf16 v[18:21], v[198:201], v[222:225], v[18:21]
	v_mfma_f32_16x16x32_bf16 v[34:37], v[194:197], v[210:213], v[34:37]
	v_mfma_f32_16x16x32_bf16 v[34:37], v[198:201], v[214:217], v[34:37]
	v_mfma_f32_16x16x32_bf16 v[50:53], v[194:197], v[202:205], v[50:53]
	v_mfma_f32_16x16x32_bf16 v[50:53], v[198:201], v[206:209], v[50:53]
	s_barrier
	s_setprio 0
	s_add_i32 s69, s69, 2
	s_add_u32 s4, s4, 0x100
	s_addc_u32 s5, s5, 0
	s_add_u32 s67, s67, 0x100
	s_addc_u32 s68, s68, 0
	s_cmp_gt_u32 s69, 29
	s_cbranch_scc0 .LBB0_1037
	s_and_b64 vcc, exec, s[18:19]
	s_cbranch_vccz .LBB0_1040
	s_barrier

.LBB0_1637:
	ds_read_b128 v[154:157], v150
	ds_read_b128 v[158:161], v150 offset:1024
	ds_read_b128 v[162:165], v150 offset:2048
	ds_read_b128 v[166:169], v150 offset:3072
	ds_read_b128 v[170:173], v151
	ds_read_b128 v[174:177], v151 offset:1024
	ds_read_b128 v[182:185], v151 offset:2048
	ds_read_b128 v[186:189], v151 offset:3072
	s_add_u32 s20, s18, 0xfff80080
	s_addc_u32 s21, s19, -1
	s_cmp_eq_u32 s63, 28
	s_cselect_b32 s23, s11, s21
	s_cselect_b32 s22, s58, s20
	s_cselect_b32 s21, s9, s62
	s_cselect_b32 s20, s59, s60
	v_lshl_add_u64 v[146:147], s[18:19], 0, v[138:139]
	s_add_i32 m0, s17, 0xc000
	ds_read_b128 v[190:193], v152
	ds_read_b128 v[194:197], v152 offset:1024
	ds_read_b128 v[198:201], v152 offset:2048
	ds_read_b128 v[202:205], v152 offset:3072
	ds_read_b128 v[206:209], v152 offset:4096
	ds_read_b128 v[210:213], v152 offset:5120
	ds_read_b128 v[214:217], v152 offset:6144
	ds_read_b128 v[218:221], v152 offset:7168
	global_load_lds_dwordx4 v[146:147], off
	v_lshl_add_u64 v[146:147], s[18:19], 0, v[140:141]
	s_add_i32 m0, s17, 0xe000
	s_nop 0
	global_load_lds_dwordx4 v[146:147], off
	s_waitcnt vmcnt(8)
	s_waitcnt lgkmcnt(0)
	s_setprio 1
	s_barrier
	v_mfma_f32_16x16x32_bf16 v[126:129], v[154:157], v[190:193], v[126:129]
	v_mfma_f32_16x16x32_bf16 v[126:129], v[158:161], v[194:197], v[126:129]
	v_mfma_f32_16x16x32_bf16 v[110:113], v[154:157], v[198:201], v[110:113]
	v_mfma_f32_16x16x32_bf16 v[110:113], v[158:161], v[202:205], v[110:113]
	v_mfma_f32_16x16x32_bf16 v[94:97], v[154:157], v[206:209], v[94:97]
	v_mfma_f32_16x16x32_bf16 v[94:97], v[158:161], v[210:213], v[94:97]
	v_mfma_f32_16x16x32_bf16 v[78:81], v[154:157], v[214:217], v[78:81]
	v_mfma_f32_16x16x32_bf16 v[78:81], v[158:161], v[218:221], v[78:81]
	v_mfma_f32_16x16x32_bf16 v[74:77], v[162:165], v[214:217], v[74:77]
	v_mfma_f32_16x16x32_bf16 v[74:77], v[166:169], v[218:221], v[74:77]
	v_mfma_f32_16x16x32_bf16 v[90:93], v[162:165], v[206:209], v[90:93]
	v_mfma_f32_16x16x32_bf16 v[90:93], v[166:169], v[210:213], v[90:93]
	v_mfma_f32_16x16x32_bf16 v[106:109], v[162:165], v[198:201], v[106:109]
	v_mfma_f32_16x16x32_bf16 v[106:109], v[166:169], v[202:205], v[106:109]
	v_mfma_f32_16x16x32_bf16 v[122:125], v[162:165], v[190:193], v[122:125]
	v_mfma_f32_16x16x32_bf16 v[122:125], v[166:169], v[194:197], v[122:125]
	v_mfma_f32_16x16x32_bf16 v[118:121], v[170:173], v[190:193], v[118:121]
	v_mfma_f32_16x16x32_bf16 v[118:121], v[174:177], v[194:197], v[118:121]
	v_mfma_f32_16x16x32_bf16 v[102:105], v[170:173], v[198:201], v[102:105]
	v_mfma_f32_16x16x32_bf16 v[102:105], v[174:177], v[202:205], v[102:105]
	v_mfma_f32_16x16x32_bf16 v[86:89], v[170:173], v[206:209], v[86:89]
	v_mfma_f32_16x16x32_bf16 v[86:89], v[174:177], v[210:213], v[86:89]
	v_mfma_f32_16x16x32_bf16 v[70:73], v[170:173], v[214:217], v[70:73]
	v_mfma_f32_16x16x32_bf16 v[70:73], v[174:177], v[218:221], v[70:73]
	v_mfma_f32_16x16x32_bf16 v[66:69], v[182:185], v[214:217], v[66:69]
	v_mfma_f32_16x16x32_bf16 v[66:69], v[186:189], v[218:221], v[66:69]
	v_mfma_f32_16x16x32_bf16 v[82:85], v[182:185], v[206:209], v[82:85]
	v_mfma_f32_16x16x32_bf16 v[82:85], v[186:189], v[210:213], v[82:85]
	v_mfma_f32_16x16x32_bf16 v[98:101], v[182:185], v[198:201], v[98:101]
	v_mfma_f32_16x16x32_bf16 v[98:101], v[186:189], v[202:205], v[98:101]
	v_mfma_f32_16x16x32_bf16 v[114:117], v[182:185], v[190:193], v[114:117]
	v_mfma_f32_16x16x32_bf16 v[114:117], v[186:189], v[194:197], v[114:117]
	s_barrier
	s_setprio 0
	s_add_i32 s66, s54, s28
	v_lshl_add_u64 v[146:147], s[20:21], 0, v[134:135]
	s_mov_b32 m0, s66
	ds_read_b128 v[190:193], v152 offset:16384
	ds_read_b128 v[194:197], v152 offset:17408
	ds_read_b128 v[198:201], v152 offset:18432
	ds_read_b128 v[202:205], v152 offset:19456
	ds_read_b128 v[206:209], v152 offset:20480
	ds_read_b128 v[210:213], v152 offset:21504
	ds_read_b128 v[214:217], v152 offset:22528
	ds_read_b128 v[218:221], v152 offset:23552
	global_load_lds_dwordx4 v[146:147], off
	s_add_i32 m0, s66, 0x2000
	s_add_u32 s66, s20, 0x80000
	v_lshl_add_u64 v[222:223], s[20:21], 0, v[130:131]
	s_addc_u32 s67, s21, 0
	s_add_i32 s68, s55, s28
	global_load_lds_dwordx4 v[222:223], off
	v_lshl_add_u64 v[224:225], s[66:67], 0, v[134:135]
	s_mov_b32 m0, s68
	v_lshl_add_u64 v[226:227], s[22:23], 0, v[132:133]
	global_load_lds_dwordx4 v[224:225], off
	v_lshl_add_u64 v[224:225], s[66:67], 0, v[130:131]
	s_add_i32 m0, s68, 0x2000
	s_nop 0
	global_load_lds_dwordx4 v[224:225], off
	v_lshl_add_u64 v[224:225], s[22:23], 0, v[136:137]
	s_mov_b32 m0, s17
	s_nop 0
	global_load_lds_dwordx4 v[224:225], off
	s_mov_b32 m0, s31
	s_nop 0
	global_load_lds_dwordx4 v[226:227], off
	s_waitcnt vmcnt(8)
	s_waitcnt lgkmcnt(0)
	s_setprio 1
	s_barrier
	v_mfma_f32_16x16x32_bf16 v[62:65], v[154:157], v[190:193], v[62:65]
	v_mfma_f32_16x16x32_bf16 v[62:65], v[158:161], v[194:197], v[62:65]
	v_mfma_f32_16x16x32_bf16 v[46:49], v[154:157], v[198:201], v[46:49]
	v_mfma_f32_16x16x32_bf16 v[46:49], v[158:161], v[202:205], v[46:49]
	v_mfma_f32_16x16x32_bf16 v[30:33], v[154:157], v[206:209], v[30:33]
	v_mfma_f32_16x16x32_bf16 v[30:33], v[158:161], v[210:213], v[30:33]
	v_mfma_f32_16x16x32_bf16 v[14:17], v[154:157], v[214:217], v[14:17]
	v_mfma_f32_16x16x32_bf16 v[14:17], v[158:161], v[218:221], v[14:17]
	v_mfma_f32_16x16x32_bf16 v[10:13], v[162:165], v[214:217], v[10:13]
	v_mfma_f32_16x16x32_bf16 v[10:13], v[166:169], v[218:221], v[10:13]
	v_mfma_f32_16x16x32_bf16 v[26:29], v[162:165], v[206:209], v[26:29]
	v_mfma_f32_16x16x32_bf16 v[26:29], v[166:169], v[210:213], v[26:29]
	v_mfma_f32_16x16x32_bf16 v[42:45], v[162:165], v[198:201], v[42:45]
	v_mfma_f32_16x16x32_bf16 v[42:45], v[166:169], v[202:205], v[42:45]
	v_mfma_f32_16x16x32_bf16 v[58:61], v[162:165], v[190:193], v[58:61]
	v_mfma_f32_16x16x32_bf16 v[58:61], v[166:169], v[194:197], v[58:61]
	v_mfma_f32_16x16x32_bf16 v[54:57], v[170:173], v[190:193], v[54:57]
	v_mfma_f32_16x16x32_bf16 v[54:57], v[174:177], v[194:197], v[54:57]
	v_mfma_f32_16x16x32_bf16 v[38:41], v[170:173], v[198:201], v[38:41]
	v_mfma_f32_16x16x32_bf16 v[38:41], v[174:177], v[202:205], v[38:41]
	v_mfma_f32_16x16x32_bf16 v[22:25], v[170:173], v[206:209], v[22:25]
	v_mfma_f32_16x16x32_bf16 v[22:25], v[174:177], v[210:213], v[22:25]
	v_mfma_f32_16x16x32_bf16 v[6:9], v[170:173], v[214:217], v[6:9]
	v_mfma_f32_16x16x32_bf16 v[6:9], v[174:177], v[218:221], v[6:9]
	v_mfma_f32_16x16x32_bf16 v[2:5], v[182:185], v[214:217], v[2:5]
	v_mfma_f32_16x16x32_bf16 v[2:5], v[186:189], v[218:221], v[2:5]
	v_mfma_f32_16x16x32_bf16 v[18:21], v[182:185], v[206:209], v[18:21]
	v_mfma_f32_16x16x32_bf16 v[18:21], v[186:189], v[210:213], v[18:21]
	v_mfma_f32_16x16x32_bf16 v[34:37], v[182:185], v[198:201], v[34:37]
	v_mfma_f32_16x16x32_bf16 v[34:37], v[186:189], v[202:205], v[34:37]
	v_mfma_f32_16x16x32_bf16 v[50:53], v[182:185], v[190:193], v[50:53]
	v_mfma_f32_16x16x32_bf16 v[50:53], v[186:189], v[194:197], v[50:53]
	s_barrier
	s_setprio 0
	s_add_i32 s66, 0, 0x18000
	v_add_u32_e32 v153, s66, v148
	s_add_i32 s67, 0, 0x1c000
	ds_read_b128 v[154:157], v153
	ds_read_b128 v[158:161], v153 offset:1024
	ds_read_b128 v[162:165], v153 offset:2048
	ds_read_b128 v[166:169], v153 offset:3072
	v_add_u32_e32 v153, s67, v148
	ds_read_b128 v[170:173], v153
	ds_read_b128 v[174:177], v153 offset:1024
	ds_read_b128 v[182:185], v153 offset:2048
	ds_read_b128 v[186:189], v153 offset:3072
	s_add_u32 s22, s22, 0x80000
	s_addc_u32 s23, s23, 0
	s_mov_b32 m0, s34
	v_lshl_add_u64 v[228:229], s[22:23], 0, v[136:137]
	ds_read_b128 v[190:193], v152 offset:32768
	ds_read_b128 v[194:197], v152 offset:33792
	ds_read_b128 v[198:201], v152 offset:34816
	ds_read_b128 v[202:205], v152 offset:35840
	ds_read_b128 v[206:209], v152 offset:36864
	ds_read_b128 v[210:213], v152 offset:37888
	ds_read_b128 v[214:217], v152 offset:38912
	ds_read_b128 v[218:221], v152 offset:39936
	global_load_lds_dwordx4 v[228:229], off
	v_lshl_add_u64 v[228:229], s[22:23], 0, v[132:133]
	s_mov_b32 m0, s35
	s_nop 0
	global_load_lds_dwordx4 v[228:229], off
	s_waitcnt vmcnt(8)
	s_waitcnt lgkmcnt(0)
	s_setprio 1
	s_barrier
	v_mfma_f32_16x16x32_bf16 v[126:129], v[154:157], v[190:193], v[126:129]
	v_mfma_f32_16x16x32_bf16 v[126:129], v[158:161], v[194:197], v[126:129]
	v_mfma_f32_16x16x32_bf16 v[110:113], v[154:157], v[198:201], v[110:113]
	v_mfma_f32_16x16x32_bf16 v[110:113], v[158:161], v[202:205], v[110:113]
	v_mfma_f32_16x16x32_bf16 v[94:97], v[154:157], v[206:209], v[94:97]
	v_mfma_f32_16x16x32_bf16 v[94:97], v[158:161], v[210:213], v[94:97]
	v_mfma_f32_16x16x32_bf16 v[78:81], v[154:157], v[214:217], v[78:81]
	v_mfma_f32_16x16x32_bf16 v[78:81], v[158:161], v[218:221], v[78:81]
	v_mfma_f32_16x16x32_bf16 v[74:77], v[162:165], v[214:217], v[74:77]
	v_mfma_f32_16x16x32_bf16 v[74:77], v[166:169], v[218:221], v[74:77]
	v_mfma_f32_16x16x32_bf16 v[90:93], v[162:165], v[206:209], v[90:93]
	v_mfma_f32_16x16x32_bf16 v[90:93], v[166:169], v[210:213], v[90:93]
	v_mfma_f32_16x16x32_bf16 v[106:109], v[162:165], v[198:201], v[106:109]
	v_mfma_f32_16x16x32_bf16 v[106:109], v[166:169], v[202:205], v[106:109]
	v_mfma_f32_16x16x32_bf16 v[122:125], v[162:165], v[190:193], v[122:125]
	v_mfma_f32_16x16x32_bf16 v[122:125], v[166:169], v[194:197], v[122:125]
	v_mfma_f32_16x16x32_bf16 v[118:121], v[170:173], v[190:193], v[118:121]
	v_mfma_f32_16x16x32_bf16 v[118:121], v[174:177], v[194:197], v[118:121]
	v_mfma_f32_16x16x32_bf16 v[102:105], v[170:173], v[198:201], v[102:105]
	v_mfma_f32_16x16x32_bf16 v[102:105], v[174:177], v[202:205], v[102:105]
	v_mfma_f32_16x16x32_bf16 v[86:89], v[170:173], v[206:209], v[86:89]
	v_mfma_f32_16x16x32_bf16 v[86:89], v[174:177], v[210:213], v[86:89]
	v_mfma_f32_16x16x32_bf16 v[70:73], v[170:173], v[214:217], v[70:73]
	v_mfma_f32_16x16x32_bf16 v[70:73], v[174:177], v[218:221], v[70:73]
	v_mfma_f32_16x16x32_bf16 v[66:69], v[182:185], v[214:217], v[66:69]
	v_mfma_f32_16x16x32_bf16 v[66:69], v[186:189], v[218:221], v[66:69]
	v_mfma_f32_16x16x32_bf16 v[82:85], v[182:185], v[206:209], v[82:85]
	v_mfma_f32_16x16x32_bf16 v[82:85], v[186:189], v[210:213], v[82:85]
	v_mfma_f32_16x16x32_bf16 v[98:101], v[182:185], v[198:201], v[98:101]
	v_mfma_f32_16x16x32_bf16 v[98:101], v[186:189], v[202:205], v[98:101]
	v_mfma_f32_16x16x32_bf16 v[114:117], v[182:185], v[190:193], v[114:117]
	v_mfma_f32_16x16x32_bf16 v[114:117], v[186:189], v[194:197], v[114:117]
	s_barrier
	s_setprio 0
	s_add_i32 s22, s66, s28
	v_lshl_add_u64 v[146:147], v[146:147], 0, s[4:5]
	s_mov_b32 m0, s22
	ds_read_b128 v[190:193], v152 offset:49152
	ds_read_b128 v[194:197], v152 offset:50176
	ds_read_b128 v[198:201], v152 offset:51200
	ds_read_b128 v[202:205], v152 offset:52224
	ds_read_b128 v[206:209], v152 offset:53248
	ds_read_b128 v[210:213], v152 offset:54272
	ds_read_b128 v[214:217], v152 offset:55296
	ds_read_b128 v[218:221], v152 offset:56320
	global_load_lds_dwordx4 v[146:147], off
	s_add_i32 m0, s22, 0x2000
	s_add_u32 s20, s20, 0x80080
	v_lshl_add_u64 v[146:147], v[222:223], 0, s[4:5]
	s_addc_u32 s21, s21, 0
	s_add_i32 s22, s67, s28
	global_load_lds_dwordx4 v[146:147], off
	v_lshl_add_u64 v[146:147], s[20:21], 0, v[134:135]
	s_mov_b32 m0, s22
	s_nop 0
	global_load_lds_dwordx4 v[146:147], off
	v_lshl_add_u64 v[146:147], s[20:21], 0, v[130:131]
	s_add_i32 m0, s22, 0x2000
	s_nop 0
	global_load_lds_dwordx4 v[146:147], off
	v_lshl_add_u64 v[146:147], v[224:225], 0, s[4:5]
	s_mov_b32 m0, s37
	s_nop 0
	global_load_lds_dwordx4 v[146:147], off
	v_lshl_add_u64 v[146:147], v[226:227], 0, s[4:5]
	s_mov_b32 m0, s52
	s_nop 0
	global_load_lds_dwordx4 v[146:147], off
	s_waitcnt vmcnt(8)
	s_waitcnt lgkmcnt(0)
	s_setprio 1
	s_barrier
	v_mfma_f32_16x16x32_bf16 v[62:65], v[154:157], v[190:193], v[62:65]
	v_mfma_f32_16x16x32_bf16 v[62:65], v[158:161], v[194:197], v[62:65]
	v_mfma_f32_16x16x32_bf16 v[46:49], v[154:157], v[198:201], v[46:49]
	v_mfma_f32_16x16x32_bf16 v[46:49], v[158:161], v[202:205], v[46:49]
	v_mfma_f32_16x16x32_bf16 v[30:33], v[154:157], v[206:209], v[30:33]
	v_mfma_f32_16x16x32_bf16 v[30:33], v[158:161], v[210:213], v[30:33]
	v_mfma_f32_16x16x32_bf16 v[14:17], v[154:157], v[214:217], v[14:17]
	v_mfma_f32_16x16x32_bf16 v[14:17], v[158:161], v[218:221], v[14:17]
	v_mfma_f32_16x16x32_bf16 v[10:13], v[162:165], v[214:217], v[10:13]
	v_mfma_f32_16x16x32_bf16 v[10:13], v[166:169], v[218:221], v[10:13]
	v_mfma_f32_16x16x32_bf16 v[26:29], v[162:165], v[206:209], v[26:29]
	v_mfma_f32_16x16x32_bf16 v[26:29], v[166:169], v[210:213], v[26:29]
	v_mfma_f32_16x16x32_bf16 v[42:45], v[162:165], v[198:201], v[42:45]
	v_mfma_f32_16x16x32_bf16 v[42:45], v[166:169], v[202:205], v[42:45]
	v_mfma_f32_16x16x32_bf16 v[58:61], v[162:165], v[190:193], v[58:61]
	v_mfma_f32_16x16x32_bf16 v[58:61], v[166:169], v[194:197], v[58:61]
	v_mfma_f32_16x16x32_bf16 v[54:57], v[170:173], v[190:193], v[54:57]
	v_mfma_f32_16x16x32_bf16 v[54:57], v[174:177], v[194:197], v[54:57]
	v_mfma_f32_16x16x32_bf16 v[38:41], v[170:173], v[198:201], v[38:41]
	v_mfma_f32_16x16x32_bf16 v[38:41], v[174:177], v[202:205], v[38:41]
	v_mfma_f32_16x16x32_bf16 v[22:25], v[170:173], v[206:209], v[22:25]
	v_mfma_f32_16x16x32_bf16 v[22:25], v[174:177], v[210:213], v[22:25]
	v_mfma_f32_16x16x32_bf16 v[6:9], v[170:173], v[214:217], v[6:9]
	v_mfma_f32_16x16x32_bf16 v[6:9], v[174:177], v[218:221], v[6:9]
	v_mfma_f32_16x16x32_bf16 v[2:5], v[182:185], v[214:217], v[2:5]
	v_mfma_f32_16x16x32_bf16 v[2:5], v[186:189], v[218:221], v[2:5]
	v_mfma_f32_16x16x32_bf16 v[18:21], v[182:185], v[206:209], v[18:21]
	v_mfma_f32_16x16x32_bf16 v[18:21], v[186:189], v[210:213], v[18:21]
	v_mfma_f32_16x16x32_bf16 v[34:37], v[182:185], v[198:201], v[34:37]
	v_mfma_f32_16x16x32_bf16 v[34:37], v[186:189], v[202:205], v[34:37]
	v_mfma_f32_16x16x32_bf16 v[50:53], v[182:185], v[190:193], v[50:53]
	v_mfma_f32_16x16x32_bf16 v[50:53], v[186:189], v[194:197], v[50:53]
	s_barrier
	s_setprio 0
	s_add_i32 s63, s63, 2
	s_add_u32 s18, s18, 0x100
	s_addc_u32 s19, s19, 0
	s_add_u32 s60, s60, 0x100
	s_addc_u32 s62, s62, 0
	s_cmp_gt_u32 s63, 29
	s_cbranch_scc0 .LBB0_1637
	s_and_b64 vcc, exec, s[6:7]
	s_cbranch_vccz .LBB0_1640
	s_barrier

.LBB0_1913:
	ds_read_b128 v[148:151], v172
	ds_read_b128 v[152:155], v172 offset:1024
	ds_read_b128 v[156:159], v172 offset:2048
	ds_read_b128 v[160:163], v172 offset:3072
	ds_read_b128 v[182:185], v173
	ds_read_b128 v[186:189], v173 offset:1024
	ds_read_b128 v[190:193], v173 offset:2048
	ds_read_b128 v[194:197], v173 offset:3072
	s_add_u32 s54, s52, 0xfff80080
	s_addc_u32 s55, s53, -1
	s_cmp_eq_u32 s82, 28
	s_cselect_b32 s57, s9, s55
	s_cselect_b32 s56, s31, s54
	s_cselect_b32 s55, s29, s79
	s_cselect_b32 s54, s77, s78
	v_lshl_add_u64 v[176:177], s[52:53], 0, v[140:141]
	s_add_i32 m0, s59, 0xc000
	ds_read_b128 v[198:201], v174
	ds_read_b128 v[202:205], v174 offset:1024
	ds_read_b128 v[206:209], v174 offset:2048
	ds_read_b128 v[210:213], v174 offset:3072
	ds_read_b128 v[214:217], v174 offset:4096
	ds_read_b128 v[218:221], v174 offset:5120
	ds_read_b128 v[222:225], v174 offset:6144
	ds_read_b128 v[226:229], v174 offset:7168
	global_load_lds_dwordx4 v[176:177], off
	v_lshl_add_u64 v[176:177], s[52:53], 0, v[142:143]
	s_add_i32 m0, s59, 0xe000
	s_nop 0
	global_load_lds_dwordx4 v[176:177], off
	s_waitcnt vmcnt(8)
	s_waitcnt lgkmcnt(0)
	s_setprio 1
	s_barrier
	v_mfma_f32_16x16x32_bf16 v[126:129], v[148:151], v[198:201], v[126:129]
	v_mfma_f32_16x16x32_bf16 v[126:129], v[152:155], v[202:205], v[126:129]
	v_mfma_f32_16x16x32_bf16 v[110:113], v[148:151], v[206:209], v[110:113]
	v_mfma_f32_16x16x32_bf16 v[110:113], v[152:155], v[210:213], v[110:113]
	v_mfma_f32_16x16x32_bf16 v[94:97], v[148:151], v[214:217], v[94:97]
	v_mfma_f32_16x16x32_bf16 v[94:97], v[152:155], v[218:221], v[94:97]
	v_mfma_f32_16x16x32_bf16 v[78:81], v[148:151], v[222:225], v[78:81]
	v_mfma_f32_16x16x32_bf16 v[78:81], v[152:155], v[226:229], v[78:81]
	v_mfma_f32_16x16x32_bf16 v[74:77], v[156:159], v[222:225], v[74:77]
	v_mfma_f32_16x16x32_bf16 v[74:77], v[160:163], v[226:229], v[74:77]
	v_mfma_f32_16x16x32_bf16 v[90:93], v[156:159], v[214:217], v[90:93]
	v_mfma_f32_16x16x32_bf16 v[90:93], v[160:163], v[218:221], v[90:93]
	v_mfma_f32_16x16x32_bf16 v[106:109], v[156:159], v[206:209], v[106:109]
	v_mfma_f32_16x16x32_bf16 v[106:109], v[160:163], v[210:213], v[106:109]
	v_mfma_f32_16x16x32_bf16 v[122:125], v[156:159], v[198:201], v[122:125]
	v_mfma_f32_16x16x32_bf16 v[122:125], v[160:163], v[202:205], v[122:125]
	v_mfma_f32_16x16x32_bf16 v[118:121], v[182:185], v[198:201], v[118:121]
	v_mfma_f32_16x16x32_bf16 v[118:121], v[186:189], v[202:205], v[118:121]
	v_mfma_f32_16x16x32_bf16 v[102:105], v[182:185], v[206:209], v[102:105]
	v_mfma_f32_16x16x32_bf16 v[102:105], v[186:189], v[210:213], v[102:105]
	v_mfma_f32_16x16x32_bf16 v[86:89], v[182:185], v[214:217], v[86:89]
	v_mfma_f32_16x16x32_bf16 v[86:89], v[186:189], v[218:221], v[86:89]
	v_mfma_f32_16x16x32_bf16 v[70:73], v[182:185], v[222:225], v[70:73]
	v_mfma_f32_16x16x32_bf16 v[70:73], v[186:189], v[226:229], v[70:73]
	v_mfma_f32_16x16x32_bf16 v[66:69], v[190:193], v[222:225], v[66:69]
	v_mfma_f32_16x16x32_bf16 v[66:69], v[194:197], v[226:229], v[66:69]
	v_mfma_f32_16x16x32_bf16 v[82:85], v[190:193], v[214:217], v[82:85]
	v_mfma_f32_16x16x32_bf16 v[82:85], v[194:197], v[218:221], v[82:85]
	v_mfma_f32_16x16x32_bf16 v[98:101], v[190:193], v[206:209], v[98:101]
	v_mfma_f32_16x16x32_bf16 v[98:101], v[194:197], v[210:213], v[98:101]
	v_mfma_f32_16x16x32_bf16 v[114:117], v[190:193], v[198:201], v[114:117]
	v_mfma_f32_16x16x32_bf16 v[114:117], v[194:197], v[202:205], v[114:117]
	s_barrier
	s_setprio 0
	s_add_i32 s83, s72, s58
	v_lshl_add_u64 v[176:177], s[54:55], 0, v[132:133]
	s_mov_b32 m0, s83
	ds_read_b128 v[198:201], v174 offset:16384
	ds_read_b128 v[202:205], v174 offset:17408
	ds_read_b128 v[206:209], v174 offset:18432
	ds_read_b128 v[210:213], v174 offset:19456
	ds_read_b128 v[214:217], v174 offset:20480
	ds_read_b128 v[218:221], v174 offset:21504
	ds_read_b128 v[222:225], v174 offset:22528
	ds_read_b128 v[226:229], v174 offset:23552
	global_load_lds_dwordx4 v[176:177], off
	s_add_i32 m0, s83, 0x2000
	s_add_u32 s88, s54, 0x80000
	v_lshl_add_u64 v[230:231], s[54:55], 0, v[136:137]
	s_addc_u32 s89, s55, 0
	s_add_i32 s83, s73, s58
	global_load_lds_dwordx4 v[230:231], off
	v_lshl_add_u64 v[232:233], s[88:89], 0, v[132:133]
	s_mov_b32 m0, s83
	v_lshl_add_u64 v[234:235], s[56:57], 0, v[134:135]
	global_load_lds_dwordx4 v[232:233], off
	v_lshl_add_u64 v[232:233], s[88:89], 0, v[136:137]
	s_add_i32 m0, s83, 0x2000
	s_nop 0
	global_load_lds_dwordx4 v[232:233], off
	v_lshl_add_u64 v[232:233], s[56:57], 0, v[130:131]
	s_mov_b32 m0, s59
	s_nop 0
	global_load_lds_dwordx4 v[232:233], off
	s_mov_b32 m0, s60
	s_nop 0
	global_load_lds_dwordx4 v[234:235], off
	s_waitcnt vmcnt(8)
	s_waitcnt lgkmcnt(0)
	s_setprio 1
	s_barrier
	v_mfma_f32_16x16x32_bf16 v[62:65], v[148:151], v[198:201], v[62:65]
	v_mfma_f32_16x16x32_bf16 v[62:65], v[152:155], v[202:205], v[62:65]
	v_mfma_f32_16x16x32_bf16 v[46:49], v[148:151], v[206:209], v[46:49]
	v_mfma_f32_16x16x32_bf16 v[46:49], v[152:155], v[210:213], v[46:49]
	v_mfma_f32_16x16x32_bf16 v[30:33], v[148:151], v[214:217], v[30:33]
	v_mfma_f32_16x16x32_bf16 v[30:33], v[152:155], v[218:221], v[30:33]
	v_mfma_f32_16x16x32_bf16 v[14:17], v[148:151], v[222:225], v[14:17]
	v_mfma_f32_16x16x32_bf16 v[14:17], v[152:155], v[226:229], v[14:17]
	v_mfma_f32_16x16x32_bf16 v[10:13], v[156:159], v[222:225], v[10:13]
	v_mfma_f32_16x16x32_bf16 v[10:13], v[160:163], v[226:229], v[10:13]
	v_mfma_f32_16x16x32_bf16 v[26:29], v[156:159], v[214:217], v[26:29]
	v_mfma_f32_16x16x32_bf16 v[26:29], v[160:163], v[218:221], v[26:29]
	v_mfma_f32_16x16x32_bf16 v[42:45], v[156:159], v[206:209], v[42:45]
	v_mfma_f32_16x16x32_bf16 v[42:45], v[160:163], v[210:213], v[42:45]
	v_mfma_f32_16x16x32_bf16 v[58:61], v[156:159], v[198:201], v[58:61]
	v_mfma_f32_16x16x32_bf16 v[58:61], v[160:163], v[202:205], v[58:61]
	v_mfma_f32_16x16x32_bf16 v[54:57], v[182:185], v[198:201], v[54:57]
	v_mfma_f32_16x16x32_bf16 v[54:57], v[186:189], v[202:205], v[54:57]
	v_mfma_f32_16x16x32_bf16 v[38:41], v[182:185], v[206:209], v[38:41]
	v_mfma_f32_16x16x32_bf16 v[38:41], v[186:189], v[210:213], v[38:41]
	v_mfma_f32_16x16x32_bf16 v[22:25], v[182:185], v[214:217], v[22:25]
	v_mfma_f32_16x16x32_bf16 v[22:25], v[186:189], v[218:221], v[22:25]
	v_mfma_f32_16x16x32_bf16 v[6:9], v[182:185], v[222:225], v[6:9]
	v_mfma_f32_16x16x32_bf16 v[6:9], v[186:189], v[226:229], v[6:9]
	v_mfma_f32_16x16x32_bf16 v[2:5], v[190:193], v[222:225], v[2:5]
	v_mfma_f32_16x16x32_bf16 v[2:5], v[194:197], v[226:229], v[2:5]
	v_mfma_f32_16x16x32_bf16 v[18:21], v[190:193], v[214:217], v[18:21]
	v_mfma_f32_16x16x32_bf16 v[18:21], v[194:197], v[218:221], v[18:21]
	v_mfma_f32_16x16x32_bf16 v[34:37], v[190:193], v[206:209], v[34:37]
	v_mfma_f32_16x16x32_bf16 v[34:37], v[194:197], v[210:213], v[34:37]
	v_mfma_f32_16x16x32_bf16 v[50:53], v[190:193], v[198:201], v[50:53]
	v_mfma_f32_16x16x32_bf16 v[50:53], v[194:197], v[202:205], v[50:53]
	s_barrier
	s_setprio 0
	s_add_i32 s83, 0, 0x18000
	s_add_i32 s88, 0, 0x1c000
	v_add_u32_e32 v160, s83, v166
	v_add_u32_e32 v179, s88, v166
	ds_read_b128 v[148:151], v160
	ds_read_b128 v[152:155], v160 offset:1024
	ds_read_b128 v[156:159], v160 offset:2048
	ds_read_b128 v[160:163], v160 offset:3072
	ds_read_b128 v[182:185], v179
	ds_read_b128 v[186:189], v179 offset:1024
	ds_read_b128 v[190:193], v179 offset:2048
	ds_read_b128 v[194:197], v179 offset:3072
	s_add_u32 s56, s56, 0x80000
	s_addc_u32 s57, s57, 0
	s_mov_b32 m0, s62
	v_lshl_add_u64 v[236:237], s[56:57], 0, v[130:131]
	ds_read_b128 v[198:201], v174 offset:32768
	ds_read_b128 v[202:205], v174 offset:33792
	ds_read_b128 v[206:209], v174 offset:34816
	ds_read_b128 v[210:213], v174 offset:35840
	ds_read_b128 v[214:217], v174 offset:36864
	ds_read_b128 v[218:221], v174 offset:37888
	ds_read_b128 v[222:225], v174 offset:38912
	ds_read_b128 v[226:229], v174 offset:39936
	global_load_lds_dwordx4 v[236:237], off
	v_lshl_add_u64 v[236:237], s[56:57], 0, v[134:135]
	s_mov_b32 m0, s63
	s_nop 0
	global_load_lds_dwordx4 v[236:237], off
	s_waitcnt vmcnt(8)
	s_waitcnt lgkmcnt(0)
	s_setprio 1
	s_barrier
	v_mfma_f32_16x16x32_bf16 v[126:129], v[148:151], v[198:201], v[126:129]
	v_mfma_f32_16x16x32_bf16 v[126:129], v[152:155], v[202:205], v[126:129]
	v_mfma_f32_16x16x32_bf16 v[110:113], v[148:151], v[206:209], v[110:113]
	v_mfma_f32_16x16x32_bf16 v[110:113], v[152:155], v[210:213], v[110:113]
	v_mfma_f32_16x16x32_bf16 v[94:97], v[148:151], v[214:217], v[94:97]
	v_mfma_f32_16x16x32_bf16 v[94:97], v[152:155], v[218:221], v[94:97]
	v_mfma_f32_16x16x32_bf16 v[78:81], v[148:151], v[222:225], v[78:81]
	v_mfma_f32_16x16x32_bf16 v[78:81], v[152:155], v[226:229], v[78:81]
	v_mfma_f32_16x16x32_bf16 v[74:77], v[156:159], v[222:225], v[74:77]
	v_mfma_f32_16x16x32_bf16 v[74:77], v[160:163], v[226:229], v[74:77]
	v_mfma_f32_16x16x32_bf16 v[90:93], v[156:159], v[214:217], v[90:93]
	v_mfma_f32_16x16x32_bf16 v[90:93], v[160:163], v[218:221], v[90:93]
	v_mfma_f32_16x16x32_bf16 v[106:109], v[156:159], v[206:209], v[106:109]
	v_mfma_f32_16x16x32_bf16 v[106:109], v[160:163], v[210:213], v[106:109]
	v_mfma_f32_16x16x32_bf16 v[122:125], v[156:159], v[198:201], v[122:125]
	v_mfma_f32_16x16x32_bf16 v[122:125], v[160:163], v[202:205], v[122:125]
	v_mfma_f32_16x16x32_bf16 v[118:121], v[182:185], v[198:201], v[118:121]
	v_mfma_f32_16x16x32_bf16 v[118:121], v[186:189], v[202:205], v[118:121]
	v_mfma_f32_16x16x32_bf16 v[102:105], v[182:185], v[206:209], v[102:105]
	v_mfma_f32_16x16x32_bf16 v[102:105], v[186:189], v[210:213], v[102:105]
	v_mfma_f32_16x16x32_bf16 v[86:89], v[182:185], v[214:217], v[86:89]
	v_mfma_f32_16x16x32_bf16 v[86:89], v[186:189], v[218:221], v[86:89]
	v_mfma_f32_16x16x32_bf16 v[70:73], v[182:185], v[222:225], v[70:73]
	v_mfma_f32_16x16x32_bf16 v[70:73], v[186:189], v[226:229], v[70:73]
	v_mfma_f32_16x16x32_bf16 v[66:69], v[190:193], v[222:225], v[66:69]
	v_mfma_f32_16x16x32_bf16 v[66:69], v[194:197], v[226:229], v[66:69]
	v_mfma_f32_16x16x32_bf16 v[82:85], v[190:193], v[214:217], v[82:85]
	v_mfma_f32_16x16x32_bf16 v[82:85], v[194:197], v[218:221], v[82:85]
	v_mfma_f32_16x16x32_bf16 v[98:101], v[190:193], v[206:209], v[98:101]
	v_mfma_f32_16x16x32_bf16 v[98:101], v[194:197], v[210:213], v[98:101]
	v_mfma_f32_16x16x32_bf16 v[114:117], v[190:193], v[198:201], v[114:117]
	v_mfma_f32_16x16x32_bf16 v[114:117], v[194:197], v[202:205], v[114:117]
	s_barrier
	s_setprio 0
	s_add_i32 s56, s83, s58
	v_lshl_add_u64 v[176:177], v[176:177], 0, s[20:21]
	s_mov_b32 m0, s56
	ds_read_b128 v[198:201], v174 offset:49152
	ds_read_b128 v[202:205], v174 offset:50176
	ds_read_b128 v[206:209], v174 offset:51200
	ds_read_b128 v[210:213], v174 offset:52224
	ds_read_b128 v[214:217], v174 offset:53248
	ds_read_b128 v[218:221], v174 offset:54272
	ds_read_b128 v[222:225], v174 offset:55296
	ds_read_b128 v[226:229], v174 offset:56320
	global_load_lds_dwordx4 v[176:177], off
	s_add_i32 m0, s56, 0x2000
	s_add_u32 s54, s54, 0x80080
	v_lshl_add_u64 v[176:177], v[230:231], 0, s[20:21]
	s_addc_u32 s55, s55, 0
	s_add_i32 s56, s88, s58
	global_load_lds_dwordx4 v[176:177], off
	v_lshl_add_u64 v[176:177], s[54:55], 0, v[132:133]
	s_mov_b32 m0, s56
	s_nop 0
	global_load_lds_dwordx4 v[176:177], off
	v_lshl_add_u64 v[176:177], s[54:55], 0, v[136:137]
	s_add_i32 m0, s56, 0x2000
	s_nop 0
	global_load_lds_dwordx4 v[176:177], off
	v_lshl_add_u64 v[176:177], v[232:233], 0, s[20:21]
	s_mov_b32 m0, s67
	s_nop 0
	global_load_lds_dwordx4 v[176:177], off
	v_lshl_add_u64 v[176:177], v[234:235], 0, s[20:21]
	s_mov_b32 m0, s68
	s_nop 0
	global_load_lds_dwordx4 v[176:177], off
	s_waitcnt vmcnt(8)
	s_waitcnt lgkmcnt(0)
	s_setprio 1
	s_barrier
	v_mfma_f32_16x16x32_bf16 v[62:65], v[148:151], v[198:201], v[62:65]
	v_mfma_f32_16x16x32_bf16 v[62:65], v[152:155], v[202:205], v[62:65]
	v_mfma_f32_16x16x32_bf16 v[46:49], v[148:151], v[206:209], v[46:49]
	v_mfma_f32_16x16x32_bf16 v[46:49], v[152:155], v[210:213], v[46:49]
	v_mfma_f32_16x16x32_bf16 v[30:33], v[148:151], v[214:217], v[30:33]
	v_mfma_f32_16x16x32_bf16 v[30:33], v[152:155], v[218:221], v[30:33]
	v_mfma_f32_16x16x32_bf16 v[14:17], v[148:151], v[222:225], v[14:17]
	v_mfma_f32_16x16x32_bf16 v[14:17], v[152:155], v[226:229], v[14:17]
	v_mfma_f32_16x16x32_bf16 v[10:13], v[156:159], v[222:225], v[10:13]
	v_mfma_f32_16x16x32_bf16 v[10:13], v[160:163], v[226:229], v[10:13]
	v_mfma_f32_16x16x32_bf16 v[26:29], v[156:159], v[214:217], v[26:29]
	v_mfma_f32_16x16x32_bf16 v[26:29], v[160:163], v[218:221], v[26:29]
	v_mfma_f32_16x16x32_bf16 v[42:45], v[156:159], v[206:209], v[42:45]
	v_mfma_f32_16x16x32_bf16 v[42:45], v[160:163], v[210:213], v[42:45]
	v_mfma_f32_16x16x32_bf16 v[58:61], v[156:159], v[198:201], v[58:61]
	v_mfma_f32_16x16x32_bf16 v[58:61], v[160:163], v[202:205], v[58:61]
	v_mfma_f32_16x16x32_bf16 v[54:57], v[182:185], v[198:201], v[54:57]
	v_mfma_f32_16x16x32_bf16 v[54:57], v[186:189], v[202:205], v[54:57]
	v_mfma_f32_16x16x32_bf16 v[38:41], v[182:185], v[206:209], v[38:41]
	v_mfma_f32_16x16x32_bf16 v[38:41], v[186:189], v[210:213], v[38:41]
	v_mfma_f32_16x16x32_bf16 v[22:25], v[182:185], v[214:217], v[22:25]
	v_mfma_f32_16x16x32_bf16 v[22:25], v[186:189], v[218:221], v[22:25]
	v_mfma_f32_16x16x32_bf16 v[6:9], v[182:185], v[222:225], v[6:9]
	v_mfma_f32_16x16x32_bf16 v[6:9], v[186:189], v[226:229], v[6:9]
	v_mfma_f32_16x16x32_bf16 v[2:5], v[190:193], v[222:225], v[2:5]
	v_mfma_f32_16x16x32_bf16 v[2:5], v[194:197], v[226:229], v[2:5]
	v_mfma_f32_16x16x32_bf16 v[18:21], v[190:193], v[214:217], v[18:21]
	v_mfma_f32_16x16x32_bf16 v[18:21], v[194:197], v[218:221], v[18:21]
	v_mfma_f32_16x16x32_bf16 v[34:37], v[190:193], v[206:209], v[34:37]
	v_mfma_f32_16x16x32_bf16 v[34:37], v[194:197], v[210:213], v[34:37]
	v_mfma_f32_16x16x32_bf16 v[50:53], v[190:193], v[198:201], v[50:53]
	v_mfma_f32_16x16x32_bf16 v[50:53], v[194:197], v[202:205], v[50:53]
	s_barrier
	s_setprio 0
	s_add_i32 s82, s82, 2
	s_add_u32 s52, s52, 0x100
	s_addc_u32 s53, s53, 0
	s_add_u32 s78, s78, 0x100
	s_addc_u32 s79, s79, 0
	s_cmp_gt_u32 s82, 29
	s_cbranch_scc0 .LBB0_1913
	s_and_b64 vcc, exec, s[22:23]
	s_cbranch_vccz .LBB0_1916
	s_barrier

.LBB0_2098:
	ds_read_b128 v[146:149], v168
	ds_read_b128 v[150:153], v168 offset:1024
	ds_read_b128 v[172:175], v168 offset:2048
	ds_read_b128 v[182:185], v168 offset:3072
	ds_read_b128 v[186:189], v169
	ds_read_b128 v[190:193], v169 offset:1024
	ds_read_b128 v[194:197], v169 offset:2048
	ds_read_b128 v[198:201], v169 offset:3072
	s_add_u32 s28, s26, 0xfffc0080
	s_addc_u32 s29, s27, -1
	s_cmp_eq_u32 s72, 4
	s_cselect_b32 s31, s3, s29
	s_cselect_b32 s30, s5, s28
	s_cselect_b32 s29, s17, s71
	s_cselect_b32 s28, s19, s70
	v_lshl_add_u64 v[176:177], s[26:27], 0, v[138:139]
	s_add_i32 m0, s53, 0xc000
	ds_read_b128 v[202:205], v170
	ds_read_b128 v[206:209], v170 offset:1024
	ds_read_b128 v[210:213], v170 offset:2048
	ds_read_b128 v[214:217], v170 offset:3072
	ds_read_b128 v[218:221], v170 offset:4096
	ds_read_b128 v[222:225], v170 offset:5120
	ds_read_b128 v[226:229], v170 offset:6144
	ds_read_b128 v[230:233], v170 offset:7168
	global_load_lds_dwordx4 v[176:177], off
	v_lshl_add_u64 v[176:177], s[26:27], 0, v[140:141]
	s_add_i32 m0, s53, 0xe000
	s_nop 0
	global_load_lds_dwordx4 v[176:177], off
	s_waitcnt vmcnt(8)
	s_waitcnt lgkmcnt(0)
	s_setprio 1
	s_barrier
	v_mfma_f32_16x16x32_bf16 v[126:129], v[146:149], v[202:205], v[126:129]
	v_mfma_f32_16x16x32_bf16 v[126:129], v[150:153], v[206:209], v[126:129]
	v_mfma_f32_16x16x32_bf16 v[110:113], v[146:149], v[210:213], v[110:113]
	v_mfma_f32_16x16x32_bf16 v[110:113], v[150:153], v[214:217], v[110:113]
	v_mfma_f32_16x16x32_bf16 v[94:97], v[146:149], v[218:221], v[94:97]
	v_mfma_f32_16x16x32_bf16 v[94:97], v[150:153], v[222:225], v[94:97]
	v_mfma_f32_16x16x32_bf16 v[78:81], v[146:149], v[226:229], v[78:81]
	v_mfma_f32_16x16x32_bf16 v[78:81], v[150:153], v[230:233], v[78:81]
	v_mfma_f32_16x16x32_bf16 v[74:77], v[172:175], v[226:229], v[74:77]
	v_mfma_f32_16x16x32_bf16 v[74:77], v[182:185], v[230:233], v[74:77]
	v_mfma_f32_16x16x32_bf16 v[90:93], v[172:175], v[218:221], v[90:93]
	v_mfma_f32_16x16x32_bf16 v[90:93], v[182:185], v[222:225], v[90:93]
	v_mfma_f32_16x16x32_bf16 v[106:109], v[172:175], v[210:213], v[106:109]
	v_mfma_f32_16x16x32_bf16 v[106:109], v[182:185], v[214:217], v[106:109]
	v_mfma_f32_16x16x32_bf16 v[122:125], v[172:175], v[202:205], v[122:125]
	v_mfma_f32_16x16x32_bf16 v[122:125], v[182:185], v[206:209], v[122:125]
	v_mfma_f32_16x16x32_bf16 v[118:121], v[186:189], v[202:205], v[118:121]
	v_mfma_f32_16x16x32_bf16 v[118:121], v[190:193], v[206:209], v[118:121]
	v_mfma_f32_16x16x32_bf16 v[102:105], v[186:189], v[210:213], v[102:105]
	v_mfma_f32_16x16x32_bf16 v[102:105], v[190:193], v[214:217], v[102:105]
	v_mfma_f32_16x16x32_bf16 v[86:89], v[186:189], v[218:221], v[86:89]
	v_mfma_f32_16x16x32_bf16 v[86:89], v[190:193], v[222:225], v[86:89]
	v_mfma_f32_16x16x32_bf16 v[70:73], v[186:189], v[226:229], v[70:73]
	v_mfma_f32_16x16x32_bf16 v[70:73], v[190:193], v[230:233], v[70:73]
	v_mfma_f32_16x16x32_bf16 v[66:69], v[194:197], v[226:229], v[66:69]
	v_mfma_f32_16x16x32_bf16 v[66:69], v[198:201], v[230:233], v[66:69]
	v_mfma_f32_16x16x32_bf16 v[82:85], v[194:197], v[218:221], v[82:85]
	v_mfma_f32_16x16x32_bf16 v[82:85], v[198:201], v[222:225], v[82:85]
	v_mfma_f32_16x16x32_bf16 v[98:101], v[194:197], v[210:213], v[98:101]
	v_mfma_f32_16x16x32_bf16 v[98:101], v[198:201], v[214:217], v[98:101]
	v_mfma_f32_16x16x32_bf16 v[114:117], v[194:197], v[202:205], v[114:117]
	v_mfma_f32_16x16x32_bf16 v[114:117], v[198:201], v[206:209], v[114:117]
	s_barrier
	s_setprio 0
	s_add_i32 s73, s67, s52
	v_lshl_add_u64 v[176:177], s[28:29], 0, v[132:133]
	s_mov_b32 m0, s73
	ds_read_b128 v[202:205], v170 offset:16384
	ds_read_b128 v[206:209], v170 offset:17408
	ds_read_b128 v[210:213], v170 offset:18432
	ds_read_b128 v[214:217], v170 offset:19456
	ds_read_b128 v[218:221], v170 offset:20480
	ds_read_b128 v[222:225], v170 offset:21504
	ds_read_b128 v[226:229], v170 offset:22528
	ds_read_b128 v[230:233], v170 offset:23552
	global_load_lds_dwordx4 v[176:177], off
	s_add_i32 m0, s73, 0x2000
	s_add_u32 s76, s28, 0x20000
	v_lshl_add_u64 v[234:235], s[28:29], 0, v[136:137]
	s_addc_u32 s77, s29, 0
	s_add_i32 s73, s68, s52
	global_load_lds_dwordx4 v[234:235], off
	v_lshl_add_u64 v[236:237], s[76:77], 0, v[132:133]
	s_mov_b32 m0, s73
	v_lshl_add_u64 v[238:239], s[30:31], 0, v[134:135]
	global_load_lds_dwordx4 v[236:237], off
	v_lshl_add_u64 v[236:237], s[76:77], 0, v[136:137]
	s_add_i32 m0, s73, 0x2000
	s_nop 0
	global_load_lds_dwordx4 v[236:237], off
	v_lshl_add_u64 v[236:237], s[30:31], 0, v[130:131]
	s_mov_b32 m0, s53
	s_nop 0
	global_load_lds_dwordx4 v[236:237], off
	s_mov_b32 m0, s54
	s_nop 0
	global_load_lds_dwordx4 v[238:239], off
	s_waitcnt vmcnt(8)
	s_waitcnt lgkmcnt(0)
	s_setprio 1
	s_barrier
	v_mfma_f32_16x16x32_bf16 v[62:65], v[146:149], v[202:205], v[62:65]
	v_mfma_f32_16x16x32_bf16 v[62:65], v[150:153], v[206:209], v[62:65]
	v_mfma_f32_16x16x32_bf16 v[46:49], v[146:149], v[210:213], v[46:49]
	v_mfma_f32_16x16x32_bf16 v[46:49], v[150:153], v[214:217], v[46:49]
	v_mfma_f32_16x16x32_bf16 v[30:33], v[146:149], v[218:221], v[30:33]
	v_mfma_f32_16x16x32_bf16 v[30:33], v[150:153], v[222:225], v[30:33]
	v_mfma_f32_16x16x32_bf16 v[14:17], v[146:149], v[226:229], v[14:17]
	v_mfma_f32_16x16x32_bf16 v[14:17], v[150:153], v[230:233], v[14:17]
	v_mfma_f32_16x16x32_bf16 v[10:13], v[172:175], v[226:229], v[10:13]
	v_mfma_f32_16x16x32_bf16 v[10:13], v[182:185], v[230:233], v[10:13]
	v_mfma_f32_16x16x32_bf16 v[26:29], v[172:175], v[218:221], v[26:29]
	v_mfma_f32_16x16x32_bf16 v[26:29], v[182:185], v[222:225], v[26:29]
	v_mfma_f32_16x16x32_bf16 v[42:45], v[172:175], v[210:213], v[42:45]
	v_mfma_f32_16x16x32_bf16 v[42:45], v[182:185], v[214:217], v[42:45]
	v_mfma_f32_16x16x32_bf16 v[58:61], v[172:175], v[202:205], v[58:61]
	v_mfma_f32_16x16x32_bf16 v[58:61], v[182:185], v[206:209], v[58:61]
	v_mfma_f32_16x16x32_bf16 v[54:57], v[186:189], v[202:205], v[54:57]
	v_mfma_f32_16x16x32_bf16 v[54:57], v[190:193], v[206:209], v[54:57]
	v_mfma_f32_16x16x32_bf16 v[38:41], v[186:189], v[210:213], v[38:41]
	v_mfma_f32_16x16x32_bf16 v[38:41], v[190:193], v[214:217], v[38:41]
	v_mfma_f32_16x16x32_bf16 v[22:25], v[186:189], v[218:221], v[22:25]
	v_mfma_f32_16x16x32_bf16 v[22:25], v[190:193], v[222:225], v[22:25]
	v_mfma_f32_16x16x32_bf16 v[6:9], v[186:189], v[226:229], v[6:9]
	v_mfma_f32_16x16x32_bf16 v[6:9], v[190:193], v[230:233], v[6:9]
	v_mfma_f32_16x16x32_bf16 v[2:5], v[194:197], v[226:229], v[2:5]
	v_mfma_f32_16x16x32_bf16 v[2:5], v[198:201], v[230:233], v[2:5]
	v_mfma_f32_16x16x32_bf16 v[18:21], v[194:197], v[218:221], v[18:21]
	v_mfma_f32_16x16x32_bf16 v[18:21], v[198:201], v[222:225], v[18:21]
	v_mfma_f32_16x16x32_bf16 v[34:37], v[194:197], v[210:213], v[34:37]
	v_mfma_f32_16x16x32_bf16 v[34:37], v[198:201], v[214:217], v[34:37]
	v_mfma_f32_16x16x32_bf16 v[50:53], v[194:197], v[202:205], v[50:53]
	v_mfma_f32_16x16x32_bf16 v[50:53], v[198:201], v[206:209], v[50:53]
	s_barrier
	s_setprio 0
	s_add_i32 s73, 0, 0x18000
	v_add_u32_e32 v179, s73, v162
	s_add_i32 s76, 0, 0x1c000
	ds_read_b128 v[146:149], v179
	ds_read_b128 v[150:153], v179 offset:1024
	ds_read_b128 v[172:175], v179 offset:2048
	ds_read_b128 v[182:185], v179 offset:3072
	v_add_u32_e32 v179, s76, v162
	ds_read_b128 v[186:189], v179
	ds_read_b128 v[190:193], v179 offset:1024
	ds_read_b128 v[194:197], v179 offset:2048
	ds_read_b128 v[198:201], v179 offset:3072
	s_add_u32 s30, s30, 0x40000
	s_addc_u32 s31, s31, 0
	s_mov_b32 m0, s55
	v_lshl_add_u64 v[240:241], s[30:31], 0, v[130:131]
	ds_read_b128 v[202:205], v170 offset:32768
	ds_read_b128 v[206:209], v170 offset:33792
	ds_read_b128 v[210:213], v170 offset:34816
	ds_read_b128 v[214:217], v170 offset:35840
	ds_read_b128 v[218:221], v170 offset:36864
	ds_read_b128 v[222:225], v170 offset:37888
	ds_read_b128 v[226:229], v170 offset:38912
	ds_read_b128 v[230:233], v170 offset:39936
	global_load_lds_dwordx4 v[240:241], off
	v_lshl_add_u64 v[240:241], s[30:31], 0, v[134:135]
	s_mov_b32 m0, s56
	s_nop 0
	global_load_lds_dwordx4 v[240:241], off
	s_waitcnt vmcnt(8)
	s_waitcnt lgkmcnt(0)
	s_setprio 1
	s_barrier
	v_mfma_f32_16x16x32_bf16 v[126:129], v[146:149], v[202:205], v[126:129]
	v_mfma_f32_16x16x32_bf16 v[126:129], v[150:153], v[206:209], v[126:129]
	v_mfma_f32_16x16x32_bf16 v[110:113], v[146:149], v[210:213], v[110:113]
	v_mfma_f32_16x16x32_bf16 v[110:113], v[150:153], v[214:217], v[110:113]
	v_mfma_f32_16x16x32_bf16 v[94:97], v[146:149], v[218:221], v[94:97]
	v_mfma_f32_16x16x32_bf16 v[94:97], v[150:153], v[222:225], v[94:97]
	v_mfma_f32_16x16x32_bf16 v[78:81], v[146:149], v[226:229], v[78:81]
	v_mfma_f32_16x16x32_bf16 v[78:81], v[150:153], v[230:233], v[78:81]
	v_mfma_f32_16x16x32_bf16 v[74:77], v[172:175], v[226:229], v[74:77]
	v_mfma_f32_16x16x32_bf16 v[74:77], v[182:185], v[230:233], v[74:77]
	v_mfma_f32_16x16x32_bf16 v[90:93], v[172:175], v[218:221], v[90:93]
	v_mfma_f32_16x16x32_bf16 v[90:93], v[182:185], v[222:225], v[90:93]
	v_mfma_f32_16x16x32_bf16 v[106:109], v[172:175], v[210:213], v[106:109]
	v_mfma_f32_16x16x32_bf16 v[106:109], v[182:185], v[214:217], v[106:109]
	v_mfma_f32_16x16x32_bf16 v[122:125], v[172:175], v[202:205], v[122:125]
	v_mfma_f32_16x16x32_bf16 v[122:125], v[182:185], v[206:209], v[122:125]
	v_mfma_f32_16x16x32_bf16 v[118:121], v[186:189], v[202:205], v[118:121]
	v_mfma_f32_16x16x32_bf16 v[118:121], v[190:193], v[206:209], v[118:121]
	v_mfma_f32_16x16x32_bf16 v[102:105], v[186:189], v[210:213], v[102:105]
	v_mfma_f32_16x16x32_bf16 v[102:105], v[190:193], v[214:217], v[102:105]
	v_mfma_f32_16x16x32_bf16 v[86:89], v[186:189], v[218:221], v[86:89]
	v_mfma_f32_16x16x32_bf16 v[86:89], v[190:193], v[222:225], v[86:89]
	v_mfma_f32_16x16x32_bf16 v[70:73], v[186:189], v[226:229], v[70:73]
	v_mfma_f32_16x16x32_bf16 v[70:73], v[190:193], v[230:233], v[70:73]
	v_mfma_f32_16x16x32_bf16 v[66:69], v[194:197], v[226:229], v[66:69]
	v_mfma_f32_16x16x32_bf16 v[66:69], v[198:201], v[230:233], v[66:69]
	v_mfma_f32_16x16x32_bf16 v[82:85], v[194:197], v[218:221], v[82:85]
	v_mfma_f32_16x16x32_bf16 v[82:85], v[198:201], v[222:225], v[82:85]
	v_mfma_f32_16x16x32_bf16 v[98:101], v[194:197], v[210:213], v[98:101]
	v_mfma_f32_16x16x32_bf16 v[98:101], v[198:201], v[214:217], v[98:101]
	v_mfma_f32_16x16x32_bf16 v[114:117], v[194:197], v[202:205], v[114:117]
	v_mfma_f32_16x16x32_bf16 v[114:117], v[198:201], v[206:209], v[114:117]
	s_barrier
	s_setprio 0
	s_add_i32 s30, s73, s52
	v_lshl_add_u64 v[176:177], v[176:177], 0, s[12:13]
	s_mov_b32 m0, s30
	ds_read_b128 v[202:205], v170 offset:49152
	ds_read_b128 v[206:209], v170 offset:50176
	ds_read_b128 v[210:213], v170 offset:51200
	ds_read_b128 v[214:217], v170 offset:52224
	ds_read_b128 v[218:221], v170 offset:53248
	ds_read_b128 v[222:225], v170 offset:54272
	ds_read_b128 v[226:229], v170 offset:55296
	ds_read_b128 v[230:233], v170 offset:56320
	global_load_lds_dwordx4 v[176:177], off
	s_add_i32 m0, s30, 0x2000
	s_add_u32 s28, s28, 0x20080
	v_lshl_add_u64 v[176:177], v[234:235], 0, s[12:13]
	s_addc_u32 s29, s29, 0
	s_add_i32 s30, s76, s52
	global_load_lds_dwordx4 v[176:177], off
	v_lshl_add_u64 v[176:177], s[28:29], 0, v[132:133]
	s_mov_b32 m0, s30
	s_nop 0
	global_load_lds_dwordx4 v[176:177], off
	v_lshl_add_u64 v[176:177], s[28:29], 0, v[136:137]
	s_add_i32 m0, s30, 0x2000
	s_nop 0
	global_load_lds_dwordx4 v[176:177], off
	v_lshl_add_u64 v[176:177], v[236:237], 0, s[12:13]
	s_mov_b32 m0, s59
	s_nop 0
	global_load_lds_dwordx4 v[176:177], off
	v_lshl_add_u64 v[176:177], v[238:239], 0, s[12:13]
	s_mov_b32 m0, s60
	s_nop 0
	global_load_lds_dwordx4 v[176:177], off
	s_waitcnt vmcnt(8)
	s_waitcnt lgkmcnt(0)
	s_setprio 1
	s_barrier
	v_mfma_f32_16x16x32_bf16 v[62:65], v[146:149], v[202:205], v[62:65]
	v_mfma_f32_16x16x32_bf16 v[62:65], v[150:153], v[206:209], v[62:65]
	v_mfma_f32_16x16x32_bf16 v[46:49], v[146:149], v[210:213], v[46:49]
	v_mfma_f32_16x16x32_bf16 v[46:49], v[150:153], v[214:217], v[46:49]
	v_mfma_f32_16x16x32_bf16 v[30:33], v[146:149], v[218:221], v[30:33]
	v_mfma_f32_16x16x32_bf16 v[30:33], v[150:153], v[222:225], v[30:33]
	v_mfma_f32_16x16x32_bf16 v[14:17], v[146:149], v[226:229], v[14:17]
	v_mfma_f32_16x16x32_bf16 v[14:17], v[150:153], v[230:233], v[14:17]
	v_mfma_f32_16x16x32_bf16 v[10:13], v[172:175], v[226:229], v[10:13]
	v_mfma_f32_16x16x32_bf16 v[10:13], v[182:185], v[230:233], v[10:13]
	v_mfma_f32_16x16x32_bf16 v[26:29], v[172:175], v[218:221], v[26:29]
	v_mfma_f32_16x16x32_bf16 v[26:29], v[182:185], v[222:225], v[26:29]
	v_mfma_f32_16x16x32_bf16 v[42:45], v[172:175], v[210:213], v[42:45]
	v_mfma_f32_16x16x32_bf16 v[42:45], v[182:185], v[214:217], v[42:45]
	v_mfma_f32_16x16x32_bf16 v[58:61], v[172:175], v[202:205], v[58:61]
	v_mfma_f32_16x16x32_bf16 v[58:61], v[182:185], v[206:209], v[58:61]
	v_mfma_f32_16x16x32_bf16 v[54:57], v[186:189], v[202:205], v[54:57]
	v_mfma_f32_16x16x32_bf16 v[54:57], v[190:193], v[206:209], v[54:57]
	v_mfma_f32_16x16x32_bf16 v[38:41], v[186:189], v[210:213], v[38:41]
	v_mfma_f32_16x16x32_bf16 v[38:41], v[190:193], v[214:217], v[38:41]
	v_mfma_f32_16x16x32_bf16 v[22:25], v[186:189], v[218:221], v[22:25]
	v_mfma_f32_16x16x32_bf16 v[22:25], v[190:193], v[222:225], v[22:25]
	v_mfma_f32_16x16x32_bf16 v[6:9], v[186:189], v[226:229], v[6:9]
	v_mfma_f32_16x16x32_bf16 v[6:9], v[190:193], v[230:233], v[6:9]
	v_mfma_f32_16x16x32_bf16 v[2:5], v[194:197], v[226:229], v[2:5]
	v_mfma_f32_16x16x32_bf16 v[2:5], v[198:201], v[230:233], v[2:5]
	v_mfma_f32_16x16x32_bf16 v[18:21], v[194:197], v[218:221], v[18:21]
	v_mfma_f32_16x16x32_bf16 v[18:21], v[198:201], v[222:225], v[18:21]
	v_mfma_f32_16x16x32_bf16 v[34:37], v[194:197], v[210:213], v[34:37]
	v_mfma_f32_16x16x32_bf16 v[34:37], v[198:201], v[214:217], v[34:37]
	v_mfma_f32_16x16x32_bf16 v[50:53], v[194:197], v[202:205], v[50:53]
	v_mfma_f32_16x16x32_bf16 v[50:53], v[198:201], v[206:209], v[50:53]
	s_barrier
	s_setprio 0
	s_add_i32 s72, s72, 2
	s_add_u32 s26, s26, 0x100
	s_addc_u32 s27, s27, 0
	s_add_u32 s70, s70, 0x100
	s_addc_u32 s71, s71, 0
	s_cmp_gt_u32 s72, 5
	s_cbranch_scc0 .LBB0_2098
	s_and_b64 vcc, exec, s[14:15]
	s_cbranch_vccz .LBB0_2101
	s_barrier

.LBB0_2146:
	ds_read_b128 v[146:149], v1
	ds_read_b128 v[156:159], v1 offset:1024
	ds_read_b128 v[160:163], v1 offset:2048
	ds_read_b128 v[164:167], v1 offset:3072
	ds_read_b128 v[168:171], v153
	ds_read_b128 v[172:175], v153 offset:1024
	ds_read_b128 v[182:185], v153 offset:2048
	ds_read_b128 v[186:189], v153 offset:3072
	s_add_u32 s26, s22, 0xfffc0080
	s_addc_u32 s27, s23, -1
	s_cmp_eq_u32 s71, 4
	s_cselect_b32 s29, s15, s27
	s_cselect_b32 s28, s67, s26
	s_cselect_b32 s27, s13, s70
	s_cselect_b32 s26, s68, s69
	v_lshl_add_u64 v[176:177], s[22:23], 0, v[138:139]
	s_add_i32 m0, s21, 0xc000
	ds_read_b128 v[190:193], v154
	ds_read_b128 v[194:197], v154 offset:1024
	ds_read_b128 v[198:201], v154 offset:2048
	ds_read_b128 v[202:205], v154 offset:3072
	ds_read_b128 v[206:209], v154 offset:4096
	ds_read_b128 v[210:213], v154 offset:5120
	ds_read_b128 v[214:217], v154 offset:6144
	ds_read_b128 v[218:221], v154 offset:7168
	global_load_lds_dwordx4 v[176:177], off
	v_lshl_add_u64 v[176:177], s[22:23], 0, v[140:141]
	s_add_i32 m0, s21, 0xe000
	s_nop 0
	global_load_lds_dwordx4 v[176:177], off
	s_waitcnt vmcnt(8)
	s_waitcnt lgkmcnt(0)
	s_setprio 1
	s_barrier
	v_mfma_f32_16x16x32_bf16 v[126:129], v[146:149], v[190:193], v[126:129]
	v_mfma_f32_16x16x32_bf16 v[126:129], v[156:159], v[194:197], v[126:129]
	v_mfma_f32_16x16x32_bf16 v[110:113], v[146:149], v[198:201], v[110:113]
	v_mfma_f32_16x16x32_bf16 v[110:113], v[156:159], v[202:205], v[110:113]
	v_mfma_f32_16x16x32_bf16 v[94:97], v[146:149], v[206:209], v[94:97]
	v_mfma_f32_16x16x32_bf16 v[94:97], v[156:159], v[210:213], v[94:97]
	v_mfma_f32_16x16x32_bf16 v[78:81], v[146:149], v[214:217], v[78:81]
	v_mfma_f32_16x16x32_bf16 v[78:81], v[156:159], v[218:221], v[78:81]
	v_mfma_f32_16x16x32_bf16 v[74:77], v[160:163], v[214:217], v[74:77]
	v_mfma_f32_16x16x32_bf16 v[74:77], v[164:167], v[218:221], v[74:77]
	v_mfma_f32_16x16x32_bf16 v[90:93], v[160:163], v[206:209], v[90:93]
	v_mfma_f32_16x16x32_bf16 v[90:93], v[164:167], v[210:213], v[90:93]
	v_mfma_f32_16x16x32_bf16 v[106:109], v[160:163], v[198:201], v[106:109]
	v_mfma_f32_16x16x32_bf16 v[106:109], v[164:167], v[202:205], v[106:109]
	v_mfma_f32_16x16x32_bf16 v[122:125], v[160:163], v[190:193], v[122:125]
	v_mfma_f32_16x16x32_bf16 v[122:125], v[164:167], v[194:197], v[122:125]
	v_mfma_f32_16x16x32_bf16 v[118:121], v[168:171], v[190:193], v[118:121]
	v_mfma_f32_16x16x32_bf16 v[118:121], v[172:175], v[194:197], v[118:121]
	v_mfma_f32_16x16x32_bf16 v[102:105], v[168:171], v[198:201], v[102:105]
	v_mfma_f32_16x16x32_bf16 v[102:105], v[172:175], v[202:205], v[102:105]
	v_mfma_f32_16x16x32_bf16 v[86:89], v[168:171], v[206:209], v[86:89]
	v_mfma_f32_16x16x32_bf16 v[86:89], v[172:175], v[210:213], v[86:89]
	v_mfma_f32_16x16x32_bf16 v[70:73], v[168:171], v[214:217], v[70:73]
	v_mfma_f32_16x16x32_bf16 v[70:73], v[172:175], v[218:221], v[70:73]
	v_mfma_f32_16x16x32_bf16 v[66:69], v[182:185], v[214:217], v[66:69]
	v_mfma_f32_16x16x32_bf16 v[66:69], v[186:189], v[218:221], v[66:69]
	v_mfma_f32_16x16x32_bf16 v[82:85], v[182:185], v[206:209], v[82:85]
	v_mfma_f32_16x16x32_bf16 v[82:85], v[186:189], v[210:213], v[82:85]
	v_mfma_f32_16x16x32_bf16 v[98:101], v[182:185], v[198:201], v[98:101]
	v_mfma_f32_16x16x32_bf16 v[98:101], v[186:189], v[202:205], v[98:101]
	v_mfma_f32_16x16x32_bf16 v[114:117], v[182:185], v[190:193], v[114:117]
	v_mfma_f32_16x16x32_bf16 v[114:117], v[186:189], v[194:197], v[114:117]
	s_barrier
	s_setprio 0
	s_add_i32 s72, s62, s37
	v_lshl_add_u64 v[176:177], s[26:27], 0, v[132:133]
	s_mov_b32 m0, s72
	ds_read_b128 v[190:193], v154 offset:16384
	ds_read_b128 v[194:197], v154 offset:17408
	ds_read_b128 v[198:201], v154 offset:18432
	ds_read_b128 v[202:205], v154 offset:19456
	ds_read_b128 v[206:209], v154 offset:20480
	ds_read_b128 v[210:213], v154 offset:21504
	ds_read_b128 v[214:217], v154 offset:22528
	ds_read_b128 v[218:221], v154 offset:23552
	global_load_lds_dwordx4 v[176:177], off
	s_add_i32 m0, s72, 0x2000
	s_add_u32 s72, s26, 0x20000
	v_lshl_add_u64 v[222:223], s[26:27], 0, v[136:137]
	s_addc_u32 s73, s27, 0
	s_add_i32 s76, s63, s37
	global_load_lds_dwordx4 v[222:223], off
	v_lshl_add_u64 v[224:225], s[72:73], 0, v[132:133]
	s_mov_b32 m0, s76
	v_lshl_add_u64 v[226:227], s[28:29], 0, v[134:135]
	global_load_lds_dwordx4 v[224:225], off
	v_lshl_add_u64 v[224:225], s[72:73], 0, v[136:137]
	s_add_i32 m0, s76, 0x2000
	s_nop 0
	global_load_lds_dwordx4 v[224:225], off
	v_lshl_add_u64 v[224:225], s[28:29], 0, v[130:131]
	s_mov_b32 m0, s21
	s_nop 0
	global_load_lds_dwordx4 v[224:225], off
	s_mov_b32 m0, s54
	s_nop 0
	global_load_lds_dwordx4 v[226:227], off
	s_waitcnt vmcnt(8)
	s_waitcnt lgkmcnt(0)
	s_setprio 1
	s_barrier
	v_mfma_f32_16x16x32_bf16 v[62:65], v[146:149], v[190:193], v[62:65]
	v_mfma_f32_16x16x32_bf16 v[62:65], v[156:159], v[194:197], v[62:65]
	v_mfma_f32_16x16x32_bf16 v[46:49], v[146:149], v[198:201], v[46:49]
	v_mfma_f32_16x16x32_bf16 v[46:49], v[156:159], v[202:205], v[46:49]
	v_mfma_f32_16x16x32_bf16 v[30:33], v[146:149], v[206:209], v[30:33]
	v_mfma_f32_16x16x32_bf16 v[30:33], v[156:159], v[210:213], v[30:33]
	v_mfma_f32_16x16x32_bf16 v[14:17], v[146:149], v[214:217], v[14:17]
	v_mfma_f32_16x16x32_bf16 v[14:17], v[156:159], v[218:221], v[14:17]
	v_mfma_f32_16x16x32_bf16 v[10:13], v[160:163], v[214:217], v[10:13]
	v_mfma_f32_16x16x32_bf16 v[10:13], v[164:167], v[218:221], v[10:13]
	v_mfma_f32_16x16x32_bf16 v[26:29], v[160:163], v[206:209], v[26:29]
	v_mfma_f32_16x16x32_bf16 v[26:29], v[164:167], v[210:213], v[26:29]
	v_mfma_f32_16x16x32_bf16 v[42:45], v[160:163], v[198:201], v[42:45]
	v_mfma_f32_16x16x32_bf16 v[42:45], v[164:167], v[202:205], v[42:45]
	v_mfma_f32_16x16x32_bf16 v[58:61], v[160:163], v[190:193], v[58:61]
	v_mfma_f32_16x16x32_bf16 v[58:61], v[164:167], v[194:197], v[58:61]
	v_mfma_f32_16x16x32_bf16 v[54:57], v[168:171], v[190:193], v[54:57]
	v_mfma_f32_16x16x32_bf16 v[54:57], v[172:175], v[194:197], v[54:57]
	v_mfma_f32_16x16x32_bf16 v[38:41], v[168:171], v[198:201], v[38:41]
	v_mfma_f32_16x16x32_bf16 v[38:41], v[172:175], v[202:205], v[38:41]
	v_mfma_f32_16x16x32_bf16 v[22:25], v[168:171], v[206:209], v[22:25]
	v_mfma_f32_16x16x32_bf16 v[22:25], v[172:175], v[210:213], v[22:25]
	v_mfma_f32_16x16x32_bf16 v[6:9], v[168:171], v[214:217], v[6:9]
	v_mfma_f32_16x16x32_bf16 v[6:9], v[172:175], v[218:221], v[6:9]
	v_mfma_f32_16x16x32_bf16 v[2:5], v[182:185], v[214:217], v[2:5]
	v_mfma_f32_16x16x32_bf16 v[2:5], v[186:189], v[218:221], v[2:5]
	v_mfma_f32_16x16x32_bf16 v[18:21], v[182:185], v[206:209], v[18:21]
	v_mfma_f32_16x16x32_bf16 v[18:21], v[186:189], v[210:213], v[18:21]
	v_mfma_f32_16x16x32_bf16 v[34:37], v[182:185], v[198:201], v[34:37]
	v_mfma_f32_16x16x32_bf16 v[34:37], v[186:189], v[202:205], v[34:37]
	v_mfma_f32_16x16x32_bf16 v[50:53], v[182:185], v[190:193], v[50:53]
	v_mfma_f32_16x16x32_bf16 v[50:53], v[186:189], v[194:197], v[50:53]
	s_barrier
	s_setprio 0
	s_add_i32 s72, 0, 0x18000
	s_add_i32 s73, 0, 0x1c000
	v_add_u32_e32 v164, s72, v151
	v_add_u32_e32 v179, s73, v151
	ds_read_b128 v[146:149], v164
	ds_read_b128 v[156:159], v164 offset:1024
	ds_read_b128 v[160:163], v164 offset:2048
	ds_read_b128 v[164:167], v164 offset:3072
	ds_read_b128 v[168:171], v179
	ds_read_b128 v[172:175], v179 offset:1024
	ds_read_b128 v[182:185], v179 offset:2048
	ds_read_b128 v[186:189], v179 offset:3072
	s_add_u32 s28, s28, 0x40000
	s_addc_u32 s29, s29, 0
	s_mov_b32 m0, s55
	v_lshl_add_u64 v[228:229], s[28:29], 0, v[130:131]
	ds_read_b128 v[190:193], v154 offset:32768
	ds_read_b128 v[194:197], v154 offset:33792
	ds_read_b128 v[198:201], v154 offset:34816
	ds_read_b128 v[202:205], v154 offset:35840
	ds_read_b128 v[206:209], v154 offset:36864
	ds_read_b128 v[210:213], v154 offset:37888
	ds_read_b128 v[214:217], v154 offset:38912
	ds_read_b128 v[218:221], v154 offset:39936
	global_load_lds_dwordx4 v[228:229], off
	v_lshl_add_u64 v[228:229], s[28:29], 0, v[134:135]
	s_mov_b32 m0, s56
	s_nop 0
	global_load_lds_dwordx4 v[228:229], off
	s_waitcnt vmcnt(8)
	s_waitcnt lgkmcnt(0)
	s_setprio 1
	s_barrier
	v_mfma_f32_16x16x32_bf16 v[126:129], v[146:149], v[190:193], v[126:129]
	v_mfma_f32_16x16x32_bf16 v[126:129], v[156:159], v[194:197], v[126:129]
	v_mfma_f32_16x16x32_bf16 v[110:113], v[146:149], v[198:201], v[110:113]
	v_mfma_f32_16x16x32_bf16 v[110:113], v[156:159], v[202:205], v[110:113]
	v_mfma_f32_16x16x32_bf16 v[94:97], v[146:149], v[206:209], v[94:97]
	v_mfma_f32_16x16x32_bf16 v[94:97], v[156:159], v[210:213], v[94:97]
	v_mfma_f32_16x16x32_bf16 v[78:81], v[146:149], v[214:217], v[78:81]
	v_mfma_f32_16x16x32_bf16 v[78:81], v[156:159], v[218:221], v[78:81]
	v_mfma_f32_16x16x32_bf16 v[74:77], v[160:163], v[214:217], v[74:77]
	v_mfma_f32_16x16x32_bf16 v[74:77], v[164:167], v[218:221], v[74:77]
	v_mfma_f32_16x16x32_bf16 v[90:93], v[160:163], v[206:209], v[90:93]
	v_mfma_f32_16x16x32_bf16 v[90:93], v[164:167], v[210:213], v[90:93]
	v_mfma_f32_16x16x32_bf16 v[106:109], v[160:163], v[198:201], v[106:109]
	v_mfma_f32_16x16x32_bf16 v[106:109], v[164:167], v[202:205], v[106:109]
	v_mfma_f32_16x16x32_bf16 v[122:125], v[160:163], v[190:193], v[122:125]
	v_mfma_f32_16x16x32_bf16 v[122:125], v[164:167], v[194:197], v[122:125]
	v_mfma_f32_16x16x32_bf16 v[118:121], v[168:171], v[190:193], v[118:121]
	v_mfma_f32_16x16x32_bf16 v[118:121], v[172:175], v[194:197], v[118:121]
	v_mfma_f32_16x16x32_bf16 v[102:105], v[168:171], v[198:201], v[102:105]
	v_mfma_f32_16x16x32_bf16 v[102:105], v[172:175], v[202:205], v[102:105]
	v_mfma_f32_16x16x32_bf16 v[86:89], v[168:171], v[206:209], v[86:89]
	v_mfma_f32_16x16x32_bf16 v[86:89], v[172:175], v[210:213], v[86:89]
	v_mfma_f32_16x16x32_bf16 v[70:73], v[168:171], v[214:217], v[70:73]
	v_mfma_f32_16x16x32_bf16 v[70:73], v[172:175], v[218:221], v[70:73]
	v_mfma_f32_16x16x32_bf16 v[66:69], v[182:185], v[214:217], v[66:69]
	v_mfma_f32_16x16x32_bf16 v[66:69], v[186:189], v[218:221], v[66:69]
	v_mfma_f32_16x16x32_bf16 v[82:85], v[182:185], v[206:209], v[82:85]
	v_mfma_f32_16x16x32_bf16 v[82:85], v[186:189], v[210:213], v[82:85]
	v_mfma_f32_16x16x32_bf16 v[98:101], v[182:185], v[198:201], v[98:101]
	v_mfma_f32_16x16x32_bf16 v[98:101], v[186:189], v[202:205], v[98:101]
	v_mfma_f32_16x16x32_bf16 v[114:117], v[182:185], v[190:193], v[114:117]
	v_mfma_f32_16x16x32_bf16 v[114:117], v[186:189], v[194:197], v[114:117]
	s_barrier
	s_setprio 0
	s_add_i32 s28, s72, s37
	v_lshl_add_u64 v[176:177], v[176:177], 0, s[6:7]
	s_mov_b32 m0, s28
	ds_read_b128 v[190:193], v154 offset:49152
	ds_read_b128 v[194:197], v154 offset:50176
	ds_read_b128 v[198:201], v154 offset:51200
	ds_read_b128 v[202:205], v154 offset:52224
	ds_read_b128 v[206:209], v154 offset:53248
	ds_read_b128 v[210:213], v154 offset:54272
	ds_read_b128 v[214:217], v154 offset:55296
	ds_read_b128 v[218:221], v154 offset:56320
	global_load_lds_dwordx4 v[176:177], off
	s_add_i32 m0, s28, 0x2000
	s_add_u32 s26, s26, 0x20080
	v_lshl_add_u64 v[176:177], v[222:223], 0, s[6:7]
	s_addc_u32 s27, s27, 0
	s_add_i32 s28, s73, s37
	global_load_lds_dwordx4 v[176:177], off
	v_lshl_add_u64 v[176:177], s[26:27], 0, v[132:133]
	s_mov_b32 m0, s28
	s_nop 0
	global_load_lds_dwordx4 v[176:177], off
	v_lshl_add_u64 v[176:177], s[26:27], 0, v[136:137]
	s_add_i32 m0, s28, 0x2000
	s_nop 0
	global_load_lds_dwordx4 v[176:177], off
	v_lshl_add_u64 v[176:177], v[224:225], 0, s[6:7]
	s_mov_b32 m0, s58
	s_nop 0
	global_load_lds_dwordx4 v[176:177], off
	v_lshl_add_u64 v[176:177], v[226:227], 0, s[6:7]
	s_mov_b32 m0, s59
	s_nop 0
	global_load_lds_dwordx4 v[176:177], off
	s_waitcnt vmcnt(8)
	s_waitcnt lgkmcnt(0)
	s_setprio 1
	s_barrier
	v_mfma_f32_16x16x32_bf16 v[62:65], v[146:149], v[190:193], v[62:65]
	v_mfma_f32_16x16x32_bf16 v[62:65], v[156:159], v[194:197], v[62:65]
	v_mfma_f32_16x16x32_bf16 v[46:49], v[146:149], v[198:201], v[46:49]
	v_mfma_f32_16x16x32_bf16 v[46:49], v[156:159], v[202:205], v[46:49]
	v_mfma_f32_16x16x32_bf16 v[30:33], v[146:149], v[206:209], v[30:33]
	v_mfma_f32_16x16x32_bf16 v[30:33], v[156:159], v[210:213], v[30:33]
	v_mfma_f32_16x16x32_bf16 v[14:17], v[146:149], v[214:217], v[14:17]
	v_mfma_f32_16x16x32_bf16 v[14:17], v[156:159], v[218:221], v[14:17]
	v_mfma_f32_16x16x32_bf16 v[10:13], v[160:163], v[214:217], v[10:13]
	v_mfma_f32_16x16x32_bf16 v[10:13], v[164:167], v[218:221], v[10:13]
	v_mfma_f32_16x16x32_bf16 v[26:29], v[160:163], v[206:209], v[26:29]
	v_mfma_f32_16x16x32_bf16 v[26:29], v[164:167], v[210:213], v[26:29]
	v_mfma_f32_16x16x32_bf16 v[42:45], v[160:163], v[198:201], v[42:45]
	v_mfma_f32_16x16x32_bf16 v[42:45], v[164:167], v[202:205], v[42:45]
	v_mfma_f32_16x16x32_bf16 v[58:61], v[160:163], v[190:193], v[58:61]
	v_mfma_f32_16x16x32_bf16 v[58:61], v[164:167], v[194:197], v[58:61]
	v_mfma_f32_16x16x32_bf16 v[54:57], v[168:171], v[190:193], v[54:57]
	v_mfma_f32_16x16x32_bf16 v[54:57], v[172:175], v[194:197], v[54:57]
	v_mfma_f32_16x16x32_bf16 v[38:41], v[168:171], v[198:201], v[38:41]
	v_mfma_f32_16x16x32_bf16 v[38:41], v[172:175], v[202:205], v[38:41]
	v_mfma_f32_16x16x32_bf16 v[22:25], v[168:171], v[206:209], v[22:25]
	v_mfma_f32_16x16x32_bf16 v[22:25], v[172:175], v[210:213], v[22:25]
	v_mfma_f32_16x16x32_bf16 v[6:9], v[168:171], v[214:217], v[6:9]
	v_mfma_f32_16x16x32_bf16 v[6:9], v[172:175], v[218:221], v[6:9]
	v_mfma_f32_16x16x32_bf16 v[2:5], v[182:185], v[214:217], v[2:5]
	v_mfma_f32_16x16x32_bf16 v[2:5], v[186:189], v[218:221], v[2:5]
	v_mfma_f32_16x16x32_bf16 v[18:21], v[182:185], v[206:209], v[18:21]
	v_mfma_f32_16x16x32_bf16 v[18:21], v[186:189], v[210:213], v[18:21]
	v_mfma_f32_16x16x32_bf16 v[34:37], v[182:185], v[198:201], v[34:37]
	v_mfma_f32_16x16x32_bf16 v[34:37], v[186:189], v[202:205], v[34:37]
	v_mfma_f32_16x16x32_bf16 v[50:53], v[182:185], v[190:193], v[50:53]
	v_mfma_f32_16x16x32_bf16 v[50:53], v[186:189], v[194:197], v[50:53]
	s_barrier
	s_setprio 0
	s_add_i32 s71, s71, 2
	s_add_u32 s22, s22, 0x100
	s_addc_u32 s23, s23, 0
	s_add_u32 s69, s69, 0x100
	s_addc_u32 s70, s70, 0
	s_cmp_gt_u32 s71, 5
	s_cbranch_scc0 .LBB0_2146
	s_and_b64 vcc, exec, s[10:11]
	s_cbranch_vccz .LBB0_2149
	s_barrier

.LBB0_2322:
	ds_read_b128 v[144:147], v150
	ds_read_b128 v[154:157], v150 offset:1024
	ds_read_b128 v[158:161], v150 offset:2048
	ds_read_b128 v[162:165], v150 offset:3072
	ds_read_b128 v[166:169], v151
	ds_read_b128 v[170:173], v151 offset:1024
	ds_read_b128 v[174:177], v151 offset:2048
	ds_read_b128 v[182:185], v151 offset:3072
	s_add_i32 s72, s30, 2
	s_add_u32 s31, s28, 0xfff80080
	s_addc_u32 s34, s29, -1
	s_cmp_eq_u32 s17, s30
	s_cselect_b32 s30, s26, s19
	s_cselect_b32 s35, s23, s34
	s_cselect_b32 s34, s22, s31
	s_cselect_b32 s31, s27, s21
	v_lshl_add_u64 v[218:219], s[28:29], 0, v[138:139]
	s_add_i32 m0, s3, 0xc000
	ds_read_b128 v[186:189], v152
	ds_read_b128 v[190:193], v152 offset:1024
	ds_read_b128 v[194:197], v152 offset:2048
	ds_read_b128 v[198:201], v152 offset:3072
	ds_read_b128 v[202:205], v152 offset:4096
	ds_read_b128 v[206:209], v152 offset:5120
	ds_read_b128 v[210:213], v152 offset:6144
	ds_read_b128 v[214:217], v152 offset:7168
	global_load_lds_dwordx4 v[218:219], off
	v_lshl_add_u64 v[218:219], s[28:29], 0, v[140:141]
	s_add_i32 m0, s3, 0xe000
	s_nop 0
	global_load_lds_dwordx4 v[218:219], off
	s_waitcnt vmcnt(8)
	s_waitcnt lgkmcnt(0)
	s_setprio 1
	s_barrier
	v_mfma_f32_16x16x32_bf16 v[126:129], v[144:147], v[186:189], v[126:129]
	v_mfma_f32_16x16x32_bf16 v[126:129], v[154:157], v[190:193], v[126:129]
	v_mfma_f32_16x16x32_bf16 v[118:121], v[144:147], v[194:197], v[118:121]
	v_mfma_f32_16x16x32_bf16 v[118:121], v[154:157], v[198:201], v[118:121]
	v_mfma_f32_16x16x32_bf16 v[106:109], v[144:147], v[202:205], v[106:109]
	v_mfma_f32_16x16x32_bf16 v[106:109], v[154:157], v[206:209], v[106:109]
	v_mfma_f32_16x16x32_bf16 v[90:93], v[144:147], v[210:213], v[90:93]
	v_mfma_f32_16x16x32_bf16 v[90:93], v[154:157], v[214:217], v[90:93]
	v_mfma_f32_16x16x32_bf16 v[82:85], v[158:161], v[210:213], v[82:85]
	v_mfma_f32_16x16x32_bf16 v[82:85], v[162:165], v[214:217], v[82:85]
	v_mfma_f32_16x16x32_bf16 v[98:101], v[158:161], v[202:205], v[98:101]
	v_mfma_f32_16x16x32_bf16 v[98:101], v[162:165], v[206:209], v[98:101]
	v_mfma_f32_16x16x32_bf16 v[114:117], v[158:161], v[194:197], v[114:117]
	v_mfma_f32_16x16x32_bf16 v[114:117], v[162:165], v[198:201], v[114:117]
	v_mfma_f32_16x16x32_bf16 v[122:125], v[158:161], v[186:189], v[122:125]
	v_mfma_f32_16x16x32_bf16 v[122:125], v[162:165], v[190:193], v[122:125]
	v_mfma_f32_16x16x32_bf16 v[110:113], v[166:169], v[186:189], v[110:113]
	v_mfma_f32_16x16x32_bf16 v[110:113], v[170:173], v[190:193], v[110:113]
	v_mfma_f32_16x16x32_bf16 v[94:97], v[166:169], v[194:197], v[94:97]
	v_mfma_f32_16x16x32_bf16 v[94:97], v[170:173], v[198:201], v[94:97]
	v_mfma_f32_16x16x32_bf16 v[78:81], v[166:169], v[202:205], v[78:81]
	v_mfma_f32_16x16x32_bf16 v[78:81], v[170:173], v[206:209], v[78:81]
	v_mfma_f32_16x16x32_bf16 v[70:73], v[166:169], v[210:213], v[70:73]
	v_mfma_f32_16x16x32_bf16 v[70:73], v[170:173], v[214:217], v[70:73]
	v_mfma_f32_16x16x32_bf16 v[66:69], v[174:177], v[210:213], v[66:69]
	v_mfma_f32_16x16x32_bf16 v[66:69], v[182:185], v[214:217], v[66:69]
	v_mfma_f32_16x16x32_bf16 v[74:77], v[174:177], v[202:205], v[74:77]
	v_mfma_f32_16x16x32_bf16 v[74:77], v[182:185], v[206:209], v[74:77]
	v_mfma_f32_16x16x32_bf16 v[86:89], v[174:177], v[194:197], v[86:89]
	v_mfma_f32_16x16x32_bf16 v[86:89], v[182:185], v[198:201], v[86:89]
	v_mfma_f32_16x16x32_bf16 v[102:105], v[174:177], v[186:189], v[102:105]
	v_mfma_f32_16x16x32_bf16 v[102:105], v[182:185], v[190:193], v[102:105]
	s_barrier
	s_setprio 0
	s_add_i32 s73, s63, s52
	v_lshl_add_u64 v[218:219], s[30:31], 0, v[132:133]
	s_mov_b32 m0, s73
	ds_read_b128 v[186:189], v152 offset:16384
	ds_read_b128 v[190:193], v152 offset:17408
	ds_read_b128 v[194:197], v152 offset:18432
	ds_read_b128 v[198:201], v152 offset:19456
	ds_read_b128 v[202:205], v152 offset:20480
	ds_read_b128 v[206:209], v152 offset:21504
	ds_read_b128 v[210:213], v152 offset:22528
	ds_read_b128 v[214:217], v152 offset:23552
	global_load_lds_dwordx4 v[218:219], off
	s_add_i32 m0, s73, 0x2000
	s_add_u32 s76, s30, 0x80000
	v_lshl_add_u64 v[220:221], s[30:31], 0, v[136:137]
	s_addc_u32 s77, s31, 0
	s_add_i32 s73, s66, s52
	global_load_lds_dwordx4 v[220:221], off
	v_lshl_add_u64 v[222:223], s[76:77], 0, v[132:133]
	s_mov_b32 m0, s73
	v_lshl_add_u64 v[224:225], s[34:35], 0, v[134:135]
	global_load_lds_dwordx4 v[222:223], off
	v_lshl_add_u64 v[222:223], s[76:77], 0, v[136:137]
	s_add_i32 m0, s73, 0x2000
	s_nop 0
	global_load_lds_dwordx4 v[222:223], off
	v_lshl_add_u64 v[222:223], s[34:35], 0, v[130:131]
	s_mov_b32 m0, s3
	s_nop 0
	global_load_lds_dwordx4 v[222:223], off
	s_mov_b32 m0, s54
	s_nop 0
	global_load_lds_dwordx4 v[224:225], off
	s_waitcnt vmcnt(8)
	s_waitcnt lgkmcnt(0)
	s_setprio 1
	s_barrier
	v_mfma_f32_16x16x32_bf16 v[62:65], v[144:147], v[186:189], v[62:65]
	v_mfma_f32_16x16x32_bf16 v[62:65], v[154:157], v[190:193], v[62:65]
	v_mfma_f32_16x16x32_bf16 v[54:57], v[144:147], v[194:197], v[54:57]
	v_mfma_f32_16x16x32_bf16 v[54:57], v[154:157], v[198:201], v[54:57]
	v_mfma_f32_16x16x32_bf16 v[42:45], v[144:147], v[202:205], v[42:45]
	v_mfma_f32_16x16x32_bf16 v[42:45], v[154:157], v[206:209], v[42:45]
	v_mfma_f32_16x16x32_bf16 v[26:29], v[144:147], v[210:213], v[26:29]
	v_mfma_f32_16x16x32_bf16 v[26:29], v[154:157], v[214:217], v[26:29]
	v_mfma_f32_16x16x32_bf16 v[18:21], v[158:161], v[210:213], v[18:21]
	v_mfma_f32_16x16x32_bf16 v[18:21], v[162:165], v[214:217], v[18:21]
	v_mfma_f32_16x16x32_bf16 v[34:37], v[158:161], v[202:205], v[34:37]
	v_mfma_f32_16x16x32_bf16 v[34:37], v[162:165], v[206:209], v[34:37]
	v_mfma_f32_16x16x32_bf16 v[50:53], v[158:161], v[194:197], v[50:53]
	v_mfma_f32_16x16x32_bf16 v[50:53], v[162:165], v[198:201], v[50:53]
	v_mfma_f32_16x16x32_bf16 v[58:61], v[158:161], v[186:189], v[58:61]
	v_mfma_f32_16x16x32_bf16 v[58:61], v[162:165], v[190:193], v[58:61]
	v_mfma_f32_16x16x32_bf16 v[46:49], v[166:169], v[186:189], v[46:49]
	v_mfma_f32_16x16x32_bf16 v[46:49], v[170:173], v[190:193], v[46:49]
	v_mfma_f32_16x16x32_bf16 v[30:33], v[166:169], v[194:197], v[30:33]
	v_mfma_f32_16x16x32_bf16 v[30:33], v[170:173], v[198:201], v[30:33]
	v_mfma_f32_16x16x32_bf16 v[14:17], v[166:169], v[202:205], v[14:17]
	v_mfma_f32_16x16x32_bf16 v[14:17], v[170:173], v[206:209], v[14:17]
	v_mfma_f32_16x16x32_bf16 v[6:9], v[166:169], v[210:213], v[6:9]
	v_mfma_f32_16x16x32_bf16 v[6:9], v[170:173], v[214:217], v[6:9]
	v_mfma_f32_16x16x32_bf16 v[2:5], v[174:177], v[210:213], v[2:5]
	v_mfma_f32_16x16x32_bf16 v[2:5], v[182:185], v[214:217], v[2:5]
	v_mfma_f32_16x16x32_bf16 v[10:13], v[174:177], v[202:205], v[10:13]
	v_mfma_f32_16x16x32_bf16 v[10:13], v[182:185], v[206:209], v[10:13]
	v_mfma_f32_16x16x32_bf16 v[22:25], v[174:177], v[194:197], v[22:25]
	v_mfma_f32_16x16x32_bf16 v[22:25], v[182:185], v[198:201], v[22:25]
	v_mfma_f32_16x16x32_bf16 v[38:41], v[174:177], v[186:189], v[38:41]
	v_mfma_f32_16x16x32_bf16 v[38:41], v[182:185], v[190:193], v[38:41]
	s_barrier
	s_setprio 0
	s_add_i32 s73, 0, 0x18000
	v_add_u32_e32 v153, s73, v148
	s_add_i32 s76, 0, 0x1c000
	ds_read_b128 v[144:147], v153
	ds_read_b128 v[154:157], v153 offset:1024
	ds_read_b128 v[158:161], v153 offset:2048
	ds_read_b128 v[162:165], v153 offset:3072
	v_add_u32_e32 v153, s76, v148
	ds_read_b128 v[166:169], v153
	ds_read_b128 v[170:173], v153 offset:1024
	ds_read_b128 v[174:177], v153 offset:2048
	ds_read_b128 v[182:185], v153 offset:3072
	s_add_u32 s34, s34, 0x80000
	s_addc_u32 s35, s35, 0
	s_mov_b32 m0, s55
	v_lshl_add_u64 v[226:227], s[34:35], 0, v[130:131]
	ds_read_b128 v[186:189], v152 offset:32768
	ds_read_b128 v[190:193], v152 offset:33792
	ds_read_b128 v[194:197], v152 offset:34816
	ds_read_b128 v[198:201], v152 offset:35840
	ds_read_b128 v[202:205], v152 offset:36864
	ds_read_b128 v[206:209], v152 offset:37888
	ds_read_b128 v[210:213], v152 offset:38912
	ds_read_b128 v[214:217], v152 offset:39936
	global_load_lds_dwordx4 v[226:227], off
	v_lshl_add_u64 v[226:227], s[34:35], 0, v[134:135]
	s_mov_b32 m0, s56
	s_nop 0
	global_load_lds_dwordx4 v[226:227], off
	s_waitcnt vmcnt(8)
	s_waitcnt lgkmcnt(0)
	s_setprio 1
	s_barrier
	v_mfma_f32_16x16x32_bf16 v[126:129], v[144:147], v[186:189], v[126:129]
	v_mfma_f32_16x16x32_bf16 v[126:129], v[154:157], v[190:193], v[126:129]
	v_mfma_f32_16x16x32_bf16 v[118:121], v[144:147], v[194:197], v[118:121]
	v_mfma_f32_16x16x32_bf16 v[118:121], v[154:157], v[198:201], v[118:121]
	v_mfma_f32_16x16x32_bf16 v[106:109], v[144:147], v[202:205], v[106:109]
	v_mfma_f32_16x16x32_bf16 v[106:109], v[154:157], v[206:209], v[106:109]
	v_mfma_f32_16x16x32_bf16 v[90:93], v[144:147], v[210:213], v[90:93]
	v_mfma_f32_16x16x32_bf16 v[90:93], v[154:157], v[214:217], v[90:93]
	v_mfma_f32_16x16x32_bf16 v[82:85], v[158:161], v[210:213], v[82:85]
	v_mfma_f32_16x16x32_bf16 v[82:85], v[162:165], v[214:217], v[82:85]
	v_mfma_f32_16x16x32_bf16 v[98:101], v[158:161], v[202:205], v[98:101]
	v_mfma_f32_16x16x32_bf16 v[98:101], v[162:165], v[206:209], v[98:101]
	v_mfma_f32_16x16x32_bf16 v[114:117], v[158:161], v[194:197], v[114:117]
	v_mfma_f32_16x16x32_bf16 v[114:117], v[162:165], v[198:201], v[114:117]
	v_mfma_f32_16x16x32_bf16 v[122:125], v[158:161], v[186:189], v[122:125]
	v_mfma_f32_16x16x32_bf16 v[122:125], v[162:165], v[190:193], v[122:125]
	v_mfma_f32_16x16x32_bf16 v[110:113], v[166:169], v[186:189], v[110:113]
	v_mfma_f32_16x16x32_bf16 v[110:113], v[170:173], v[190:193], v[110:113]
	v_mfma_f32_16x16x32_bf16 v[94:97], v[166:169], v[194:197], v[94:97]
	v_mfma_f32_16x16x32_bf16 v[94:97], v[170:173], v[198:201], v[94:97]
	v_mfma_f32_16x16x32_bf16 v[78:81], v[166:169], v[202:205], v[78:81]
	v_mfma_f32_16x16x32_bf16 v[78:81], v[170:173], v[206:209], v[78:81]
	v_mfma_f32_16x16x32_bf16 v[70:73], v[166:169], v[210:213], v[70:73]
	v_mfma_f32_16x16x32_bf16 v[70:73], v[170:173], v[214:217], v[70:73]
	v_mfma_f32_16x16x32_bf16 v[66:69], v[174:177], v[210:213], v[66:69]
	v_mfma_f32_16x16x32_bf16 v[66:69], v[182:185], v[214:217], v[66:69]
	v_mfma_f32_16x16x32_bf16 v[74:77], v[174:177], v[202:205], v[74:77]
	v_mfma_f32_16x16x32_bf16 v[74:77], v[182:185], v[206:209], v[74:77]
	v_mfma_f32_16x16x32_bf16 v[86:89], v[174:177], v[194:197], v[86:89]
	v_mfma_f32_16x16x32_bf16 v[86:89], v[182:185], v[198:201], v[86:89]
	v_mfma_f32_16x16x32_bf16 v[102:105], v[174:177], v[186:189], v[102:105]
	v_mfma_f32_16x16x32_bf16 v[102:105], v[182:185], v[190:193], v[102:105]
	s_barrier
	s_setprio 0
	s_add_i32 s34, s73, s52
	v_lshl_add_u64 v[218:219], v[218:219], 0, s[6:7]
	s_mov_b32 m0, s34
	ds_read_b128 v[186:189], v152 offset:49152
	ds_read_b128 v[190:193], v152 offset:50176
	ds_read_b128 v[194:197], v152 offset:51200
	ds_read_b128 v[198:201], v152 offset:52224
	ds_read_b128 v[202:205], v152 offset:53248
	ds_read_b128 v[206:209], v152 offset:54272
	ds_read_b128 v[210:213], v152 offset:55296
	ds_read_b128 v[214:217], v152 offset:56320
	global_load_lds_dwordx4 v[218:219], off
	s_add_i32 m0, s34, 0x2000
	s_add_u32 s30, s30, 0x80080
	v_lshl_add_u64 v[218:219], v[220:221], 0, s[6:7]
	s_addc_u32 s31, s31, 0
	s_add_i32 s34, s76, s52
	global_load_lds_dwordx4 v[218:219], off
	v_lshl_add_u64 v[218:219], s[30:31], 0, v[132:133]
	s_mov_b32 m0, s34
	s_nop 0
	global_load_lds_dwordx4 v[218:219], off
	v_lshl_add_u64 v[218:219], s[30:31], 0, v[136:137]
	s_add_i32 m0, s34, 0x2000
	s_nop 0
	global_load_lds_dwordx4 v[218:219], off
	v_lshl_add_u64 v[218:219], v[222:223], 0, s[6:7]
	s_mov_b32 m0, s58
	s_nop 0
	global_load_lds_dwordx4 v[218:219], off
	v_lshl_add_u64 v[218:219], v[224:225], 0, s[6:7]
	s_mov_b32 m0, s59
	s_nop 0
	global_load_lds_dwordx4 v[218:219], off
	s_waitcnt vmcnt(8)
	s_waitcnt lgkmcnt(0)
	s_setprio 1
	s_barrier
	v_mfma_f32_16x16x32_bf16 v[62:65], v[144:147], v[186:189], v[62:65]
	v_mfma_f32_16x16x32_bf16 v[62:65], v[154:157], v[190:193], v[62:65]
	v_mfma_f32_16x16x32_bf16 v[54:57], v[144:147], v[194:197], v[54:57]
	v_mfma_f32_16x16x32_bf16 v[54:57], v[154:157], v[198:201], v[54:57]
	v_mfma_f32_16x16x32_bf16 v[42:45], v[144:147], v[202:205], v[42:45]
	v_mfma_f32_16x16x32_bf16 v[42:45], v[154:157], v[206:209], v[42:45]
	v_mfma_f32_16x16x32_bf16 v[26:29], v[144:147], v[210:213], v[26:29]
	v_mfma_f32_16x16x32_bf16 v[26:29], v[154:157], v[214:217], v[26:29]
	v_mfma_f32_16x16x32_bf16 v[18:21], v[158:161], v[210:213], v[18:21]
	v_mfma_f32_16x16x32_bf16 v[18:21], v[162:165], v[214:217], v[18:21]
	v_mfma_f32_16x16x32_bf16 v[34:37], v[158:161], v[202:205], v[34:37]
	v_mfma_f32_16x16x32_bf16 v[34:37], v[162:165], v[206:209], v[34:37]
	v_mfma_f32_16x16x32_bf16 v[50:53], v[158:161], v[194:197], v[50:53]
	v_mfma_f32_16x16x32_bf16 v[50:53], v[162:165], v[198:201], v[50:53]
	v_mfma_f32_16x16x32_bf16 v[58:61], v[158:161], v[186:189], v[58:61]
	v_mfma_f32_16x16x32_bf16 v[58:61], v[162:165], v[190:193], v[58:61]
	v_mfma_f32_16x16x32_bf16 v[46:49], v[166:169], v[186:189], v[46:49]
	v_mfma_f32_16x16x32_bf16 v[46:49], v[170:173], v[190:193], v[46:49]
	v_mfma_f32_16x16x32_bf16 v[30:33], v[166:169], v[194:197], v[30:33]
	v_mfma_f32_16x16x32_bf16 v[30:33], v[170:173], v[198:201], v[30:33]
	v_mfma_f32_16x16x32_bf16 v[14:17], v[166:169], v[202:205], v[14:17]
	v_mfma_f32_16x16x32_bf16 v[14:17], v[170:173], v[206:209], v[14:17]
	v_mfma_f32_16x16x32_bf16 v[6:9], v[166:169], v[210:213], v[6:9]
	v_mfma_f32_16x16x32_bf16 v[6:9], v[170:173], v[214:217], v[6:9]
	v_mfma_f32_16x16x32_bf16 v[2:5], v[174:177], v[210:213], v[2:5]
	v_mfma_f32_16x16x32_bf16 v[2:5], v[182:185], v[214:217], v[2:5]
	v_mfma_f32_16x16x32_bf16 v[10:13], v[174:177], v[202:205], v[10:13]
	v_mfma_f32_16x16x32_bf16 v[10:13], v[182:185], v[206:209], v[10:13]
	v_mfma_f32_16x16x32_bf16 v[22:25], v[174:177], v[194:197], v[22:25]
	v_mfma_f32_16x16x32_bf16 v[22:25], v[182:185], v[198:201], v[22:25]
	v_mfma_f32_16x16x32_bf16 v[38:41], v[174:177], v[186:189], v[38:41]
	v_mfma_f32_16x16x32_bf16 v[38:41], v[182:185], v[190:193], v[38:41]
	s_barrier
	s_setprio 0
	s_add_u32 s28, s28, 0x100
	s_addc_u32 s29, s29, 0
	s_add_u32 s19, s19, 0x100
	s_addc_u32 s21, s21, 0
	s_cmp_ge_i32 s72, s71
	s_mov_b32 s30, s72
	s_cbranch_scc0 .LBB0_2322
	s_and_b64 vcc, exec, s[8:9]
	s_cbranch_vccz .LBB0_2325
	s_barrier

.LBB0_2565:
	ds_read_b128 v[144:147], v151
	ds_read_b128 v[154:157], v151 offset:1024
	ds_read_b128 v[158:161], v151 offset:2048
	ds_read_b128 v[162:165], v151 offset:3072
	ds_read_b128 v[166:169], v152
	ds_read_b128 v[170:173], v152 offset:1024
	ds_read_b128 v[174:177], v152 offset:2048
	ds_read_b128 v[182:185], v152 offset:3072
	s_add_i32 s71, s22, 2
	s_add_u32 s23, s20, 0xffea0080
	s_addc_u32 s26, s21, -1
	s_cmp_eq_u32 s68, s22
	s_cselect_b32 s22, s18, s69
	s_cselect_b32 s27, s17, s26
	s_cselect_b32 s26, s16, s23
	s_cselect_b32 s23, s19, s70
	v_lshl_add_u64 v[218:219], s[20:21], 0, v[138:139]
	s_add_i32 m0, s35, 0xc000
	ds_read_b128 v[186:189], v153
	ds_read_b128 v[190:193], v153 offset:1024
	ds_read_b128 v[194:197], v153 offset:2048
	ds_read_b128 v[198:201], v153 offset:3072
	ds_read_b128 v[202:205], v153 offset:4096
	ds_read_b128 v[206:209], v153 offset:5120
	ds_read_b128 v[210:213], v153 offset:6144
	ds_read_b128 v[214:217], v153 offset:7168
	global_load_lds_dwordx4 v[218:219], off
	v_lshl_add_u64 v[218:219], s[20:21], 0, v[140:141]
	s_add_i32 m0, s35, 0xe000
	s_nop 0
	global_load_lds_dwordx4 v[218:219], off
	s_waitcnt vmcnt(8)
	s_waitcnt lgkmcnt(0)
	s_setprio 1
	s_barrier
	v_mfma_f32_16x16x32_bf16 v[126:129], v[144:147], v[186:189], v[126:129]
	v_mfma_f32_16x16x32_bf16 v[126:129], v[154:157], v[190:193], v[126:129]
	v_mfma_f32_16x16x32_bf16 v[118:121], v[144:147], v[194:197], v[118:121]
	v_mfma_f32_16x16x32_bf16 v[118:121], v[154:157], v[198:201], v[118:121]
	v_mfma_f32_16x16x32_bf16 v[106:109], v[144:147], v[202:205], v[106:109]
	v_mfma_f32_16x16x32_bf16 v[106:109], v[154:157], v[206:209], v[106:109]
	v_mfma_f32_16x16x32_bf16 v[90:93], v[144:147], v[210:213], v[90:93]
	v_mfma_f32_16x16x32_bf16 v[90:93], v[154:157], v[214:217], v[90:93]
	v_mfma_f32_16x16x32_bf16 v[82:85], v[158:161], v[210:213], v[82:85]
	v_mfma_f32_16x16x32_bf16 v[82:85], v[162:165], v[214:217], v[82:85]
	v_mfma_f32_16x16x32_bf16 v[98:101], v[158:161], v[202:205], v[98:101]
	v_mfma_f32_16x16x32_bf16 v[98:101], v[162:165], v[206:209], v[98:101]
	v_mfma_f32_16x16x32_bf16 v[114:117], v[158:161], v[194:197], v[114:117]
	v_mfma_f32_16x16x32_bf16 v[114:117], v[162:165], v[198:201], v[114:117]
	v_mfma_f32_16x16x32_bf16 v[122:125], v[158:161], v[186:189], v[122:125]
	v_mfma_f32_16x16x32_bf16 v[122:125], v[162:165], v[190:193], v[122:125]
	v_mfma_f32_16x16x32_bf16 v[110:113], v[166:169], v[186:189], v[110:113]
	v_mfma_f32_16x16x32_bf16 v[110:113], v[170:173], v[190:193], v[110:113]
	v_mfma_f32_16x16x32_bf16 v[94:97], v[166:169], v[194:197], v[94:97]
	v_mfma_f32_16x16x32_bf16 v[94:97], v[170:173], v[198:201], v[94:97]
	v_mfma_f32_16x16x32_bf16 v[78:81], v[166:169], v[202:205], v[78:81]
	v_mfma_f32_16x16x32_bf16 v[78:81], v[170:173], v[206:209], v[78:81]
	v_mfma_f32_16x16x32_bf16 v[70:73], v[166:169], v[210:213], v[70:73]
	v_mfma_f32_16x16x32_bf16 v[70:73], v[170:173], v[214:217], v[70:73]
	v_mfma_f32_16x16x32_bf16 v[66:69], v[174:177], v[210:213], v[66:69]
	v_mfma_f32_16x16x32_bf16 v[66:69], v[182:185], v[214:217], v[66:69]
	v_mfma_f32_16x16x32_bf16 v[74:77], v[174:177], v[202:205], v[74:77]
	v_mfma_f32_16x16x32_bf16 v[74:77], v[182:185], v[206:209], v[74:77]
	v_mfma_f32_16x16x32_bf16 v[86:89], v[174:177], v[194:197], v[86:89]
	v_mfma_f32_16x16x32_bf16 v[86:89], v[182:185], v[198:201], v[86:89]
	v_mfma_f32_16x16x32_bf16 v[102:105], v[174:177], v[186:189], v[102:105]
	v_mfma_f32_16x16x32_bf16 v[102:105], v[182:185], v[190:193], v[102:105]
	s_barrier
	s_setprio 0
	s_add_i32 s72, s52, s31
	v_lshl_add_u64 v[218:219], s[22:23], 0, v[132:133]
	s_mov_b32 m0, s72
	ds_read_b128 v[186:189], v153 offset:16384
	ds_read_b128 v[190:193], v153 offset:17408
	ds_read_b128 v[194:197], v153 offset:18432
	ds_read_b128 v[198:201], v153 offset:19456
	ds_read_b128 v[202:205], v153 offset:20480
	ds_read_b128 v[206:209], v153 offset:21504
	ds_read_b128 v[210:213], v153 offset:22528
	ds_read_b128 v[214:217], v153 offset:23552
	global_load_lds_dwordx4 v[218:219], off
	s_add_i32 m0, s72, 0x2000
	s_add_u32 s72, s22, 0x160000
	v_lshl_add_u64 v[220:221], s[22:23], 0, v[136:137]
	s_addc_u32 s73, s23, 0
	s_add_i32 s76, s53, s31
	global_load_lds_dwordx4 v[220:221], off
	v_lshl_add_u64 v[222:223], s[72:73], 0, v[132:133]
	s_mov_b32 m0, s76
	v_lshl_add_u64 v[224:225], s[26:27], 0, v[134:135]
	global_load_lds_dwordx4 v[222:223], off
	v_lshl_add_u64 v[222:223], s[72:73], 0, v[136:137]
	s_add_i32 m0, s76, 0x2000
	s_nop 0
	global_load_lds_dwordx4 v[222:223], off
	v_lshl_add_u64 v[222:223], s[26:27], 0, v[130:131]
	s_mov_b32 m0, s35
	s_nop 0
	global_load_lds_dwordx4 v[222:223], off
	s_mov_b32 m0, s36
	s_nop 0
	global_load_lds_dwordx4 v[224:225], off
	s_waitcnt vmcnt(8)
	s_waitcnt lgkmcnt(0)
	s_setprio 1
	s_barrier
	v_mfma_f32_16x16x32_bf16 v[62:65], v[144:147], v[186:189], v[62:65]
	v_mfma_f32_16x16x32_bf16 v[62:65], v[154:157], v[190:193], v[62:65]
	v_mfma_f32_16x16x32_bf16 v[54:57], v[144:147], v[194:197], v[54:57]
	v_mfma_f32_16x16x32_bf16 v[54:57], v[154:157], v[198:201], v[54:57]
	v_mfma_f32_16x16x32_bf16 v[42:45], v[144:147], v[202:205], v[42:45]
	v_mfma_f32_16x16x32_bf16 v[42:45], v[154:157], v[206:209], v[42:45]
	v_mfma_f32_16x16x32_bf16 v[26:29], v[144:147], v[210:213], v[26:29]
	v_mfma_f32_16x16x32_bf16 v[26:29], v[154:157], v[214:217], v[26:29]
	v_mfma_f32_16x16x32_bf16 v[18:21], v[158:161], v[210:213], v[18:21]
	v_mfma_f32_16x16x32_bf16 v[18:21], v[162:165], v[214:217], v[18:21]
	v_mfma_f32_16x16x32_bf16 v[34:37], v[158:161], v[202:205], v[34:37]
	v_mfma_f32_16x16x32_bf16 v[34:37], v[162:165], v[206:209], v[34:37]
	v_mfma_f32_16x16x32_bf16 v[50:53], v[158:161], v[194:197], v[50:53]
	v_mfma_f32_16x16x32_bf16 v[50:53], v[162:165], v[198:201], v[50:53]
	v_mfma_f32_16x16x32_bf16 v[58:61], v[158:161], v[186:189], v[58:61]
	v_mfma_f32_16x16x32_bf16 v[58:61], v[162:165], v[190:193], v[58:61]
	v_mfma_f32_16x16x32_bf16 v[46:49], v[166:169], v[186:189], v[46:49]
	v_mfma_f32_16x16x32_bf16 v[46:49], v[170:173], v[190:193], v[46:49]
	v_mfma_f32_16x16x32_bf16 v[30:33], v[166:169], v[194:197], v[30:33]
	v_mfma_f32_16x16x32_bf16 v[30:33], v[170:173], v[198:201], v[30:33]
	v_mfma_f32_16x16x32_bf16 v[14:17], v[166:169], v[202:205], v[14:17]
	v_mfma_f32_16x16x32_bf16 v[14:17], v[170:173], v[206:209], v[14:17]
	v_mfma_f32_16x16x32_bf16 v[6:9], v[166:169], v[210:213], v[6:9]
	v_mfma_f32_16x16x32_bf16 v[6:9], v[170:173], v[214:217], v[6:9]
	v_mfma_f32_16x16x32_bf16 v[2:5], v[174:177], v[210:213], v[2:5]
	v_mfma_f32_16x16x32_bf16 v[2:5], v[182:185], v[214:217], v[2:5]
	v_mfma_f32_16x16x32_bf16 v[10:13], v[174:177], v[202:205], v[10:13]
	v_mfma_f32_16x16x32_bf16 v[10:13], v[182:185], v[206:209], v[10:13]
	v_mfma_f32_16x16x32_bf16 v[22:25], v[174:177], v[194:197], v[22:25]
	v_mfma_f32_16x16x32_bf16 v[22:25], v[182:185], v[198:201], v[22:25]
	v_mfma_f32_16x16x32_bf16 v[38:41], v[174:177], v[186:189], v[38:41]
	v_mfma_f32_16x16x32_bf16 v[38:41], v[182:185], v[190:193], v[38:41]
	s_barrier
	s_setprio 0
	s_add_i32 s72, 0, 0x18000
	s_add_i32 s73, 0, 0x1c000
	v_add_u32_e32 v162, s72, v149
	v_add_u32_e32 v179, s73, v149
	ds_read_b128 v[144:147], v162
	ds_read_b128 v[154:157], v162 offset:1024
	ds_read_b128 v[158:161], v162 offset:2048
	ds_read_b128 v[162:165], v162 offset:3072
	ds_read_b128 v[166:169], v179
	ds_read_b128 v[170:173], v179 offset:1024
	ds_read_b128 v[174:177], v179 offset:2048
	ds_read_b128 v[182:185], v179 offset:3072
	s_add_u32 s26, s26, 0x160000
	s_addc_u32 s27, s27, 0
	s_mov_b32 m0, s37
	v_lshl_add_u64 v[226:227], s[26:27], 0, v[130:131]
	ds_read_b128 v[186:189], v153 offset:32768
	ds_read_b128 v[190:193], v153 offset:33792
	ds_read_b128 v[194:197], v153 offset:34816
	ds_read_b128 v[198:201], v153 offset:35840
	ds_read_b128 v[202:205], v153 offset:36864
	ds_read_b128 v[206:209], v153 offset:37888
	ds_read_b128 v[210:213], v153 offset:38912
	ds_read_b128 v[214:217], v153 offset:39936
	global_load_lds_dwordx4 v[226:227], off
	v_lshl_add_u64 v[226:227], s[26:27], 0, v[134:135]
	s_mov_b32 m0, s38
	s_nop 0
	global_load_lds_dwordx4 v[226:227], off
	s_waitcnt vmcnt(8)
	s_waitcnt lgkmcnt(0)
	s_setprio 1
	s_barrier
	v_mfma_f32_16x16x32_bf16 v[126:129], v[144:147], v[186:189], v[126:129]
	v_mfma_f32_16x16x32_bf16 v[126:129], v[154:157], v[190:193], v[126:129]
	v_mfma_f32_16x16x32_bf16 v[118:121], v[144:147], v[194:197], v[118:121]
	v_mfma_f32_16x16x32_bf16 v[118:121], v[154:157], v[198:201], v[118:121]
	v_mfma_f32_16x16x32_bf16 v[106:109], v[144:147], v[202:205], v[106:109]
	v_mfma_f32_16x16x32_bf16 v[106:109], v[154:157], v[206:209], v[106:109]
	v_mfma_f32_16x16x32_bf16 v[90:93], v[144:147], v[210:213], v[90:93]
	v_mfma_f32_16x16x32_bf16 v[90:93], v[154:157], v[214:217], v[90:93]
	v_mfma_f32_16x16x32_bf16 v[82:85], v[158:161], v[210:213], v[82:85]
	v_mfma_f32_16x16x32_bf16 v[82:85], v[162:165], v[214:217], v[82:85]
	v_mfma_f32_16x16x32_bf16 v[98:101], v[158:161], v[202:205], v[98:101]
	v_mfma_f32_16x16x32_bf16 v[98:101], v[162:165], v[206:209], v[98:101]
	v_mfma_f32_16x16x32_bf16 v[114:117], v[158:161], v[194:197], v[114:117]
	v_mfma_f32_16x16x32_bf16 v[114:117], v[162:165], v[198:201], v[114:117]
	v_mfma_f32_16x16x32_bf16 v[122:125], v[158:161], v[186:189], v[122:125]
	v_mfma_f32_16x16x32_bf16 v[122:125], v[162:165], v[190:193], v[122:125]
	v_mfma_f32_16x16x32_bf16 v[110:113], v[166:169], v[186:189], v[110:113]
	v_mfma_f32_16x16x32_bf16 v[110:113], v[170:173], v[190:193], v[110:113]
	v_mfma_f32_16x16x32_bf16 v[94:97], v[166:169], v[194:197], v[94:97]
	v_mfma_f32_16x16x32_bf16 v[94:97], v[170:173], v[198:201], v[94:97]
	v_mfma_f32_16x16x32_bf16 v[78:81], v[166:169], v[202:205], v[78:81]
	v_mfma_f32_16x16x32_bf16 v[78:81], v[170:173], v[206:209], v[78:81]
	v_mfma_f32_16x16x32_bf16 v[70:73], v[166:169], v[210:213], v[70:73]
	v_mfma_f32_16x16x32_bf16 v[70:73], v[170:173], v[214:217], v[70:73]
	v_mfma_f32_16x16x32_bf16 v[66:69], v[174:177], v[210:213], v[66:69]
	v_mfma_f32_16x16x32_bf16 v[66:69], v[182:185], v[214:217], v[66:69]
	v_mfma_f32_16x16x32_bf16 v[74:77], v[174:177], v[202:205], v[74:77]
	v_mfma_f32_16x16x32_bf16 v[74:77], v[182:185], v[206:209], v[74:77]
	v_mfma_f32_16x16x32_bf16 v[86:89], v[174:177], v[194:197], v[86:89]
	v_mfma_f32_16x16x32_bf16 v[86:89], v[182:185], v[198:201], v[86:89]
	v_mfma_f32_16x16x32_bf16 v[102:105], v[174:177], v[186:189], v[102:105]
	v_mfma_f32_16x16x32_bf16 v[102:105], v[182:185], v[190:193], v[102:105]
	s_barrier
	s_setprio 0
	s_add_i32 s26, s72, s31
	v_lshl_add_u64 v[218:219], v[218:219], 0, s[4:5]
	s_mov_b32 m0, s26
	ds_read_b128 v[186:189], v153 offset:49152
	ds_read_b128 v[190:193], v153 offset:50176
	ds_read_b128 v[194:197], v153 offset:51200
	ds_read_b128 v[198:201], v153 offset:52224
	ds_read_b128 v[202:205], v153 offset:53248
	ds_read_b128 v[206:209], v153 offset:54272
	ds_read_b128 v[210:213], v153 offset:55296
	ds_read_b128 v[214:217], v153 offset:56320
	global_load_lds_dwordx4 v[218:219], off
	s_add_i32 m0, s26, 0x2000
	s_add_u32 s22, s22, 0x160080
	v_lshl_add_u64 v[218:219], v[220:221], 0, s[4:5]
	s_addc_u32 s23, s23, 0
	s_add_i32 s26, s73, s31
	global_load_lds_dwordx4 v[218:219], off
	v_lshl_add_u64 v[218:219], s[22:23], 0, v[132:133]
	s_mov_b32 m0, s26
	s_nop 0
	global_load_lds_dwordx4 v[218:219], off
	v_lshl_add_u64 v[218:219], s[22:23], 0, v[136:137]
	s_add_i32 m0, s26, 0x2000
	s_nop 0
	global_load_lds_dwordx4 v[218:219], off
	v_lshl_add_u64 v[218:219], v[222:223], 0, s[4:5]
	s_mov_b32 m0, s42
	s_nop 0
	global_load_lds_dwordx4 v[218:219], off
	v_lshl_add_u64 v[218:219], v[224:225], 0, s[4:5]
	s_mov_b32 m0, s43
	s_nop 0
	global_load_lds_dwordx4 v[218:219], off
	s_waitcnt vmcnt(8)
	s_waitcnt lgkmcnt(0)
	s_setprio 1
	s_barrier
	v_mfma_f32_16x16x32_bf16 v[62:65], v[144:147], v[186:189], v[62:65]
	v_mfma_f32_16x16x32_bf16 v[62:65], v[154:157], v[190:193], v[62:65]
	v_mfma_f32_16x16x32_bf16 v[54:57], v[144:147], v[194:197], v[54:57]
	v_mfma_f32_16x16x32_bf16 v[54:57], v[154:157], v[198:201], v[54:57]
	v_mfma_f32_16x16x32_bf16 v[42:45], v[144:147], v[202:205], v[42:45]
	v_mfma_f32_16x16x32_bf16 v[42:45], v[154:157], v[206:209], v[42:45]
	v_mfma_f32_16x16x32_bf16 v[26:29], v[144:147], v[210:213], v[26:29]
	v_mfma_f32_16x16x32_bf16 v[26:29], v[154:157], v[214:217], v[26:29]
	v_mfma_f32_16x16x32_bf16 v[18:21], v[158:161], v[210:213], v[18:21]
	v_mfma_f32_16x16x32_bf16 v[18:21], v[162:165], v[214:217], v[18:21]
	v_mfma_f32_16x16x32_bf16 v[34:37], v[158:161], v[202:205], v[34:37]
	v_mfma_f32_16x16x32_bf16 v[34:37], v[162:165], v[206:209], v[34:37]
	v_mfma_f32_16x16x32_bf16 v[50:53], v[158:161], v[194:197], v[50:53]
	v_mfma_f32_16x16x32_bf16 v[50:53], v[162:165], v[198:201], v[50:53]
	v_mfma_f32_16x16x32_bf16 v[58:61], v[158:161], v[186:189], v[58:61]
	v_mfma_f32_16x16x32_bf16 v[58:61], v[162:165], v[190:193], v[58:61]
	v_mfma_f32_16x16x32_bf16 v[46:49], v[166:169], v[186:189], v[46:49]
	v_mfma_f32_16x16x32_bf16 v[46:49], v[170:173], v[190:193], v[46:49]
	v_mfma_f32_16x16x32_bf16 v[30:33], v[166:169], v[194:197], v[30:33]
	v_mfma_f32_16x16x32_bf16 v[30:33], v[170:173], v[198:201], v[30:33]
	v_mfma_f32_16x16x32_bf16 v[14:17], v[166:169], v[202:205], v[14:17]
	v_mfma_f32_16x16x32_bf16 v[14:17], v[170:173], v[206:209], v[14:17]
	v_mfma_f32_16x16x32_bf16 v[6:9], v[166:169], v[210:213], v[6:9]
	v_mfma_f32_16x16x32_bf16 v[6:9], v[170:173], v[214:217], v[6:9]
	v_mfma_f32_16x16x32_bf16 v[2:5], v[174:177], v[210:213], v[2:5]
	v_mfma_f32_16x16x32_bf16 v[2:5], v[182:185], v[214:217], v[2:5]
	v_mfma_f32_16x16x32_bf16 v[10:13], v[174:177], v[202:205], v[10:13]
	v_mfma_f32_16x16x32_bf16 v[10:13], v[182:185], v[206:209], v[10:13]
	v_mfma_f32_16x16x32_bf16 v[22:25], v[174:177], v[194:197], v[22:25]
	v_mfma_f32_16x16x32_bf16 v[22:25], v[182:185], v[198:201], v[22:25]
	v_mfma_f32_16x16x32_bf16 v[38:41], v[174:177], v[186:189], v[38:41]
	v_mfma_f32_16x16x32_bf16 v[38:41], v[182:185], v[190:193], v[38:41]
	s_barrier
	s_setprio 0
	s_add_u32 s20, s20, 0x100
	s_addc_u32 s21, s21, 0
	s_add_u32 s69, s69, 0x100
	s_addc_u32 s70, s70, 0
	s_cmp_ge_i32 s71, s67
	s_mov_b32 s22, s71
	s_cbranch_scc0 .LBB0_2565
	s_and_b64 vcc, exec, s[6:7]
	s_cbranch_vccz .LBB0_2568
	s_barrier

.LBB0_2731:
	ds_read_b128 v[146:149], v162
	ds_read_b128 v[150:153], v162 offset:1024
	ds_read_b128 v[166:169], v162 offset:2048
	ds_read_b128 v[170:173], v162 offset:3072
	ds_read_b128 v[174:177], v163
	ds_read_b128 v[182:185], v163 offset:1024
	ds_read_b128 v[186:189], v163 offset:2048
	ds_read_b128 v[190:193], v163 offset:3072
	s_add_u32 s24, s4, 0xfff80080
	s_addc_u32 s25, s5, -1
	s_cmp_eq_u32 s55, 28
	s_cselect_b32 s27, s15, s25
	s_cselect_b32 s26, s47, s24
	s_cselect_b32 s25, s13, s54
	s_cselect_b32 s24, s52, s53
	v_lshl_add_u64 v[226:227], s[4:5], 0, v[138:139]
	s_add_i32 m0, s21, 0xc000
	ds_read_b128 v[194:197], v164
	ds_read_b128 v[198:201], v164 offset:1024
	ds_read_b128 v[202:205], v164 offset:2048
	ds_read_b128 v[206:209], v164 offset:3072
	ds_read_b128 v[210:213], v164 offset:4096
	ds_read_b128 v[214:217], v164 offset:5120
	ds_read_b128 v[218:221], v164 offset:6144
	ds_read_b128 v[222:225], v164 offset:7168
	global_load_lds_dwordx4 v[226:227], off
	v_lshl_add_u64 v[226:227], s[4:5], 0, v[140:141]
	s_add_i32 m0, s21, 0xe000
	s_nop 0
	global_load_lds_dwordx4 v[226:227], off
	s_waitcnt vmcnt(8)
	s_waitcnt lgkmcnt(0)
	s_setprio 1
	s_barrier
	v_mfma_f32_16x16x32_bf16 v[126:129], v[146:149], v[194:197], v[126:129]
	v_mfma_f32_16x16x32_bf16 v[126:129], v[150:153], v[198:201], v[126:129]
	v_mfma_f32_16x16x32_bf16 v[110:113], v[146:149], v[202:205], v[110:113]
	v_mfma_f32_16x16x32_bf16 v[110:113], v[150:153], v[206:209], v[110:113]
	v_mfma_f32_16x16x32_bf16 v[94:97], v[146:149], v[210:213], v[94:97]
	v_mfma_f32_16x16x32_bf16 v[94:97], v[150:153], v[214:217], v[94:97]
	v_mfma_f32_16x16x32_bf16 v[78:81], v[146:149], v[218:221], v[78:81]
	v_mfma_f32_16x16x32_bf16 v[78:81], v[150:153], v[222:225], v[78:81]
	v_mfma_f32_16x16x32_bf16 v[74:77], v[166:169], v[218:221], v[74:77]
	v_mfma_f32_16x16x32_bf16 v[74:77], v[170:173], v[222:225], v[74:77]
	v_mfma_f32_16x16x32_bf16 v[90:93], v[166:169], v[210:213], v[90:93]
	v_mfma_f32_16x16x32_bf16 v[90:93], v[170:173], v[214:217], v[90:93]
	v_mfma_f32_16x16x32_bf16 v[106:109], v[166:169], v[202:205], v[106:109]
	v_mfma_f32_16x16x32_bf16 v[106:109], v[170:173], v[206:209], v[106:109]
	v_mfma_f32_16x16x32_bf16 v[122:125], v[166:169], v[194:197], v[122:125]
	v_mfma_f32_16x16x32_bf16 v[122:125], v[170:173], v[198:201], v[122:125]
	v_mfma_f32_16x16x32_bf16 v[118:121], v[174:177], v[194:197], v[118:121]
	v_mfma_f32_16x16x32_bf16 v[118:121], v[182:185], v[198:201], v[118:121]
	v_mfma_f32_16x16x32_bf16 v[102:105], v[174:177], v[202:205], v[102:105]
	v_mfma_f32_16x16x32_bf16 v[102:105], v[182:185], v[206:209], v[102:105]
	v_mfma_f32_16x16x32_bf16 v[86:89], v[174:177], v[210:213], v[86:89]
	v_mfma_f32_16x16x32_bf16 v[86:89], v[182:185], v[214:217], v[86:89]
	v_mfma_f32_16x16x32_bf16 v[70:73], v[174:177], v[218:221], v[70:73]
	v_mfma_f32_16x16x32_bf16 v[70:73], v[182:185], v[222:225], v[70:73]
	v_mfma_f32_16x16x32_bf16 v[66:69], v[186:189], v[218:221], v[66:69]
	v_mfma_f32_16x16x32_bf16 v[66:69], v[190:193], v[222:225], v[66:69]
	v_mfma_f32_16x16x32_bf16 v[82:85], v[186:189], v[210:213], v[82:85]
	v_mfma_f32_16x16x32_bf16 v[82:85], v[190:193], v[214:217], v[82:85]
	v_mfma_f32_16x16x32_bf16 v[98:101], v[186:189], v[202:205], v[98:101]
	v_mfma_f32_16x16x32_bf16 v[98:101], v[190:193], v[206:209], v[98:101]
	v_mfma_f32_16x16x32_bf16 v[114:117], v[186:189], v[194:197], v[114:117]
	v_mfma_f32_16x16x32_bf16 v[114:117], v[190:193], v[198:201], v[114:117]
	s_barrier
	s_setprio 0
	s_add_i32 s56, s44, s30
	v_lshl_add_u64 v[226:227], s[24:25], 0, v[132:133]
	s_mov_b32 m0, s56
	ds_read_b128 v[194:197], v164 offset:16384
	ds_read_b128 v[198:201], v164 offset:17408
	ds_read_b128 v[202:205], v164 offset:18432
	ds_read_b128 v[206:209], v164 offset:19456
	ds_read_b128 v[210:213], v164 offset:20480
	ds_read_b128 v[214:217], v164 offset:21504
	ds_read_b128 v[218:221], v164 offset:22528
	ds_read_b128 v[222:225], v164 offset:23552
	global_load_lds_dwordx4 v[226:227], off
	s_add_i32 m0, s56, 0x2000
	s_add_u32 s56, s24, 0x80000
	v_lshl_add_u64 v[228:229], s[24:25], 0, v[136:137]
	s_addc_u32 s57, s25, 0
	s_add_i32 s58, s45, s30
	global_load_lds_dwordx4 v[228:229], off
	v_lshl_add_u64 v[230:231], s[56:57], 0, v[132:133]
	s_mov_b32 m0, s58
	v_lshl_add_u64 v[232:233], s[26:27], 0, v[134:135]
	global_load_lds_dwordx4 v[230:231], off
	v_lshl_add_u64 v[230:231], s[56:57], 0, v[136:137]
	s_add_i32 m0, s58, 0x2000
	s_nop 0
	global_load_lds_dwordx4 v[230:231], off
	v_lshl_add_u64 v[230:231], s[26:27], 0, v[130:131]
	s_mov_b32 m0, s21
	s_nop 0
	global_load_lds_dwordx4 v[230:231], off
	s_mov_b32 m0, s23
	s_nop 0
	global_load_lds_dwordx4 v[232:233], off
	s_waitcnt vmcnt(8)
	s_waitcnt lgkmcnt(0)
	s_setprio 1
	s_barrier
	v_mfma_f32_16x16x32_bf16 v[62:65], v[146:149], v[194:197], v[62:65]
	v_mfma_f32_16x16x32_bf16 v[62:65], v[150:153], v[198:201], v[62:65]
	v_mfma_f32_16x16x32_bf16 v[46:49], v[146:149], v[202:205], v[46:49]
	v_mfma_f32_16x16x32_bf16 v[46:49], v[150:153], v[206:209], v[46:49]
	v_mfma_f32_16x16x32_bf16 v[30:33], v[146:149], v[210:213], v[30:33]
	v_mfma_f32_16x16x32_bf16 v[30:33], v[150:153], v[214:217], v[30:33]
	v_mfma_f32_16x16x32_bf16 v[14:17], v[146:149], v[218:221], v[14:17]
	v_mfma_f32_16x16x32_bf16 v[14:17], v[150:153], v[222:225], v[14:17]
	v_mfma_f32_16x16x32_bf16 v[10:13], v[166:169], v[218:221], v[10:13]
	v_mfma_f32_16x16x32_bf16 v[10:13], v[170:173], v[222:225], v[10:13]
	v_mfma_f32_16x16x32_bf16 v[26:29], v[166:169], v[210:213], v[26:29]
	v_mfma_f32_16x16x32_bf16 v[26:29], v[170:173], v[214:217], v[26:29]
	v_mfma_f32_16x16x32_bf16 v[42:45], v[166:169], v[202:205], v[42:45]
	v_mfma_f32_16x16x32_bf16 v[42:45], v[170:173], v[206:209], v[42:45]
	v_mfma_f32_16x16x32_bf16 v[58:61], v[166:169], v[194:197], v[58:61]
	v_mfma_f32_16x16x32_bf16 v[58:61], v[170:173], v[198:201], v[58:61]
	v_mfma_f32_16x16x32_bf16 v[54:57], v[174:177], v[194:197], v[54:57]
	v_mfma_f32_16x16x32_bf16 v[54:57], v[182:185], v[198:201], v[54:57]
	v_mfma_f32_16x16x32_bf16 v[38:41], v[174:177], v[202:205], v[38:41]
	v_mfma_f32_16x16x32_bf16 v[38:41], v[182:185], v[206:209], v[38:41]
	v_mfma_f32_16x16x32_bf16 v[22:25], v[174:177], v[210:213], v[22:25]
	v_mfma_f32_16x16x32_bf16 v[22:25], v[182:185], v[214:217], v[22:25]
	v_mfma_f32_16x16x32_bf16 v[6:9], v[174:177], v[218:221], v[6:9]
	v_mfma_f32_16x16x32_bf16 v[6:9], v[182:185], v[222:225], v[6:9]
	v_mfma_f32_16x16x32_bf16 v[2:5], v[186:189], v[218:221], v[2:5]
	v_mfma_f32_16x16x32_bf16 v[2:5], v[190:193], v[222:225], v[2:5]
	v_mfma_f32_16x16x32_bf16 v[18:21], v[186:189], v[210:213], v[18:21]
	v_mfma_f32_16x16x32_bf16 v[18:21], v[190:193], v[214:217], v[18:21]
	v_mfma_f32_16x16x32_bf16 v[34:37], v[186:189], v[202:205], v[34:37]
	v_mfma_f32_16x16x32_bf16 v[34:37], v[190:193], v[206:209], v[34:37]
	v_mfma_f32_16x16x32_bf16 v[50:53], v[186:189], v[194:197], v[50:53]
	v_mfma_f32_16x16x32_bf16 v[50:53], v[190:193], v[198:201], v[50:53]
	s_barrier
	s_setprio 0
	s_add_i32 s56, 0, 0x18000
	s_add_i32 s57, 0, 0x1c000
	v_add_u32_e32 v170, s56, v156
	v_add_u32_e32 v179, s57, v156
	ds_read_b128 v[146:149], v170
	ds_read_b128 v[150:153], v170 offset:1024
	ds_read_b128 v[166:169], v170 offset:2048
	ds_read_b128 v[170:173], v170 offset:3072
	ds_read_b128 v[174:177], v179
	ds_read_b128 v[182:185], v179 offset:1024
	ds_read_b128 v[186:189], v179 offset:2048
	ds_read_b128 v[190:193], v179 offset:3072
	s_add_u32 s26, s26, 0x80000
	s_addc_u32 s27, s27, 0
	s_mov_b32 m0, s31
	v_lshl_add_u64 v[234:235], s[26:27], 0, v[130:131]
	ds_read_b128 v[194:197], v164 offset:32768
	ds_read_b128 v[198:201], v164 offset:33792
	ds_read_b128 v[202:205], v164 offset:34816
	ds_read_b128 v[206:209], v164 offset:35840
	ds_read_b128 v[210:213], v164 offset:36864
	ds_read_b128 v[214:217], v164 offset:37888
	ds_read_b128 v[218:221], v164 offset:38912
	ds_read_b128 v[222:225], v164 offset:39936
	global_load_lds_dwordx4 v[234:235], off
	v_lshl_add_u64 v[234:235], s[26:27], 0, v[134:135]
	s_mov_b32 m0, s34
	s_nop 0
	global_load_lds_dwordx4 v[234:235], off
	s_waitcnt vmcnt(8)
	s_waitcnt lgkmcnt(0)
	s_setprio 1
	s_barrier
	v_mfma_f32_16x16x32_bf16 v[126:129], v[146:149], v[194:197], v[126:129]
	v_mfma_f32_16x16x32_bf16 v[126:129], v[150:153], v[198:201], v[126:129]
	v_mfma_f32_16x16x32_bf16 v[110:113], v[146:149], v[202:205], v[110:113]
	v_mfma_f32_16x16x32_bf16 v[110:113], v[150:153], v[206:209], v[110:113]
	v_mfma_f32_16x16x32_bf16 v[94:97], v[146:149], v[210:213], v[94:97]
	v_mfma_f32_16x16x32_bf16 v[94:97], v[150:153], v[214:217], v[94:97]
	v_mfma_f32_16x16x32_bf16 v[78:81], v[146:149], v[218:221], v[78:81]
	v_mfma_f32_16x16x32_bf16 v[78:81], v[150:153], v[222:225], v[78:81]
	v_mfma_f32_16x16x32_bf16 v[74:77], v[166:169], v[218:221], v[74:77]
	v_mfma_f32_16x16x32_bf16 v[74:77], v[170:173], v[222:225], v[74:77]
	v_mfma_f32_16x16x32_bf16 v[90:93], v[166:169], v[210:213], v[90:93]
	v_mfma_f32_16x16x32_bf16 v[90:93], v[170:173], v[214:217], v[90:93]
	v_mfma_f32_16x16x32_bf16 v[106:109], v[166:169], v[202:205], v[106:109]
	v_mfma_f32_16x16x32_bf16 v[106:109], v[170:173], v[206:209], v[106:109]
	v_mfma_f32_16x16x32_bf16 v[122:125], v[166:169], v[194:197], v[122:125]
	v_mfma_f32_16x16x32_bf16 v[122:125], v[170:173], v[198:201], v[122:125]
	v_mfma_f32_16x16x32_bf16 v[118:121], v[174:177], v[194:197], v[118:121]
	v_mfma_f32_16x16x32_bf16 v[118:121], v[182:185], v[198:201], v[118:121]
	v_mfma_f32_16x16x32_bf16 v[102:105], v[174:177], v[202:205], v[102:105]
	v_mfma_f32_16x16x32_bf16 v[102:105], v[182:185], v[206:209], v[102:105]
	v_mfma_f32_16x16x32_bf16 v[86:89], v[174:177], v[210:213], v[86:89]
	v_mfma_f32_16x16x32_bf16 v[86:89], v[182:185], v[214:217], v[86:89]
	v_mfma_f32_16x16x32_bf16 v[70:73], v[174:177], v[218:221], v[70:73]
	v_mfma_f32_16x16x32_bf16 v[70:73], v[182:185], v[222:225], v[70:73]
	v_mfma_f32_16x16x32_bf16 v[66:69], v[186:189], v[218:221], v[66:69]
	v_mfma_f32_16x16x32_bf16 v[66:69], v[190:193], v[222:225], v[66:69]
	v_mfma_f32_16x16x32_bf16 v[82:85], v[186:189], v[210:213], v[82:85]
	v_mfma_f32_16x16x32_bf16 v[82:85], v[190:193], v[214:217], v[82:85]
	v_mfma_f32_16x16x32_bf16 v[98:101], v[186:189], v[202:205], v[98:101]
	v_mfma_f32_16x16x32_bf16 v[98:101], v[190:193], v[206:209], v[98:101]
	v_mfma_f32_16x16x32_bf16 v[114:117], v[186:189], v[194:197], v[114:117]
	v_mfma_f32_16x16x32_bf16 v[114:117], v[190:193], v[198:201], v[114:117]
	s_barrier
	s_setprio 0
	s_add_i32 s26, s56, s30
	v_lshl_add_u64 v[226:227], v[226:227], 0, s[8:9]
	s_mov_b32 m0, s26
	ds_read_b128 v[194:197], v164 offset:49152
	ds_read_b128 v[198:201], v164 offset:50176
	ds_read_b128 v[202:205], v164 offset:51200
	ds_read_b128 v[206:209], v164 offset:52224
	ds_read_b128 v[210:213], v164 offset:53248
	ds_read_b128 v[214:217], v164 offset:54272
	ds_read_b128 v[218:221], v164 offset:55296
	ds_read_b128 v[222:225], v164 offset:56320
	global_load_lds_dwordx4 v[226:227], off
	s_add_i32 m0, s26, 0x2000
	s_add_u32 s24, s24, 0x80080
	v_lshl_add_u64 v[226:227], v[228:229], 0, s[8:9]
	s_addc_u32 s25, s25, 0
	s_add_i32 s26, s57, s30
	global_load_lds_dwordx4 v[226:227], off
	v_lshl_add_u64 v[226:227], s[24:25], 0, v[132:133]
	s_mov_b32 m0, s26
	s_nop 0
	global_load_lds_dwordx4 v[226:227], off
	v_lshl_add_u64 v[226:227], s[24:25], 0, v[136:137]
	s_add_i32 m0, s26, 0x2000
	s_nop 0
	global_load_lds_dwordx4 v[226:227], off
	v_lshl_add_u64 v[226:227], v[230:231], 0, s[8:9]
	s_mov_b32 m0, s36
	s_nop 0
	global_load_lds_dwordx4 v[226:227], off
	v_lshl_add_u64 v[226:227], v[232:233], 0, s[8:9]
	s_mov_b32 m0, s37
	s_nop 0
	global_load_lds_dwordx4 v[226:227], off
	s_waitcnt vmcnt(8)
	s_waitcnt lgkmcnt(0)
	s_setprio 1
	s_barrier
	v_mfma_f32_16x16x32_bf16 v[62:65], v[146:149], v[194:197], v[62:65]
	v_mfma_f32_16x16x32_bf16 v[62:65], v[150:153], v[198:201], v[62:65]
	v_mfma_f32_16x16x32_bf16 v[46:49], v[146:149], v[202:205], v[46:49]
	v_mfma_f32_16x16x32_bf16 v[46:49], v[150:153], v[206:209], v[46:49]
	v_mfma_f32_16x16x32_bf16 v[30:33], v[146:149], v[210:213], v[30:33]
	v_mfma_f32_16x16x32_bf16 v[30:33], v[150:153], v[214:217], v[30:33]
	v_mfma_f32_16x16x32_bf16 v[14:17], v[146:149], v[218:221], v[14:17]
	v_mfma_f32_16x16x32_bf16 v[14:17], v[150:153], v[222:225], v[14:17]
	v_mfma_f32_16x16x32_bf16 v[10:13], v[166:169], v[218:221], v[10:13]
	v_mfma_f32_16x16x32_bf16 v[10:13], v[170:173], v[222:225], v[10:13]
	v_mfma_f32_16x16x32_bf16 v[26:29], v[166:169], v[210:213], v[26:29]
	v_mfma_f32_16x16x32_bf16 v[26:29], v[170:173], v[214:217], v[26:29]
	v_mfma_f32_16x16x32_bf16 v[42:45], v[166:169], v[202:205], v[42:45]
	v_mfma_f32_16x16x32_bf16 v[42:45], v[170:173], v[206:209], v[42:45]
	v_mfma_f32_16x16x32_bf16 v[58:61], v[166:169], v[194:197], v[58:61]
	v_mfma_f32_16x16x32_bf16 v[58:61], v[170:173], v[198:201], v[58:61]
	v_mfma_f32_16x16x32_bf16 v[54:57], v[174:177], v[194:197], v[54:57]
	v_mfma_f32_16x16x32_bf16 v[54:57], v[182:185], v[198:201], v[54:57]
	v_mfma_f32_16x16x32_bf16 v[38:41], v[174:177], v[202:205], v[38:41]
	v_mfma_f32_16x16x32_bf16 v[38:41], v[182:185], v[206:209], v[38:41]
	v_mfma_f32_16x16x32_bf16 v[22:25], v[174:177], v[210:213], v[22:25]
	v_mfma_f32_16x16x32_bf16 v[22:25], v[182:185], v[214:217], v[22:25]
	v_mfma_f32_16x16x32_bf16 v[6:9], v[174:177], v[218:221], v[6:9]
	v_mfma_f32_16x16x32_bf16 v[6:9], v[182:185], v[222:225], v[6:9]
	v_mfma_f32_16x16x32_bf16 v[2:5], v[186:189], v[218:221], v[2:5]
	v_mfma_f32_16x16x32_bf16 v[2:5], v[190:193], v[222:225], v[2:5]
	v_mfma_f32_16x16x32_bf16 v[18:21], v[186:189], v[210:213], v[18:21]
	v_mfma_f32_16x16x32_bf16 v[18:21], v[190:193], v[214:217], v[18:21]
	v_mfma_f32_16x16x32_bf16 v[34:37], v[186:189], v[202:205], v[34:37]
	v_mfma_f32_16x16x32_bf16 v[34:37], v[190:193], v[206:209], v[34:37]
	v_mfma_f32_16x16x32_bf16 v[50:53], v[186:189], v[194:197], v[50:53]
	v_mfma_f32_16x16x32_bf16 v[50:53], v[190:193], v[198:201], v[50:53]
	s_barrier
	s_setprio 0
	s_add_i32 s55, s55, 2
	s_add_u32 s4, s4, 0x100
	s_addc_u32 s5, s5, 0
	s_add_u32 s53, s53, 0x100
	s_addc_u32 s54, s54, 0
	s_cmp_gt_u32 s55, 29
	s_cbranch_scc0 .LBB0_2731
	s_and_b64 vcc, exec, s[10:11]
	s_cbranch_vccz .LBB0_2734
	s_barrier

.LBB0_3060:
	ds_read_b128 v[154:157], v150
	ds_read_b128 v[158:161], v150 offset:1024
	ds_read_b128 v[162:165], v150 offset:2048
	ds_read_b128 v[166:169], v150 offset:3072
	ds_read_b128 v[170:173], v151
	ds_read_b128 v[174:177], v151 offset:1024
	ds_read_b128 v[182:185], v151 offset:2048
	ds_read_b128 v[186:189], v151 offset:3072
	s_add_u32 s28, s26, 0xfff80080
	s_addc_u32 s29, s27, -1
	s_cmp_eq_u32 s60, 28
	s_cselect_b32 s31, s19, s29
	s_cselect_b32 s30, s56, s28
	s_cselect_b32 s29, s17, s59
	s_cselect_b32 s28, s57, s58
	v_lshl_add_u64 v[146:147], s[26:27], 0, v[138:139]
	s_add_i32 m0, s25, 0xc000
	ds_read_b128 v[190:193], v152
	ds_read_b128 v[194:197], v152 offset:1024
	ds_read_b128 v[198:201], v152 offset:2048
	ds_read_b128 v[202:205], v152 offset:3072
	ds_read_b128 v[206:209], v152 offset:4096
	ds_read_b128 v[210:213], v152 offset:5120
	ds_read_b128 v[214:217], v152 offset:6144
	ds_read_b128 v[218:221], v152 offset:7168
	global_load_lds_dwordx4 v[146:147], off
	v_lshl_add_u64 v[146:147], s[26:27], 0, v[140:141]
	s_add_i32 m0, s25, 0xe000
	s_nop 0
	global_load_lds_dwordx4 v[146:147], off
	s_waitcnt vmcnt(8)
	s_waitcnt lgkmcnt(0)
	s_setprio 1
	s_barrier
	v_mfma_f32_16x16x32_bf16 v[126:129], v[154:157], v[190:193], v[126:129]
	v_mfma_f32_16x16x32_bf16 v[126:129], v[158:161], v[194:197], v[126:129]
	v_mfma_f32_16x16x32_bf16 v[118:121], v[154:157], v[198:201], v[118:121]
	v_mfma_f32_16x16x32_bf16 v[118:121], v[158:161], v[202:205], v[118:121]
	v_mfma_f32_16x16x32_bf16 v[102:105], v[154:157], v[206:209], v[102:105]
	v_mfma_f32_16x16x32_bf16 v[102:105], v[158:161], v[210:213], v[102:105]
	v_mfma_f32_16x16x32_bf16 v[86:89], v[154:157], v[214:217], v[86:89]
	v_mfma_f32_16x16x32_bf16 v[86:89], v[158:161], v[218:221], v[86:89]
	v_mfma_f32_16x16x32_bf16 v[78:81], v[162:165], v[214:217], v[78:81]
	v_mfma_f32_16x16x32_bf16 v[78:81], v[166:169], v[218:221], v[78:81]
	v_mfma_f32_16x16x32_bf16 v[94:97], v[162:165], v[206:209], v[94:97]
	v_mfma_f32_16x16x32_bf16 v[94:97], v[166:169], v[210:213], v[94:97]
	v_mfma_f32_16x16x32_bf16 v[110:113], v[162:165], v[198:201], v[110:113]
	v_mfma_f32_16x16x32_bf16 v[110:113], v[166:169], v[202:205], v[110:113]
	v_mfma_f32_16x16x32_bf16 v[122:125], v[162:165], v[190:193], v[122:125]
	v_mfma_f32_16x16x32_bf16 v[122:125], v[166:169], v[194:197], v[122:125]
	v_mfma_f32_16x16x32_bf16 v[114:117], v[170:173], v[190:193], v[114:117]
	v_mfma_f32_16x16x32_bf16 v[114:117], v[174:177], v[194:197], v[114:117]
	v_mfma_f32_16x16x32_bf16 v[98:101], v[170:173], v[198:201], v[98:101]
	v_mfma_f32_16x16x32_bf16 v[98:101], v[174:177], v[202:205], v[98:101]
	v_mfma_f32_16x16x32_bf16 v[82:85], v[170:173], v[206:209], v[82:85]
	v_mfma_f32_16x16x32_bf16 v[82:85], v[174:177], v[210:213], v[82:85]
	v_mfma_f32_16x16x32_bf16 v[70:73], v[170:173], v[214:217], v[70:73]
	v_mfma_f32_16x16x32_bf16 v[70:73], v[174:177], v[218:221], v[70:73]
	v_mfma_f32_16x16x32_bf16 v[66:69], v[182:185], v[214:217], v[66:69]
	v_mfma_f32_16x16x32_bf16 v[66:69], v[186:189], v[218:221], v[66:69]
	v_mfma_f32_16x16x32_bf16 v[74:77], v[182:185], v[206:209], v[74:77]
	v_mfma_f32_16x16x32_bf16 v[74:77], v[186:189], v[210:213], v[74:77]
	v_mfma_f32_16x16x32_bf16 v[90:93], v[182:185], v[198:201], v[90:93]
	v_mfma_f32_16x16x32_bf16 v[90:93], v[186:189], v[202:205], v[90:93]
	v_mfma_f32_16x16x32_bf16 v[106:109], v[182:185], v[190:193], v[106:109]
	v_mfma_f32_16x16x32_bf16 v[106:109], v[186:189], v[194:197], v[106:109]
	s_barrier
	s_setprio 0
	s_add_i32 s62, s47, s37
	v_lshl_add_u64 v[146:147], s[28:29], 0, v[132:133]
	s_mov_b32 m0, s62
	ds_read_b128 v[190:193], v152 offset:16384
	ds_read_b128 v[194:197], v152 offset:17408
	ds_read_b128 v[198:201], v152 offset:18432
	ds_read_b128 v[202:205], v152 offset:19456
	ds_read_b128 v[206:209], v152 offset:20480
	ds_read_b128 v[210:213], v152 offset:21504
	ds_read_b128 v[214:217], v152 offset:22528
	ds_read_b128 v[218:221], v152 offset:23552
	global_load_lds_dwordx4 v[146:147], off
	s_add_i32 m0, s62, 0x2000
	s_add_u32 s62, s28, 0x80000
	v_lshl_add_u64 v[222:223], s[28:29], 0, v[136:137]
	s_addc_u32 s63, s29, 0
	s_add_i32 s66, s50, s37
	global_load_lds_dwordx4 v[222:223], off
	v_lshl_add_u64 v[224:225], s[62:63], 0, v[132:133]
	s_mov_b32 m0, s66
	v_lshl_add_u64 v[226:227], s[30:31], 0, v[134:135]
	global_load_lds_dwordx4 v[224:225], off
	v_lshl_add_u64 v[224:225], s[62:63], 0, v[136:137]
	s_add_i32 m0, s66, 0x2000
	s_nop 0
	global_load_lds_dwordx4 v[224:225], off
	v_lshl_add_u64 v[224:225], s[30:31], 0, v[130:131]
	s_mov_b32 m0, s25
	s_nop 0
	global_load_lds_dwordx4 v[224:225], off
	s_mov_b32 m0, s38
	s_nop 0
	global_load_lds_dwordx4 v[226:227], off
	s_waitcnt vmcnt(8)
	s_waitcnt lgkmcnt(0)
	s_setprio 1
	s_barrier
	v_mfma_f32_16x16x32_bf16 v[62:65], v[154:157], v[190:193], v[62:65]
	v_mfma_f32_16x16x32_bf16 v[62:65], v[158:161], v[194:197], v[62:65]
	v_mfma_f32_16x16x32_bf16 v[54:57], v[154:157], v[198:201], v[54:57]
	v_mfma_f32_16x16x32_bf16 v[54:57], v[158:161], v[202:205], v[54:57]
	v_mfma_f32_16x16x32_bf16 v[38:41], v[154:157], v[206:209], v[38:41]
	v_mfma_f32_16x16x32_bf16 v[38:41], v[158:161], v[210:213], v[38:41]
	v_mfma_f32_16x16x32_bf16 v[22:25], v[154:157], v[214:217], v[22:25]
	v_mfma_f32_16x16x32_bf16 v[22:25], v[158:161], v[218:221], v[22:25]
	v_mfma_f32_16x16x32_bf16 v[14:17], v[162:165], v[214:217], v[14:17]
	v_mfma_f32_16x16x32_bf16 v[14:17], v[166:169], v[218:221], v[14:17]
	v_mfma_f32_16x16x32_bf16 v[30:33], v[162:165], v[206:209], v[30:33]
	v_mfma_f32_16x16x32_bf16 v[30:33], v[166:169], v[210:213], v[30:33]
	v_mfma_f32_16x16x32_bf16 v[46:49], v[162:165], v[198:201], v[46:49]
	v_mfma_f32_16x16x32_bf16 v[46:49], v[166:169], v[202:205], v[46:49]
	v_mfma_f32_16x16x32_bf16 v[58:61], v[162:165], v[190:193], v[58:61]
	v_mfma_f32_16x16x32_bf16 v[58:61], v[166:169], v[194:197], v[58:61]
	v_mfma_f32_16x16x32_bf16 v[50:53], v[170:173], v[190:193], v[50:53]
	v_mfma_f32_16x16x32_bf16 v[50:53], v[174:177], v[194:197], v[50:53]
	v_mfma_f32_16x16x32_bf16 v[34:37], v[170:173], v[198:201], v[34:37]
	v_mfma_f32_16x16x32_bf16 v[34:37], v[174:177], v[202:205], v[34:37]
	v_mfma_f32_16x16x32_bf16 v[18:21], v[170:173], v[206:209], v[18:21]
	v_mfma_f32_16x16x32_bf16 v[18:21], v[174:177], v[210:213], v[18:21]
	v_mfma_f32_16x16x32_bf16 v[6:9], v[170:173], v[214:217], v[6:9]
	v_mfma_f32_16x16x32_bf16 v[6:9], v[174:177], v[218:221], v[6:9]
	v_mfma_f32_16x16x32_bf16 v[2:5], v[182:185], v[214:217], v[2:5]
	v_mfma_f32_16x16x32_bf16 v[2:5], v[186:189], v[218:221], v[2:5]
	v_mfma_f32_16x16x32_bf16 v[10:13], v[182:185], v[206:209], v[10:13]
	v_mfma_f32_16x16x32_bf16 v[10:13], v[186:189], v[210:213], v[10:13]
	v_mfma_f32_16x16x32_bf16 v[26:29], v[182:185], v[198:201], v[26:29]
	v_mfma_f32_16x16x32_bf16 v[26:29], v[186:189], v[202:205], v[26:29]
	v_mfma_f32_16x16x32_bf16 v[42:45], v[182:185], v[190:193], v[42:45]
	v_mfma_f32_16x16x32_bf16 v[42:45], v[186:189], v[194:197], v[42:45]
	s_barrier
	s_setprio 0
	s_add_i32 s62, 0, 0x18000
	v_add_u32_e32 v153, s62, v148
	s_add_i32 s63, 0, 0x1c000
	ds_read_b128 v[154:157], v153
	ds_read_b128 v[158:161], v153 offset:1024
	ds_read_b128 v[162:165], v153 offset:2048
	ds_read_b128 v[166:169], v153 offset:3072
	v_add_u32_e32 v153, s63, v148
	ds_read_b128 v[170:173], v153
	ds_read_b128 v[174:177], v153 offset:1024
	ds_read_b128 v[182:185], v153 offset:2048
	ds_read_b128 v[186:189], v153 offset:3072
	s_add_u32 s30, s30, 0x80000
	s_addc_u32 s31, s31, 0
	s_mov_b32 m0, s39
	v_lshl_add_u64 v[228:229], s[30:31], 0, v[130:131]
	ds_read_b128 v[190:193], v152 offset:32768
	ds_read_b128 v[194:197], v152 offset:33792
	ds_read_b128 v[198:201], v152 offset:34816
	ds_read_b128 v[202:205], v152 offset:35840
	ds_read_b128 v[206:209], v152 offset:36864
	ds_read_b128 v[210:213], v152 offset:37888
	ds_read_b128 v[214:217], v152 offset:38912
	ds_read_b128 v[218:221], v152 offset:39936
	global_load_lds_dwordx4 v[228:229], off
	v_lshl_add_u64 v[228:229], s[30:31], 0, v[134:135]
	s_mov_b32 m0, s42
	s_nop 0
	global_load_lds_dwordx4 v[228:229], off
	s_waitcnt vmcnt(8)
	s_waitcnt lgkmcnt(0)
	s_setprio 1
	s_barrier
	v_mfma_f32_16x16x32_bf16 v[126:129], v[154:157], v[190:193], v[126:129]
	v_mfma_f32_16x16x32_bf16 v[126:129], v[158:161], v[194:197], v[126:129]
	v_mfma_f32_16x16x32_bf16 v[118:121], v[154:157], v[198:201], v[118:121]
	v_mfma_f32_16x16x32_bf16 v[118:121], v[158:161], v[202:205], v[118:121]
	v_mfma_f32_16x16x32_bf16 v[102:105], v[154:157], v[206:209], v[102:105]
	v_mfma_f32_16x16x32_bf16 v[102:105], v[158:161], v[210:213], v[102:105]
	v_mfma_f32_16x16x32_bf16 v[86:89], v[154:157], v[214:217], v[86:89]
	v_mfma_f32_16x16x32_bf16 v[86:89], v[158:161], v[218:221], v[86:89]
	v_mfma_f32_16x16x32_bf16 v[78:81], v[162:165], v[214:217], v[78:81]
	v_mfma_f32_16x16x32_bf16 v[78:81], v[166:169], v[218:221], v[78:81]
	v_mfma_f32_16x16x32_bf16 v[94:97], v[162:165], v[206:209], v[94:97]
	v_mfma_f32_16x16x32_bf16 v[94:97], v[166:169], v[210:213], v[94:97]
	v_mfma_f32_16x16x32_bf16 v[110:113], v[162:165], v[198:201], v[110:113]
	v_mfma_f32_16x16x32_bf16 v[110:113], v[166:169], v[202:205], v[110:113]
	v_mfma_f32_16x16x32_bf16 v[122:125], v[162:165], v[190:193], v[122:125]
	v_mfma_f32_16x16x32_bf16 v[122:125], v[166:169], v[194:197], v[122:125]
	v_mfma_f32_16x16x32_bf16 v[114:117], v[170:173], v[190:193], v[114:117]
	v_mfma_f32_16x16x32_bf16 v[114:117], v[174:177], v[194:197], v[114:117]
	v_mfma_f32_16x16x32_bf16 v[98:101], v[170:173], v[198:201], v[98:101]
	v_mfma_f32_16x16x32_bf16 v[98:101], v[174:177], v[202:205], v[98:101]
	v_mfma_f32_16x16x32_bf16 v[82:85], v[170:173], v[206:209], v[82:85]
	v_mfma_f32_16x16x32_bf16 v[82:85], v[174:177], v[210:213], v[82:85]
	v_mfma_f32_16x16x32_bf16 v[70:73], v[170:173], v[214:217], v[70:73]
	v_mfma_f32_16x16x32_bf16 v[70:73], v[174:177], v[218:221], v[70:73]
	v_mfma_f32_16x16x32_bf16 v[66:69], v[182:185], v[214:217], v[66:69]
	v_mfma_f32_16x16x32_bf16 v[66:69], v[186:189], v[218:221], v[66:69]
	v_mfma_f32_16x16x32_bf16 v[74:77], v[182:185], v[206:209], v[74:77]
	v_mfma_f32_16x16x32_bf16 v[74:77], v[186:189], v[210:213], v[74:77]
	v_mfma_f32_16x16x32_bf16 v[90:93], v[182:185], v[198:201], v[90:93]
	v_mfma_f32_16x16x32_bf16 v[90:93], v[186:189], v[202:205], v[90:93]
	v_mfma_f32_16x16x32_bf16 v[106:109], v[182:185], v[190:193], v[106:109]
	v_mfma_f32_16x16x32_bf16 v[106:109], v[186:189], v[194:197], v[106:109]
	s_barrier
	s_setprio 0
	s_add_i32 s30, s62, s37
	v_lshl_add_u64 v[146:147], v[146:147], 0, s[6:7]
	s_mov_b32 m0, s30
	ds_read_b128 v[190:193], v152 offset:49152
	ds_read_b128 v[194:197], v152 offset:50176
	ds_read_b128 v[198:201], v152 offset:51200
	ds_read_b128 v[202:205], v152 offset:52224
	ds_read_b128 v[206:209], v152 offset:53248
	ds_read_b128 v[210:213], v152 offset:54272
	ds_read_b128 v[214:217], v152 offset:55296
	ds_read_b128 v[218:221], v152 offset:56320
	global_load_lds_dwordx4 v[146:147], off
	s_add_i32 m0, s30, 0x2000
	s_add_u32 s28, s28, 0x80080
	v_lshl_add_u64 v[146:147], v[222:223], 0, s[6:7]
	s_addc_u32 s29, s29, 0
	s_add_i32 s30, s63, s37
	global_load_lds_dwordx4 v[146:147], off
	v_lshl_add_u64 v[146:147], s[28:29], 0, v[132:133]
	s_mov_b32 m0, s30
	s_nop 0
	global_load_lds_dwordx4 v[146:147], off
	v_lshl_add_u64 v[146:147], s[28:29], 0, v[136:137]
	s_add_i32 m0, s30, 0x2000
	s_nop 0
	global_load_lds_dwordx4 v[146:147], off
	v_lshl_add_u64 v[146:147], v[224:225], 0, s[6:7]
	s_mov_b32 m0, s44
	s_nop 0
	global_load_lds_dwordx4 v[146:147], off
	v_lshl_add_u64 v[146:147], v[226:227], 0, s[6:7]
	s_mov_b32 m0, s45
	s_nop 0
	global_load_lds_dwordx4 v[146:147], off
	s_waitcnt vmcnt(8)
	s_waitcnt lgkmcnt(0)
	s_setprio 1
	s_barrier
	v_mfma_f32_16x16x32_bf16 v[62:65], v[154:157], v[190:193], v[62:65]
	v_mfma_f32_16x16x32_bf16 v[62:65], v[158:161], v[194:197], v[62:65]
	v_mfma_f32_16x16x32_bf16 v[54:57], v[154:157], v[198:201], v[54:57]
	v_mfma_f32_16x16x32_bf16 v[54:57], v[158:161], v[202:205], v[54:57]
	v_mfma_f32_16x16x32_bf16 v[38:41], v[154:157], v[206:209], v[38:41]
	v_mfma_f32_16x16x32_bf16 v[38:41], v[158:161], v[210:213], v[38:41]
	v_mfma_f32_16x16x32_bf16 v[22:25], v[154:157], v[214:217], v[22:25]
	v_mfma_f32_16x16x32_bf16 v[22:25], v[158:161], v[218:221], v[22:25]
	v_mfma_f32_16x16x32_bf16 v[14:17], v[162:165], v[214:217], v[14:17]
	v_mfma_f32_16x16x32_bf16 v[14:17], v[166:169], v[218:221], v[14:17]
	v_mfma_f32_16x16x32_bf16 v[30:33], v[162:165], v[206:209], v[30:33]
	v_mfma_f32_16x16x32_bf16 v[30:33], v[166:169], v[210:213], v[30:33]
	v_mfma_f32_16x16x32_bf16 v[46:49], v[162:165], v[198:201], v[46:49]
	v_mfma_f32_16x16x32_bf16 v[46:49], v[166:169], v[202:205], v[46:49]
	v_mfma_f32_16x16x32_bf16 v[58:61], v[162:165], v[190:193], v[58:61]
	v_mfma_f32_16x16x32_bf16 v[58:61], v[166:169], v[194:197], v[58:61]
	v_mfma_f32_16x16x32_bf16 v[50:53], v[170:173], v[190:193], v[50:53]
	v_mfma_f32_16x16x32_bf16 v[50:53], v[174:177], v[194:197], v[50:53]
	v_mfma_f32_16x16x32_bf16 v[34:37], v[170:173], v[198:201], v[34:37]
	v_mfma_f32_16x16x32_bf16 v[34:37], v[174:177], v[202:205], v[34:37]
	v_mfma_f32_16x16x32_bf16 v[18:21], v[170:173], v[206:209], v[18:21]
	v_mfma_f32_16x16x32_bf16 v[18:21], v[174:177], v[210:213], v[18:21]
	v_mfma_f32_16x16x32_bf16 v[6:9], v[170:173], v[214:217], v[6:9]
	v_mfma_f32_16x16x32_bf16 v[6:9], v[174:177], v[218:221], v[6:9]
	v_mfma_f32_16x16x32_bf16 v[2:5], v[182:185], v[214:217], v[2:5]
	v_mfma_f32_16x16x32_bf16 v[2:5], v[186:189], v[218:221], v[2:5]
	v_mfma_f32_16x16x32_bf16 v[10:13], v[182:185], v[206:209], v[10:13]
	v_mfma_f32_16x16x32_bf16 v[10:13], v[186:189], v[210:213], v[10:13]
	v_mfma_f32_16x16x32_bf16 v[26:29], v[182:185], v[198:201], v[26:29]
	v_mfma_f32_16x16x32_bf16 v[26:29], v[186:189], v[202:205], v[26:29]
	v_mfma_f32_16x16x32_bf16 v[42:45], v[182:185], v[190:193], v[42:45]
	v_mfma_f32_16x16x32_bf16 v[42:45], v[186:189], v[194:197], v[42:45]
	s_barrier
	s_setprio 0
	s_add_i32 s60, s60, 2
	s_add_u32 s26, s26, 0x100
	s_addc_u32 s27, s27, 0
	s_add_u32 s58, s58, 0x100
	s_addc_u32 s59, s59, 0
	s_cmp_gt_u32 s60, 29
	s_cbranch_scc0 .LBB0_3060
	s_and_b64 vcc, exec, s[8:9]
	s_cbranch_vccz .LBB0_3063
	s_barrier

.LBB0_3191:
	ds_read_b128 v[154:157], v150
	ds_read_b128 v[158:161], v150 offset:1024
	ds_read_b128 v[162:165], v150 offset:2048
	ds_read_b128 v[166:169], v150 offset:3072
	ds_read_b128 v[170:173], v151
	ds_read_b128 v[174:177], v151 offset:1024
	ds_read_b128 v[182:185], v151 offset:2048
	ds_read_b128 v[186:189], v151 offset:3072
	s_add_u32 s20, s18, 0xfff80080
	s_addc_u32 s21, s19, -1
	s_cmp_eq_u32 s50, 28
	s_cselect_b32 s23, s11, s21
	s_cselect_b32 s22, s44, s20
	s_cselect_b32 s21, s9, s47
	s_cselect_b32 s20, s45, s46
	v_lshl_add_u64 v[146:147], s[18:19], 0, v[138:139]
	s_add_i32 m0, s17, 0xc000
	ds_read_b128 v[190:193], v152
	ds_read_b128 v[194:197], v152 offset:1024
	ds_read_b128 v[198:201], v152 offset:2048
	ds_read_b128 v[202:205], v152 offset:3072
	ds_read_b128 v[206:209], v152 offset:4096
	ds_read_b128 v[210:213], v152 offset:5120
	ds_read_b128 v[214:217], v152 offset:6144
	ds_read_b128 v[218:221], v152 offset:7168
	global_load_lds_dwordx4 v[146:147], off
	v_lshl_add_u64 v[146:147], s[18:19], 0, v[140:141]
	s_add_i32 m0, s17, 0xe000
	s_nop 0
	global_load_lds_dwordx4 v[146:147], off
	s_waitcnt vmcnt(8)
	s_waitcnt lgkmcnt(0)
	s_setprio 1
	s_barrier
	v_mfma_f32_16x16x32_bf16 v[126:129], v[154:157], v[190:193], v[126:129]
	v_mfma_f32_16x16x32_bf16 v[126:129], v[158:161], v[194:197], v[126:129]
	v_mfma_f32_16x16x32_bf16 v[110:113], v[154:157], v[198:201], v[110:113]
	v_mfma_f32_16x16x32_bf16 v[110:113], v[158:161], v[202:205], v[110:113]
	v_mfma_f32_16x16x32_bf16 v[94:97], v[154:157], v[206:209], v[94:97]
	v_mfma_f32_16x16x32_bf16 v[94:97], v[158:161], v[210:213], v[94:97]
	v_mfma_f32_16x16x32_bf16 v[78:81], v[154:157], v[214:217], v[78:81]
	v_mfma_f32_16x16x32_bf16 v[78:81], v[158:161], v[218:221], v[78:81]
	v_mfma_f32_16x16x32_bf16 v[74:77], v[162:165], v[214:217], v[74:77]
	v_mfma_f32_16x16x32_bf16 v[74:77], v[166:169], v[218:221], v[74:77]
	v_mfma_f32_16x16x32_bf16 v[90:93], v[162:165], v[206:209], v[90:93]
	v_mfma_f32_16x16x32_bf16 v[90:93], v[166:169], v[210:213], v[90:93]
	v_mfma_f32_16x16x32_bf16 v[106:109], v[162:165], v[198:201], v[106:109]
	v_mfma_f32_16x16x32_bf16 v[106:109], v[166:169], v[202:205], v[106:109]
	v_mfma_f32_16x16x32_bf16 v[122:125], v[162:165], v[190:193], v[122:125]
	v_mfma_f32_16x16x32_bf16 v[122:125], v[166:169], v[194:197], v[122:125]
	v_mfma_f32_16x16x32_bf16 v[118:121], v[170:173], v[190:193], v[118:121]
	v_mfma_f32_16x16x32_bf16 v[118:121], v[174:177], v[194:197], v[118:121]
	v_mfma_f32_16x16x32_bf16 v[102:105], v[170:173], v[198:201], v[102:105]
	v_mfma_f32_16x16x32_bf16 v[102:105], v[174:177], v[202:205], v[102:105]
	v_mfma_f32_16x16x32_bf16 v[86:89], v[170:173], v[206:209], v[86:89]
	v_mfma_f32_16x16x32_bf16 v[86:89], v[174:177], v[210:213], v[86:89]
	v_mfma_f32_16x16x32_bf16 v[70:73], v[170:173], v[214:217], v[70:73]
	v_mfma_f32_16x16x32_bf16 v[70:73], v[174:177], v[218:221], v[70:73]
	v_mfma_f32_16x16x32_bf16 v[66:69], v[182:185], v[214:217], v[66:69]
	v_mfma_f32_16x16x32_bf16 v[66:69], v[186:189], v[218:221], v[66:69]
	v_mfma_f32_16x16x32_bf16 v[82:85], v[182:185], v[206:209], v[82:85]
	v_mfma_f32_16x16x32_bf16 v[82:85], v[186:189], v[210:213], v[82:85]
	v_mfma_f32_16x16x32_bf16 v[98:101], v[182:185], v[198:201], v[98:101]
	v_mfma_f32_16x16x32_bf16 v[98:101], v[186:189], v[202:205], v[98:101]
	v_mfma_f32_16x16x32_bf16 v[114:117], v[182:185], v[190:193], v[114:117]
	v_mfma_f32_16x16x32_bf16 v[114:117], v[186:189], v[194:197], v[114:117]
	s_barrier
	s_setprio 0
	s_add_i32 s51, s38, s26
	v_lshl_add_u64 v[146:147], s[20:21], 0, v[134:135]
	s_mov_b32 m0, s51
	ds_read_b128 v[190:193], v152 offset:16384
	ds_read_b128 v[194:197], v152 offset:17408
	ds_read_b128 v[198:201], v152 offset:18432
	ds_read_b128 v[202:205], v152 offset:19456
	ds_read_b128 v[206:209], v152 offset:20480
	ds_read_b128 v[210:213], v152 offset:21504
	ds_read_b128 v[214:217], v152 offset:22528
	ds_read_b128 v[218:221], v152 offset:23552
	global_load_lds_dwordx4 v[146:147], off
	s_add_i32 m0, s51, 0x2000
	s_add_u32 s52, s20, 0x80000
	v_lshl_add_u64 v[222:223], s[20:21], 0, v[130:131]
	s_addc_u32 s53, s21, 0
	s_add_i32 s51, s39, s26
	global_load_lds_dwordx4 v[222:223], off
	v_lshl_add_u64 v[224:225], s[52:53], 0, v[134:135]
	s_mov_b32 m0, s51
	v_lshl_add_u64 v[226:227], s[22:23], 0, v[132:133]
	global_load_lds_dwordx4 v[224:225], off
	v_lshl_add_u64 v[224:225], s[52:53], 0, v[130:131]
	s_add_i32 m0, s51, 0x2000
	s_nop 0
	global_load_lds_dwordx4 v[224:225], off
	v_lshl_add_u64 v[224:225], s[22:23], 0, v[136:137]
	s_mov_b32 m0, s17
	s_nop 0
	global_load_lds_dwordx4 v[224:225], off
	s_mov_b32 m0, s29
	s_nop 0
	global_load_lds_dwordx4 v[226:227], off
	s_waitcnt vmcnt(8)
	s_waitcnt lgkmcnt(0)
	s_setprio 1
	s_barrier
	v_mfma_f32_16x16x32_bf16 v[62:65], v[154:157], v[190:193], v[62:65]
	v_mfma_f32_16x16x32_bf16 v[62:65], v[158:161], v[194:197], v[62:65]
	v_mfma_f32_16x16x32_bf16 v[46:49], v[154:157], v[198:201], v[46:49]
	v_mfma_f32_16x16x32_bf16 v[46:49], v[158:161], v[202:205], v[46:49]
	v_mfma_f32_16x16x32_bf16 v[30:33], v[154:157], v[206:209], v[30:33]
	v_mfma_f32_16x16x32_bf16 v[30:33], v[158:161], v[210:213], v[30:33]
	v_mfma_f32_16x16x32_bf16 v[14:17], v[154:157], v[214:217], v[14:17]
	v_mfma_f32_16x16x32_bf16 v[14:17], v[158:161], v[218:221], v[14:17]
	v_mfma_f32_16x16x32_bf16 v[10:13], v[162:165], v[214:217], v[10:13]
	v_mfma_f32_16x16x32_bf16 v[10:13], v[166:169], v[218:221], v[10:13]
	v_mfma_f32_16x16x32_bf16 v[26:29], v[162:165], v[206:209], v[26:29]
	v_mfma_f32_16x16x32_bf16 v[26:29], v[166:169], v[210:213], v[26:29]
	v_mfma_f32_16x16x32_bf16 v[42:45], v[162:165], v[198:201], v[42:45]
	v_mfma_f32_16x16x32_bf16 v[42:45], v[166:169], v[202:205], v[42:45]
	v_mfma_f32_16x16x32_bf16 v[58:61], v[162:165], v[190:193], v[58:61]
	v_mfma_f32_16x16x32_bf16 v[58:61], v[166:169], v[194:197], v[58:61]
	v_mfma_f32_16x16x32_bf16 v[54:57], v[170:173], v[190:193], v[54:57]
	v_mfma_f32_16x16x32_bf16 v[54:57], v[174:177], v[194:197], v[54:57]
	v_mfma_f32_16x16x32_bf16 v[38:41], v[170:173], v[198:201], v[38:41]
	v_mfma_f32_16x16x32_bf16 v[38:41], v[174:177], v[202:205], v[38:41]
	v_mfma_f32_16x16x32_bf16 v[22:25], v[170:173], v[206:209], v[22:25]
	v_mfma_f32_16x16x32_bf16 v[22:25], v[174:177], v[210:213], v[22:25]
	v_mfma_f32_16x16x32_bf16 v[6:9], v[170:173], v[214:217], v[6:9]
	v_mfma_f32_16x16x32_bf16 v[6:9], v[174:177], v[218:221], v[6:9]
	v_mfma_f32_16x16x32_bf16 v[2:5], v[182:185], v[214:217], v[2:5]
	v_mfma_f32_16x16x32_bf16 v[2:5], v[186:189], v[218:221], v[2:5]
	v_mfma_f32_16x16x32_bf16 v[18:21], v[182:185], v[206:209], v[18:21]
	v_mfma_f32_16x16x32_bf16 v[18:21], v[186:189], v[210:213], v[18:21]
	v_mfma_f32_16x16x32_bf16 v[34:37], v[182:185], v[198:201], v[34:37]
	v_mfma_f32_16x16x32_bf16 v[34:37], v[186:189], v[202:205], v[34:37]
	v_mfma_f32_16x16x32_bf16 v[50:53], v[182:185], v[190:193], v[50:53]
	v_mfma_f32_16x16x32_bf16 v[50:53], v[186:189], v[194:197], v[50:53]
	s_barrier
	s_setprio 0
	s_add_i32 s51, 0, 0x18000
	v_add_u32_e32 v153, s51, v148
	s_add_i32 s52, 0, 0x1c000
	ds_read_b128 v[154:157], v153
	ds_read_b128 v[158:161], v153 offset:1024
	ds_read_b128 v[162:165], v153 offset:2048
	ds_read_b128 v[166:169], v153 offset:3072
	v_add_u32_e32 v153, s52, v148
	ds_read_b128 v[170:173], v153
	ds_read_b128 v[174:177], v153 offset:1024
	ds_read_b128 v[182:185], v153 offset:2048
	ds_read_b128 v[186:189], v153 offset:3072
	s_add_u32 s22, s22, 0x80000
	s_addc_u32 s23, s23, 0
	s_mov_b32 m0, s30
	v_lshl_add_u64 v[228:229], s[22:23], 0, v[136:137]
	ds_read_b128 v[190:193], v152 offset:32768
	ds_read_b128 v[194:197], v152 offset:33792
	ds_read_b128 v[198:201], v152 offset:34816
	ds_read_b128 v[202:205], v152 offset:35840
	ds_read_b128 v[206:209], v152 offset:36864
	ds_read_b128 v[210:213], v152 offset:37888
	ds_read_b128 v[214:217], v152 offset:38912
	ds_read_b128 v[218:221], v152 offset:39936
	global_load_lds_dwordx4 v[228:229], off
	v_lshl_add_u64 v[228:229], s[22:23], 0, v[132:133]
	s_mov_b32 m0, s31
	s_nop 0
	global_load_lds_dwordx4 v[228:229], off
	s_waitcnt vmcnt(8)
	s_waitcnt lgkmcnt(0)
	s_setprio 1
	s_barrier
	v_mfma_f32_16x16x32_bf16 v[126:129], v[154:157], v[190:193], v[126:129]
	v_mfma_f32_16x16x32_bf16 v[126:129], v[158:161], v[194:197], v[126:129]
	v_mfma_f32_16x16x32_bf16 v[110:113], v[154:157], v[198:201], v[110:113]
	v_mfma_f32_16x16x32_bf16 v[110:113], v[158:161], v[202:205], v[110:113]
	v_mfma_f32_16x16x32_bf16 v[94:97], v[154:157], v[206:209], v[94:97]
	v_mfma_f32_16x16x32_bf16 v[94:97], v[158:161], v[210:213], v[94:97]
	v_mfma_f32_16x16x32_bf16 v[78:81], v[154:157], v[214:217], v[78:81]
	v_mfma_f32_16x16x32_bf16 v[78:81], v[158:161], v[218:221], v[78:81]
	v_mfma_f32_16x16x32_bf16 v[74:77], v[162:165], v[214:217], v[74:77]
	v_mfma_f32_16x16x32_bf16 v[74:77], v[166:169], v[218:221], v[74:77]
	v_mfma_f32_16x16x32_bf16 v[90:93], v[162:165], v[206:209], v[90:93]
	v_mfma_f32_16x16x32_bf16 v[90:93], v[166:169], v[210:213], v[90:93]
	v_mfma_f32_16x16x32_bf16 v[106:109], v[162:165], v[198:201], v[106:109]
	v_mfma_f32_16x16x32_bf16 v[106:109], v[166:169], v[202:205], v[106:109]
	v_mfma_f32_16x16x32_bf16 v[122:125], v[162:165], v[190:193], v[122:125]
	v_mfma_f32_16x16x32_bf16 v[122:125], v[166:169], v[194:197], v[122:125]
	v_mfma_f32_16x16x32_bf16 v[118:121], v[170:173], v[190:193], v[118:121]
	v_mfma_f32_16x16x32_bf16 v[118:121], v[174:177], v[194:197], v[118:121]
	v_mfma_f32_16x16x32_bf16 v[102:105], v[170:173], v[198:201], v[102:105]
	v_mfma_f32_16x16x32_bf16 v[102:105], v[174:177], v[202:205], v[102:105]
	v_mfma_f32_16x16x32_bf16 v[86:89], v[170:173], v[206:209], v[86:89]
	v_mfma_f32_16x16x32_bf16 v[86:89], v[174:177], v[210:213], v[86:89]
	v_mfma_f32_16x16x32_bf16 v[70:73], v[170:173], v[214:217], v[70:73]
	v_mfma_f32_16x16x32_bf16 v[70:73], v[174:177], v[218:221], v[70:73]
	v_mfma_f32_16x16x32_bf16 v[66:69], v[182:185], v[214:217], v[66:69]
	v_mfma_f32_16x16x32_bf16 v[66:69], v[186:189], v[218:221], v[66:69]
	v_mfma_f32_16x16x32_bf16 v[82:85], v[182:185], v[206:209], v[82:85]
	v_mfma_f32_16x16x32_bf16 v[82:85], v[186:189], v[210:213], v[82:85]
	v_mfma_f32_16x16x32_bf16 v[98:101], v[182:185], v[198:201], v[98:101]
	v_mfma_f32_16x16x32_bf16 v[98:101], v[186:189], v[202:205], v[98:101]
	v_mfma_f32_16x16x32_bf16 v[114:117], v[182:185], v[190:193], v[114:117]
	v_mfma_f32_16x16x32_bf16 v[114:117], v[186:189], v[194:197], v[114:117]
	s_barrier
	s_setprio 0
	s_add_i32 s22, s51, s26
	v_lshl_add_u64 v[146:147], v[146:147], 0, s[4:5]
	s_mov_b32 m0, s22
	ds_read_b128 v[190:193], v152 offset:49152
	ds_read_b128 v[194:197], v152 offset:50176
	ds_read_b128 v[198:201], v152 offset:51200
	ds_read_b128 v[202:205], v152 offset:52224
	ds_read_b128 v[206:209], v152 offset:53248
	ds_read_b128 v[210:213], v152 offset:54272
	ds_read_b128 v[214:217], v152 offset:55296
	ds_read_b128 v[218:221], v152 offset:56320
	global_load_lds_dwordx4 v[146:147], off
	s_add_i32 m0, s22, 0x2000
	s_add_u32 s20, s20, 0x80080
	v_lshl_add_u64 v[146:147], v[222:223], 0, s[4:5]
	s_addc_u32 s21, s21, 0
	s_add_i32 s22, s52, s26
	global_load_lds_dwordx4 v[146:147], off
	v_lshl_add_u64 v[146:147], s[20:21], 0, v[134:135]
	s_mov_b32 m0, s22
	s_nop 0
	global_load_lds_dwordx4 v[146:147], off
	v_lshl_add_u64 v[146:147], s[20:21], 0, v[130:131]
	s_add_i32 m0, s22, 0x2000
	s_nop 0
	global_load_lds_dwordx4 v[146:147], off
	v_lshl_add_u64 v[146:147], v[224:225], 0, s[4:5]
	s_mov_b32 m0, s35
	s_nop 0
	global_load_lds_dwordx4 v[146:147], off
	v_lshl_add_u64 v[146:147], v[226:227], 0, s[4:5]
	s_mov_b32 m0, s36
	s_nop 0
	global_load_lds_dwordx4 v[146:147], off
	s_waitcnt vmcnt(8)
	s_waitcnt lgkmcnt(0)
	s_setprio 1
	s_barrier
	v_mfma_f32_16x16x32_bf16 v[62:65], v[154:157], v[190:193], v[62:65]
	v_mfma_f32_16x16x32_bf16 v[62:65], v[158:161], v[194:197], v[62:65]
	v_mfma_f32_16x16x32_bf16 v[46:49], v[154:157], v[198:201], v[46:49]
	v_mfma_f32_16x16x32_bf16 v[46:49], v[158:161], v[202:205], v[46:49]
	v_mfma_f32_16x16x32_bf16 v[30:33], v[154:157], v[206:209], v[30:33]
	v_mfma_f32_16x16x32_bf16 v[30:33], v[158:161], v[210:213], v[30:33]
	v_mfma_f32_16x16x32_bf16 v[14:17], v[154:157], v[214:217], v[14:17]
	v_mfma_f32_16x16x32_bf16 v[14:17], v[158:161], v[218:221], v[14:17]
	v_mfma_f32_16x16x32_bf16 v[10:13], v[162:165], v[214:217], v[10:13]
	v_mfma_f32_16x16x32_bf16 v[10:13], v[166:169], v[218:221], v[10:13]
	v_mfma_f32_16x16x32_bf16 v[26:29], v[162:165], v[206:209], v[26:29]
	v_mfma_f32_16x16x32_bf16 v[26:29], v[166:169], v[210:213], v[26:29]
	v_mfma_f32_16x16x32_bf16 v[42:45], v[162:165], v[198:201], v[42:45]
	v_mfma_f32_16x16x32_bf16 v[42:45], v[166:169], v[202:205], v[42:45]
	v_mfma_f32_16x16x32_bf16 v[58:61], v[162:165], v[190:193], v[58:61]
	v_mfma_f32_16x16x32_bf16 v[58:61], v[166:169], v[194:197], v[58:61]
	v_mfma_f32_16x16x32_bf16 v[54:57], v[170:173], v[190:193], v[54:57]
	v_mfma_f32_16x16x32_bf16 v[54:57], v[174:177], v[194:197], v[54:57]
	v_mfma_f32_16x16x32_bf16 v[38:41], v[170:173], v[198:201], v[38:41]
	v_mfma_f32_16x16x32_bf16 v[38:41], v[174:177], v[202:205], v[38:41]
	v_mfma_f32_16x16x32_bf16 v[22:25], v[170:173], v[206:209], v[22:25]
	v_mfma_f32_16x16x32_bf16 v[22:25], v[174:177], v[210:213], v[22:25]
	v_mfma_f32_16x16x32_bf16 v[6:9], v[170:173], v[214:217], v[6:9]
	v_mfma_f32_16x16x32_bf16 v[6:9], v[174:177], v[218:221], v[6:9]
	v_mfma_f32_16x16x32_bf16 v[2:5], v[182:185], v[214:217], v[2:5]
	v_mfma_f32_16x16x32_bf16 v[2:5], v[186:189], v[218:221], v[2:5]
	v_mfma_f32_16x16x32_bf16 v[18:21], v[182:185], v[206:209], v[18:21]
	v_mfma_f32_16x16x32_bf16 v[18:21], v[186:189], v[210:213], v[18:21]
	v_mfma_f32_16x16x32_bf16 v[34:37], v[182:185], v[198:201], v[34:37]
	v_mfma_f32_16x16x32_bf16 v[34:37], v[186:189], v[202:205], v[34:37]
	v_mfma_f32_16x16x32_bf16 v[50:53], v[182:185], v[190:193], v[50:53]
	v_mfma_f32_16x16x32_bf16 v[50:53], v[186:189], v[194:197], v[50:53]
	s_barrier
	s_setprio 0
	s_add_i32 s50, s50, 2
	s_add_u32 s18, s18, 0x100
	s_addc_u32 s19, s19, 0
	s_add_u32 s46, s46, 0x100
	s_addc_u32 s47, s47, 0
	s_cmp_gt_u32 s50, 29
	s_cbranch_scc0 .LBB0_3191
	s_and_b64 vcc, exec, s[6:7]
	s_cbranch_vccz .LBB0_3194
	s_barrier

.LBB0_3274:
	ds_read_b128 v[152:155], v149
	ds_read_b128 v[156:159], v149 offset:1024
	ds_read_b128 v[160:163], v149 offset:2048
	ds_read_b128 v[164:167], v149 offset:3072
	ds_read_b128 v[168:171], v150
	ds_read_b128 v[172:175], v150 offset:1024
	ds_read_b128 v[182:185], v150 offset:2048
	ds_read_b128 v[186:189], v150 offset:3072
	s_add_u32 s22, s20, 0xffea0080
	s_addc_u32 s23, s21, -1
	s_cmpk_eq_i32 s56, 0x54
	s_cselect_b32 s25, s3, s23
	s_cselect_b32 s24, s2, s22
	s_cselect_b32 s23, s19, s55
	s_cselect_b32 s22, s18, s54
	v_lshl_add_u64 v[144:145], s[20:21], 0, v[136:137]
	s_add_i32 m0, s30, 0xc000
	ds_read_b128 v[190:193], v151
	ds_read_b128 v[194:197], v151 offset:1024
	ds_read_b128 v[198:201], v151 offset:2048
	ds_read_b128 v[202:205], v151 offset:3072
	ds_read_b128 v[206:209], v151 offset:4096
	ds_read_b128 v[210:213], v151 offset:5120
	ds_read_b128 v[214:217], v151 offset:6144
	ds_read_b128 v[218:221], v151 offset:7168
	global_load_lds_dwordx4 v[144:145], off
	v_lshl_add_u64 v[144:145], s[20:21], 0, v[138:139]
	s_add_i32 m0, s30, 0xe000
	s_nop 0
	global_load_lds_dwordx4 v[144:145], off
	s_waitcnt vmcnt(8)
	s_waitcnt lgkmcnt(0)
	s_setprio 1
	s_barrier
	v_mfma_f32_16x16x32_bf16 v[124:127], v[152:155], v[190:193], v[124:127]
	v_mfma_f32_16x16x32_bf16 v[124:127], v[156:159], v[194:197], v[124:127]
	v_mfma_f32_16x16x32_bf16 v[116:119], v[152:155], v[198:201], v[116:119]
	v_mfma_f32_16x16x32_bf16 v[116:119], v[156:159], v[202:205], v[116:119]
	v_mfma_f32_16x16x32_bf16 v[100:103], v[152:155], v[206:209], v[100:103]
	v_mfma_f32_16x16x32_bf16 v[100:103], v[156:159], v[210:213], v[100:103]
	v_mfma_f32_16x16x32_bf16 v[84:87], v[152:155], v[214:217], v[84:87]
	v_mfma_f32_16x16x32_bf16 v[84:87], v[156:159], v[218:221], v[84:87]
	v_mfma_f32_16x16x32_bf16 v[76:79], v[160:163], v[214:217], v[76:79]
	v_mfma_f32_16x16x32_bf16 v[76:79], v[164:167], v[218:221], v[76:79]
	v_mfma_f32_16x16x32_bf16 v[92:95], v[160:163], v[206:209], v[92:95]
	v_mfma_f32_16x16x32_bf16 v[92:95], v[164:167], v[210:213], v[92:95]
	v_mfma_f32_16x16x32_bf16 v[108:111], v[160:163], v[198:201], v[108:111]
	v_mfma_f32_16x16x32_bf16 v[108:111], v[164:167], v[202:205], v[108:111]
	v_mfma_f32_16x16x32_bf16 v[120:123], v[160:163], v[190:193], v[120:123]
	v_mfma_f32_16x16x32_bf16 v[120:123], v[164:167], v[194:197], v[120:123]
	v_mfma_f32_16x16x32_bf16 v[112:115], v[168:171], v[190:193], v[112:115]
	v_mfma_f32_16x16x32_bf16 v[112:115], v[172:175], v[194:197], v[112:115]
	v_mfma_f32_16x16x32_bf16 v[96:99], v[168:171], v[198:201], v[96:99]
	v_mfma_f32_16x16x32_bf16 v[96:99], v[172:175], v[202:205], v[96:99]
	v_mfma_f32_16x16x32_bf16 v[80:83], v[168:171], v[206:209], v[80:83]
	v_mfma_f32_16x16x32_bf16 v[80:83], v[172:175], v[210:213], v[80:83]
	v_mfma_f32_16x16x32_bf16 v[68:71], v[168:171], v[214:217], v[68:71]
	v_mfma_f32_16x16x32_bf16 v[68:71], v[172:175], v[218:221], v[68:71]
	v_mfma_f32_16x16x32_bf16 v[64:67], v[182:185], v[214:217], v[64:67]
	v_mfma_f32_16x16x32_bf16 v[64:67], v[186:189], v[218:221], v[64:67]
	v_mfma_f32_16x16x32_bf16 v[72:75], v[182:185], v[206:209], v[72:75]
	v_mfma_f32_16x16x32_bf16 v[72:75], v[186:189], v[210:213], v[72:75]
	v_mfma_f32_16x16x32_bf16 v[88:91], v[182:185], v[198:201], v[88:91]
	v_mfma_f32_16x16x32_bf16 v[88:91], v[186:189], v[202:205], v[88:91]
	v_mfma_f32_16x16x32_bf16 v[104:107], v[182:185], v[190:193], v[104:107]
	v_mfma_f32_16x16x32_bf16 v[104:107], v[186:189], v[194:197], v[104:107]
	s_barrier
	s_setprio 0
	s_add_i32 s57, s42, s29
	v_lshl_add_u64 v[144:145], s[22:23], 0, v[130:131]
	s_mov_b32 m0, s57
	ds_read_b128 v[190:193], v151 offset:16384
	ds_read_b128 v[194:197], v151 offset:17408
	ds_read_b128 v[198:201], v151 offset:18432
	ds_read_b128 v[202:205], v151 offset:19456
	ds_read_b128 v[206:209], v151 offset:20480
	ds_read_b128 v[210:213], v151 offset:21504
	ds_read_b128 v[214:217], v151 offset:22528
	ds_read_b128 v[218:221], v151 offset:23552
	global_load_lds_dwordx4 v[144:145], off
	s_add_i32 m0, s57, 0x2000
	s_add_u32 s58, s22, 0x160000
	v_lshl_add_u64 v[176:177], s[22:23], 0, v[134:135]
	s_addc_u32 s59, s23, 0
	s_add_i32 s57, s43, s29
	global_load_lds_dwordx4 v[176:177], off
	v_lshl_add_u64 v[222:223], s[58:59], 0, v[130:131]
	s_mov_b32 m0, s57
	v_lshl_add_u64 v[224:225], s[24:25], 0, v[132:133]
	global_load_lds_dwordx4 v[222:223], off
	v_lshl_add_u64 v[222:223], s[58:59], 0, v[134:135]
	s_add_i32 m0, s57, 0x2000
	s_nop 0
	global_load_lds_dwordx4 v[222:223], off
	v_lshl_add_u64 v[222:223], s[24:25], 0, v[128:129]
	s_mov_b32 m0, s30
	s_nop 0
	global_load_lds_dwordx4 v[222:223], off
	s_mov_b32 m0, s31
	s_nop 0
	global_load_lds_dwordx4 v[224:225], off
	s_waitcnt vmcnt(8)
	s_waitcnt lgkmcnt(0)
	s_setprio 1
	s_barrier
	v_mfma_f32_16x16x32_bf16 v[60:63], v[152:155], v[190:193], v[60:63]
	v_mfma_f32_16x16x32_bf16 v[60:63], v[156:159], v[194:197], v[60:63]
	v_mfma_f32_16x16x32_bf16 v[52:55], v[152:155], v[198:201], v[52:55]
	v_mfma_f32_16x16x32_bf16 v[52:55], v[156:159], v[202:205], v[52:55]
	v_mfma_f32_16x16x32_bf16 v[36:39], v[152:155], v[206:209], v[36:39]
	v_mfma_f32_16x16x32_bf16 v[36:39], v[156:159], v[210:213], v[36:39]
	v_mfma_f32_16x16x32_bf16 v[20:23], v[152:155], v[214:217], v[20:23]
	v_mfma_f32_16x16x32_bf16 v[20:23], v[156:159], v[218:221], v[20:23]
	v_mfma_f32_16x16x32_bf16 v[12:15], v[160:163], v[214:217], v[12:15]
	v_mfma_f32_16x16x32_bf16 v[12:15], v[164:167], v[218:221], v[12:15]
	v_mfma_f32_16x16x32_bf16 v[28:31], v[160:163], v[206:209], v[28:31]
	v_mfma_f32_16x16x32_bf16 v[28:31], v[164:167], v[210:213], v[28:31]
	v_mfma_f32_16x16x32_bf16 v[44:47], v[160:163], v[198:201], v[44:47]
	v_mfma_f32_16x16x32_bf16 v[44:47], v[164:167], v[202:205], v[44:47]
	v_mfma_f32_16x16x32_bf16 v[56:59], v[160:163], v[190:193], v[56:59]
	v_mfma_f32_16x16x32_bf16 v[56:59], v[164:167], v[194:197], v[56:59]
	v_mfma_f32_16x16x32_bf16 v[48:51], v[168:171], v[190:193], v[48:51]
	v_mfma_f32_16x16x32_bf16 v[48:51], v[172:175], v[194:197], v[48:51]
	v_mfma_f32_16x16x32_bf16 v[32:35], v[168:171], v[198:201], v[32:35]
	v_mfma_f32_16x16x32_bf16 v[32:35], v[172:175], v[202:205], v[32:35]
	v_mfma_f32_16x16x32_bf16 v[16:19], v[168:171], v[206:209], v[16:19]
	v_mfma_f32_16x16x32_bf16 v[16:19], v[172:175], v[210:213], v[16:19]
	v_mfma_f32_16x16x32_bf16 v[4:7], v[168:171], v[214:217], v[4:7]
	v_mfma_f32_16x16x32_bf16 v[4:7], v[172:175], v[218:221], v[4:7]
	v_mfma_f32_16x16x32_bf16 v[0:3], v[182:185], v[214:217], v[0:3]
	v_mfma_f32_16x16x32_bf16 v[0:3], v[186:189], v[218:221], v[0:3]
	v_mfma_f32_16x16x32_bf16 v[8:11], v[182:185], v[206:209], v[8:11]
	v_mfma_f32_16x16x32_bf16 v[8:11], v[186:189], v[210:213], v[8:11]
	v_mfma_f32_16x16x32_bf16 v[24:27], v[182:185], v[198:201], v[24:27]
	v_mfma_f32_16x16x32_bf16 v[24:27], v[186:189], v[202:205], v[24:27]
	v_mfma_f32_16x16x32_bf16 v[40:43], v[182:185], v[190:193], v[40:43]
	v_mfma_f32_16x16x32_bf16 v[40:43], v[186:189], v[194:197], v[40:43]
	s_barrier
	s_setprio 0
	s_add_i32 s57, 0, 0x18000
	s_add_i32 s58, 0, 0x1c000
	v_add_u32_e32 v164, s57, v147
	v_add_u32_e32 v179, s58, v147
	ds_read_b128 v[152:155], v164
	ds_read_b128 v[156:159], v164 offset:1024
	ds_read_b128 v[160:163], v164 offset:2048
	ds_read_b128 v[164:167], v164 offset:3072
	ds_read_b128 v[168:171], v179
	ds_read_b128 v[172:175], v179 offset:1024
	ds_read_b128 v[182:185], v179 offset:2048
	ds_read_b128 v[186:189], v179 offset:3072
	s_add_u32 s24, s24, 0x160000
	s_addc_u32 s25, s25, 0
	s_mov_b32 m0, s34
	v_lshl_add_u64 v[226:227], s[24:25], 0, v[128:129]
	ds_read_b128 v[190:193], v151 offset:32768
	ds_read_b128 v[194:197], v151 offset:33792
	ds_read_b128 v[198:201], v151 offset:34816
	ds_read_b128 v[202:205], v151 offset:35840
	ds_read_b128 v[206:209], v151 offset:36864
	ds_read_b128 v[210:213], v151 offset:37888
	ds_read_b128 v[214:217], v151 offset:38912
	ds_read_b128 v[218:221], v151 offset:39936
	global_load_lds_dwordx4 v[226:227], off
	v_lshl_add_u64 v[226:227], s[24:25], 0, v[132:133]
	s_mov_b32 m0, s35
	s_nop 0
	global_load_lds_dwordx4 v[226:227], off
	s_waitcnt vmcnt(8)
	s_waitcnt lgkmcnt(0)
	s_setprio 1
	s_barrier
	v_mfma_f32_16x16x32_bf16 v[124:127], v[152:155], v[190:193], v[124:127]
	v_mfma_f32_16x16x32_bf16 v[124:127], v[156:159], v[194:197], v[124:127]
	v_mfma_f32_16x16x32_bf16 v[116:119], v[152:155], v[198:201], v[116:119]
	v_mfma_f32_16x16x32_bf16 v[116:119], v[156:159], v[202:205], v[116:119]
	v_mfma_f32_16x16x32_bf16 v[100:103], v[152:155], v[206:209], v[100:103]
	v_mfma_f32_16x16x32_bf16 v[100:103], v[156:159], v[210:213], v[100:103]
	v_mfma_f32_16x16x32_bf16 v[84:87], v[152:155], v[214:217], v[84:87]
	v_mfma_f32_16x16x32_bf16 v[84:87], v[156:159], v[218:221], v[84:87]
	v_mfma_f32_16x16x32_bf16 v[76:79], v[160:163], v[214:217], v[76:79]
	v_mfma_f32_16x16x32_bf16 v[76:79], v[164:167], v[218:221], v[76:79]
	v_mfma_f32_16x16x32_bf16 v[92:95], v[160:163], v[206:209], v[92:95]
	v_mfma_f32_16x16x32_bf16 v[92:95], v[164:167], v[210:213], v[92:95]
	v_mfma_f32_16x16x32_bf16 v[108:111], v[160:163], v[198:201], v[108:111]
	v_mfma_f32_16x16x32_bf16 v[108:111], v[164:167], v[202:205], v[108:111]
	v_mfma_f32_16x16x32_bf16 v[120:123], v[160:163], v[190:193], v[120:123]
	v_mfma_f32_16x16x32_bf16 v[120:123], v[164:167], v[194:197], v[120:123]
	v_mfma_f32_16x16x32_bf16 v[112:115], v[168:171], v[190:193], v[112:115]
	v_mfma_f32_16x16x32_bf16 v[112:115], v[172:175], v[194:197], v[112:115]
	v_mfma_f32_16x16x32_bf16 v[96:99], v[168:171], v[198:201], v[96:99]
	v_mfma_f32_16x16x32_bf16 v[96:99], v[172:175], v[202:205], v[96:99]
	v_mfma_f32_16x16x32_bf16 v[80:83], v[168:171], v[206:209], v[80:83]
	v_mfma_f32_16x16x32_bf16 v[80:83], v[172:175], v[210:213], v[80:83]
	v_mfma_f32_16x16x32_bf16 v[68:71], v[168:171], v[214:217], v[68:71]
	v_mfma_f32_16x16x32_bf16 v[68:71], v[172:175], v[218:221], v[68:71]
	v_mfma_f32_16x16x32_bf16 v[64:67], v[182:185], v[214:217], v[64:67]
	v_mfma_f32_16x16x32_bf16 v[64:67], v[186:189], v[218:221], v[64:67]
	v_mfma_f32_16x16x32_bf16 v[72:75], v[182:185], v[206:209], v[72:75]
	v_mfma_f32_16x16x32_bf16 v[72:75], v[186:189], v[210:213], v[72:75]
	v_mfma_f32_16x16x32_bf16 v[88:91], v[182:185], v[198:201], v[88:91]
	v_mfma_f32_16x16x32_bf16 v[88:91], v[186:189], v[202:205], v[88:91]
	v_mfma_f32_16x16x32_bf16 v[104:107], v[182:185], v[190:193], v[104:107]
	v_mfma_f32_16x16x32_bf16 v[104:107], v[186:189], v[194:197], v[104:107]
	s_barrier
	s_setprio 0
	s_add_i32 s24, s57, s29
	v_lshl_add_u64 v[144:145], v[144:145], 0, s[6:7]
	s_mov_b32 m0, s24
	ds_read_b128 v[190:193], v151 offset:49152
	ds_read_b128 v[194:197], v151 offset:50176
	ds_read_b128 v[198:201], v151 offset:51200
	ds_read_b128 v[202:205], v151 offset:52224
	ds_read_b128 v[206:209], v151 offset:53248
	ds_read_b128 v[210:213], v151 offset:54272
	ds_read_b128 v[214:217], v151 offset:55296
	ds_read_b128 v[218:221], v151 offset:56320
	global_load_lds_dwordx4 v[144:145], off
	s_add_i32 m0, s24, 0x2000
	s_add_u32 s22, s22, 0x160080
	v_lshl_add_u64 v[144:145], v[176:177], 0, s[6:7]
	s_addc_u32 s23, s23, 0
	s_add_i32 s24, s58, s29
	global_load_lds_dwordx4 v[144:145], off
	v_lshl_add_u64 v[144:145], s[22:23], 0, v[130:131]
	s_mov_b32 m0, s24
	s_nop 0
	global_load_lds_dwordx4 v[144:145], off
	v_lshl_add_u64 v[144:145], s[22:23], 0, v[134:135]
	s_add_i32 m0, s24, 0x2000
	s_nop 0
	global_load_lds_dwordx4 v[144:145], off
	v_lshl_add_u64 v[144:145], v[222:223], 0, s[6:7]
	s_mov_b32 m0, s37
	s_nop 0
	global_load_lds_dwordx4 v[144:145], off
	v_lshl_add_u64 v[144:145], v[224:225], 0, s[6:7]
	s_mov_b32 m0, s38
	s_nop 0
	global_load_lds_dwordx4 v[144:145], off
	s_waitcnt vmcnt(8)
	s_waitcnt lgkmcnt(0)
	s_setprio 1
	s_barrier
	v_mfma_f32_16x16x32_bf16 v[60:63], v[152:155], v[190:193], v[60:63]
	v_mfma_f32_16x16x32_bf16 v[60:63], v[156:159], v[194:197], v[60:63]
	v_mfma_f32_16x16x32_bf16 v[52:55], v[152:155], v[198:201], v[52:55]
	v_mfma_f32_16x16x32_bf16 v[52:55], v[156:159], v[202:205], v[52:55]
	v_mfma_f32_16x16x32_bf16 v[36:39], v[152:155], v[206:209], v[36:39]
	v_mfma_f32_16x16x32_bf16 v[36:39], v[156:159], v[210:213], v[36:39]
	v_mfma_f32_16x16x32_bf16 v[20:23], v[152:155], v[214:217], v[20:23]
	v_mfma_f32_16x16x32_bf16 v[20:23], v[156:159], v[218:221], v[20:23]
	v_mfma_f32_16x16x32_bf16 v[12:15], v[160:163], v[214:217], v[12:15]
	v_mfma_f32_16x16x32_bf16 v[12:15], v[164:167], v[218:221], v[12:15]
	v_mfma_f32_16x16x32_bf16 v[28:31], v[160:163], v[206:209], v[28:31]
	v_mfma_f32_16x16x32_bf16 v[28:31], v[164:167], v[210:213], v[28:31]
	v_mfma_f32_16x16x32_bf16 v[44:47], v[160:163], v[198:201], v[44:47]
	v_mfma_f32_16x16x32_bf16 v[44:47], v[164:167], v[202:205], v[44:47]
	v_mfma_f32_16x16x32_bf16 v[56:59], v[160:163], v[190:193], v[56:59]
	v_mfma_f32_16x16x32_bf16 v[56:59], v[164:167], v[194:197], v[56:59]
	v_mfma_f32_16x16x32_bf16 v[48:51], v[168:171], v[190:193], v[48:51]
	v_mfma_f32_16x16x32_bf16 v[48:51], v[172:175], v[194:197], v[48:51]
	v_mfma_f32_16x16x32_bf16 v[32:35], v[168:171], v[198:201], v[32:35]
	v_mfma_f32_16x16x32_bf16 v[32:35], v[172:175], v[202:205], v[32:35]
	v_mfma_f32_16x16x32_bf16 v[16:19], v[168:171], v[206:209], v[16:19]
	v_mfma_f32_16x16x32_bf16 v[16:19], v[172:175], v[210:213], v[16:19]
	v_mfma_f32_16x16x32_bf16 v[4:7], v[168:171], v[214:217], v[4:7]
	v_mfma_f32_16x16x32_bf16 v[4:7], v[172:175], v[218:221], v[4:7]
	v_mfma_f32_16x16x32_bf16 v[0:3], v[182:185], v[214:217], v[0:3]
	v_mfma_f32_16x16x32_bf16 v[0:3], v[186:189], v[218:221], v[0:3]
	v_mfma_f32_16x16x32_bf16 v[8:11], v[182:185], v[206:209], v[8:11]
	v_mfma_f32_16x16x32_bf16 v[8:11], v[186:189], v[210:213], v[8:11]
	v_mfma_f32_16x16x32_bf16 v[24:27], v[182:185], v[198:201], v[24:27]
	v_mfma_f32_16x16x32_bf16 v[24:27], v[186:189], v[202:205], v[24:27]
	v_mfma_f32_16x16x32_bf16 v[40:43], v[182:185], v[190:193], v[40:43]
	v_mfma_f32_16x16x32_bf16 v[40:43], v[186:189], v[194:197], v[40:43]
	s_barrier
	s_setprio 0
	s_add_i32 s56, s56, 2
	s_add_u32 s20, s20, 0x100
	s_addc_u32 s21, s21, 0
	s_add_u32 s54, s54, 0x100
	s_addc_u32 s55, s55, 0
	s_cmpk_gt_u32 s56, 0x55
	s_cbranch_scc0 .LBB0_3274
	s_and_b64 vcc, exec, s[8:9]
	s_cbranch_vccz .LBB0_3277
	s_barrier
